# hazard-clean rebuild: s_nop between v_cmp and v_cndmask in NA mask/table code, computed VALU-to-MFMA operand distances; NA K/V prefetch two slots ahead
# speedup vs baseline: 1.1244x; 1.0003x over previous
.LBB0_1698:
	s_cmpk_lt_i32 s2, 0x200
	v_writelane_b32 v250, s86, 1
	s_cselect_b64 s[0:1], -1, 0
	v_writelane_b32 v250, s0, 2
	s_cmpk_gt_i32 s2, 0x1ff
	v_and_b32_e32 v160, 31, v0
	v_lshrrev_b32_e32 v1, 5, v198
	v_lshlrev_b32_e32 v178, 4, v0
	v_lshrrev_b32_e32 v147, 3, v0
	v_writelane_b32 v250, s1, 3
	v_writelane_b32 v251, s2, 61
	s_cbranch_scc1 .LBB0_1875
	v_readlane_b32 s4, v251, 48
	v_readlane_b32 s5, v251, 49
	v_readlane_b32 s6, v251, 15
	v_readlane_b32 s7, v251, 16
	v_readlane_b32 s8, v251, 52
	v_readlane_b32 s9, v251, 23
	v_readlane_b32 s10, v251, 61
	s_nop 3
	s_and_b32 s11, s8, 1
	v_and_b32_e32 v216, 31, v0
	v_bfe_u32 v217, v0, 5, 1
	v_mov_b32_e32 v228, 0
	v_mov_b32_e32 v229, 0xf149f2ca
	s_lshl_b32 s36, s11, 5
	v_add_u32_e32 v222, s36, v216
	v_mul_u32_u24_e32 v199, 0x90, v222
	v_lshl_add_u32 v199, v217, 4, v199
	s_cmp_eq_u32 s11, 0
	s_cselect_b32 s37, 0, 24
	s_cselect_b32 s38, 32, 0
	v_add_u32_e32 v222, s37, v216
	v_and_b32_e32 v222, 31, v222
	v_add_u32_e32 v222, s38, v222
	v_mul_u32_u24_e32 v200, 0x90, v222
	v_lshl_add_u32 v200, v217, 4, v200
	v_mul_u32_u24_e32 v222, 0x88, v216
	v_lshl_add_u32 v222, v217, 3, v222
	v_add_u32_e32 v222, 0x4800, v222
	s_lshl_b32 s36, s11, 6
	v_add_u32_e32 v201, s36, v222
	s_cmp_eq_u32 s11, 0
	s_cselect_b32 s37, 64, 48
	s_cselect_b32 s38, 0x50, 0
	v_add_u32_e32 v202, s37, v222
	v_add_u32_e32 v203, s38, v222
	v_lshrrev_b32_e32 v222, 3, v0
	v_and_b32_e32 v223, 7, v0
	v_mul_u32_u24_e32 v204, 0x90, v222
	v_lshl_add_u32 v204, v223, 4, v204
	v_mul_u32_u24_e32 v205, 0x88, v222
	v_lshl_add_u32 v205, v223, 4, v205
	v_add_u32_e32 v205, 0x4800, v205
	v_lshlrev_b32_e32 v206, 4, v0
	v_mul_u32_u24_e32 v207, 0x2200, v222
	v_lshl_add_u32 v207, v223, 4, v207
	v_lshl_or_b32 v222, s8, 5, v216
	v_lshlrev_b32_e32 v219, 7, v222
	v_lshl_add_u32 v219, v217, 4, v219
	v_lshlrev_b32_e32 v218, 10, v222
	v_lshl_add_u32 v218, v217, 3, v218
	v_and_b32_e32 v222, 3, v216
	v_add_u32_e32 v223, 1, v222
	v_and_b32_e32 v223, 3, v223
	v_lshl_add_u32 v223, v217, 2, v223
	v_sub_u32_e32 v223, v223, v216
	v_add_u32_e32 v223, 39, v223
	v_lshlrev_b32_e32 v223, 2, v223
	v_mul_u32_u24_e32 v222, 5040, v222
	v_add_u32_e32 v208, v222, v223
	v_add_u32_e32 v208, 0x8c00, v208
	s_cmp_eq_u32 s11, 0
	s_mov_b32 s37, 0x80
	s_cselect_b32 s37, s37, 0xffffffe0
	v_add_u32_e32 v209, s37, v208
	v_mov_b32_e32 v186, 0
	v_mov_b32_e32 v187, 0
	s_lshr_b32 s36, s10, 4
	s_and_b32 s36, s36, 7
	s_mul_i32 s36, s36, 0x744
	s_add_u32 s38, s6, s36
	s_addc_u32 s39, s7, 0
	v_mov_b32_e32 v222, v0
	s_mov_b32 s36, 0xd00e
	v_mul_lo_u32 v223, v222, s36
	v_lshrrev_b32_e32 v223, 26, v223
	v_mul_u32_u24_e32 v224, 1260, v223
	v_sub_u32_e32 v224, v222, v224
	v_mul_u32_u24_e32 v225, 49933, v224
	v_lshrrev_b32_e32 v225, 22, v225
	v_mul_u32_u24_e32 v226, 84, v225
	v_sub_u32_e32 v226, v224, v226
	v_add_u32_e32 v227, 1, v223
	v_and_b32_e32 v227, 3, v227
	v_sub_u32_e32 v226, v226, v227
	v_subrev_u32_e32 v226, 24, v226
	v_cmp_gt_u32_e32 vcc, 31, v226
	s_nop 1
	v_cndmask_b32_e32 v227, 0, v226, vcc
	v_mad_u32_u24 v227, v225, 31, v227
	v_lshlrev_b32_e32 v227, 2, v227
	global_load_dword v227, v227, s[38:39]
	v_lshlrev_b32_e32 v222, 2, v222
	s_waitcnt vmcnt(0)
	v_mul_f32_e32 v227, 0x3fb8aa3b, v227
	v_cndmask_b32_e32 v227, 0, v227, vcc
	ds_write_b32 v222, v227 offset:35840
	v_add_u32_e32 v222, 512, v0
	s_mov_b32 s36, 0xd00e
	v_mul_lo_u32 v223, v222, s36
	v_lshrrev_b32_e32 v223, 26, v223
	v_mul_u32_u24_e32 v224, 1260, v223
	v_sub_u32_e32 v224, v222, v224
	v_mul_u32_u24_e32 v225, 49933, v224
	v_lshrrev_b32_e32 v225, 22, v225
	v_mul_u32_u24_e32 v226, 84, v225
	v_sub_u32_e32 v226, v224, v226
	v_add_u32_e32 v227, 1, v223
	v_and_b32_e32 v227, 3, v227
	v_sub_u32_e32 v226, v226, v227
	v_subrev_u32_e32 v226, 24, v226
	v_cmp_gt_u32_e32 vcc, 31, v226
	s_nop 1
	v_cndmask_b32_e32 v227, 0, v226, vcc
	v_mad_u32_u24 v227, v225, 31, v227
	v_lshlrev_b32_e32 v227, 2, v227
	global_load_dword v227, v227, s[38:39]
	v_lshlrev_b32_e32 v222, 2, v222
	s_waitcnt vmcnt(0)
	v_mul_f32_e32 v227, 0x3fb8aa3b, v227
	v_cndmask_b32_e32 v227, 0, v227, vcc
	ds_write_b32 v222, v227 offset:35840
	v_add_u32_e32 v222, 1024, v0
	s_mov_b32 s36, 0xd00e
	v_mul_lo_u32 v223, v222, s36
	v_lshrrev_b32_e32 v223, 26, v223
	v_mul_u32_u24_e32 v224, 1260, v223
	v_sub_u32_e32 v224, v222, v224
	v_mul_u32_u24_e32 v225, 49933, v224
	v_lshrrev_b32_e32 v225, 22, v225
	v_mul_u32_u24_e32 v226, 84, v225
	v_sub_u32_e32 v226, v224, v226
	v_add_u32_e32 v227, 1, v223
	v_and_b32_e32 v227, 3, v227
	v_sub_u32_e32 v226, v226, v227
	v_subrev_u32_e32 v226, 24, v226
	v_cmp_gt_u32_e32 vcc, 31, v226
	s_nop 1
	v_cndmask_b32_e32 v227, 0, v226, vcc
	v_mad_u32_u24 v227, v225, 31, v227
	v_lshlrev_b32_e32 v227, 2, v227
	global_load_dword v227, v227, s[38:39]
	v_lshlrev_b32_e32 v222, 2, v222
	s_waitcnt vmcnt(0)
	v_mul_f32_e32 v227, 0x3fb8aa3b, v227
	v_cndmask_b32_e32 v227, 0, v227, vcc
	ds_write_b32 v222, v227 offset:35840
	v_add_u32_e32 v222, 1536, v0
	s_mov_b32 s36, 0xd00e
	v_mul_lo_u32 v223, v222, s36
	v_lshrrev_b32_e32 v223, 26, v223
	v_mul_u32_u24_e32 v224, 1260, v223
	v_sub_u32_e32 v224, v222, v224
	v_mul_u32_u24_e32 v225, 49933, v224
	v_lshrrev_b32_e32 v225, 22, v225
	v_mul_u32_u24_e32 v226, 84, v225
	v_sub_u32_e32 v226, v224, v226
	v_add_u32_e32 v227, 1, v223
	v_and_b32_e32 v227, 3, v227
	v_sub_u32_e32 v226, v226, v227
	v_subrev_u32_e32 v226, 24, v226
	v_cmp_gt_u32_e32 vcc, 31, v226
	s_nop 1
	v_cndmask_b32_e32 v227, 0, v226, vcc
	v_mad_u32_u24 v227, v225, 31, v227
	v_lshlrev_b32_e32 v227, 2, v227
	global_load_dword v227, v227, s[38:39]
	v_lshlrev_b32_e32 v222, 2, v222
	s_waitcnt vmcnt(0)
	v_mul_f32_e32 v227, 0x3fb8aa3b, v227
	v_cndmask_b32_e32 v227, 0, v227, vcc
	ds_write_b32 v222, v227 offset:35840
	v_add_u32_e32 v222, 2048, v0
	s_mov_b32 s36, 0xd00e
	v_mul_lo_u32 v223, v222, s36
	v_lshrrev_b32_e32 v223, 26, v223
	v_mul_u32_u24_e32 v224, 1260, v223
	v_sub_u32_e32 v224, v222, v224
	v_mul_u32_u24_e32 v225, 49933, v224
	v_lshrrev_b32_e32 v225, 22, v225
	v_mul_u32_u24_e32 v226, 84, v225
	v_sub_u32_e32 v226, v224, v226
	v_add_u32_e32 v227, 1, v223
	v_and_b32_e32 v227, 3, v227
	v_sub_u32_e32 v226, v226, v227
	v_subrev_u32_e32 v226, 24, v226
	v_cmp_gt_u32_e32 vcc, 31, v226
	s_nop 1
	v_cndmask_b32_e32 v227, 0, v226, vcc
	v_mad_u32_u24 v227, v225, 31, v227
	v_lshlrev_b32_e32 v227, 2, v227
	global_load_dword v227, v227, s[38:39]
	v_lshlrev_b32_e32 v222, 2, v222
	s_waitcnt vmcnt(0)
	v_mul_f32_e32 v227, 0x3fb8aa3b, v227
	v_cndmask_b32_e32 v227, 0, v227, vcc
	ds_write_b32 v222, v227 offset:35840
	v_add_u32_e32 v222, 2560, v0
	s_mov_b32 s36, 0xd00e
	v_mul_lo_u32 v223, v222, s36
	v_lshrrev_b32_e32 v223, 26, v223
	v_mul_u32_u24_e32 v224, 1260, v223
	v_sub_u32_e32 v224, v222, v224
	v_mul_u32_u24_e32 v225, 49933, v224
	v_lshrrev_b32_e32 v225, 22, v225
	v_mul_u32_u24_e32 v226, 84, v225
	v_sub_u32_e32 v226, v224, v226
	v_add_u32_e32 v227, 1, v223
	v_and_b32_e32 v227, 3, v227
	v_sub_u32_e32 v226, v226, v227
	v_subrev_u32_e32 v226, 24, v226
	v_cmp_gt_u32_e32 vcc, 31, v226
	s_nop 1
	v_cndmask_b32_e32 v227, 0, v226, vcc
	v_mad_u32_u24 v227, v225, 31, v227
	v_lshlrev_b32_e32 v227, 2, v227
	global_load_dword v227, v227, s[38:39]
	v_lshlrev_b32_e32 v222, 2, v222
	s_waitcnt vmcnt(0)
	v_mul_f32_e32 v227, 0x3fb8aa3b, v227
	v_cndmask_b32_e32 v227, 0, v227, vcc
	ds_write_b32 v222, v227 offset:35840
	v_add_u32_e32 v222, 3072, v0
	s_mov_b32 s36, 0xd00e
	v_mul_lo_u32 v223, v222, s36
	v_lshrrev_b32_e32 v223, 26, v223
	v_mul_u32_u24_e32 v224, 1260, v223
	v_sub_u32_e32 v224, v222, v224
	v_mul_u32_u24_e32 v225, 49933, v224
	v_lshrrev_b32_e32 v225, 22, v225
	v_mul_u32_u24_e32 v226, 84, v225
	v_sub_u32_e32 v226, v224, v226
	v_add_u32_e32 v227, 1, v223
	v_and_b32_e32 v227, 3, v227
	v_sub_u32_e32 v226, v226, v227
	v_subrev_u32_e32 v226, 24, v226
	v_cmp_gt_u32_e32 vcc, 31, v226
	s_nop 1
	v_cndmask_b32_e32 v227, 0, v226, vcc
	v_mad_u32_u24 v227, v225, 31, v227
	v_lshlrev_b32_e32 v227, 2, v227
	global_load_dword v227, v227, s[38:39]
	v_lshlrev_b32_e32 v222, 2, v222
	s_waitcnt vmcnt(0)
	v_mul_f32_e32 v227, 0x3fb8aa3b, v227
	v_cndmask_b32_e32 v227, 0, v227, vcc
	ds_write_b32 v222, v227 offset:35840
	v_add_u32_e32 v222, 3584, v0
	s_mov_b32 s36, 0xd00e
	v_mul_lo_u32 v223, v222, s36
	v_lshrrev_b32_e32 v223, 26, v223
	v_mul_u32_u24_e32 v224, 1260, v223
	v_sub_u32_e32 v224, v222, v224
	v_mul_u32_u24_e32 v225, 49933, v224
	v_lshrrev_b32_e32 v225, 22, v225
	v_mul_u32_u24_e32 v226, 84, v225
	v_sub_u32_e32 v226, v224, v226
	v_add_u32_e32 v227, 1, v223
	v_and_b32_e32 v227, 3, v227
	v_sub_u32_e32 v226, v226, v227
	v_subrev_u32_e32 v226, 24, v226
	v_cmp_gt_u32_e32 vcc, 31, v226
	s_nop 1
	v_cndmask_b32_e32 v227, 0, v226, vcc
	v_mad_u32_u24 v227, v225, 31, v227
	v_lshlrev_b32_e32 v227, 2, v227
	global_load_dword v227, v227, s[38:39]
	v_lshlrev_b32_e32 v222, 2, v222
	s_waitcnt vmcnt(0)
	v_mul_f32_e32 v227, 0x3fb8aa3b, v227
	v_cndmask_b32_e32 v227, 0, v227, vcc
	ds_write_b32 v222, v227 offset:35840
	v_add_u32_e32 v222, 4096, v0
	s_mov_b32 s36, 0xd00e
	v_mul_lo_u32 v223, v222, s36
	v_lshrrev_b32_e32 v223, 26, v223
	v_mul_u32_u24_e32 v224, 1260, v223
	v_sub_u32_e32 v224, v222, v224
	v_mul_u32_u24_e32 v225, 49933, v224
	v_lshrrev_b32_e32 v225, 22, v225
	v_mul_u32_u24_e32 v226, 84, v225
	v_sub_u32_e32 v226, v224, v226
	v_add_u32_e32 v227, 1, v223
	v_and_b32_e32 v227, 3, v227
	v_sub_u32_e32 v226, v226, v227
	v_subrev_u32_e32 v226, 24, v226
	v_cmp_gt_u32_e32 vcc, 31, v226
	s_nop 1
	v_cndmask_b32_e32 v227, 0, v226, vcc
	v_mad_u32_u24 v227, v225, 31, v227
	v_lshlrev_b32_e32 v227, 2, v227
	global_load_dword v227, v227, s[38:39]
	v_lshlrev_b32_e32 v222, 2, v222
	s_waitcnt vmcnt(0)
	v_mul_f32_e32 v227, 0x3fb8aa3b, v227
	v_cndmask_b32_e32 v227, 0, v227, vcc
	ds_write_b32 v222, v227 offset:35840
	v_add_u32_e32 v222, 4608, v0
	s_mov_b32 s36, 0xd00e
	v_mul_lo_u32 v223, v222, s36
	v_lshrrev_b32_e32 v223, 26, v223
	v_mul_u32_u24_e32 v224, 1260, v223
	v_sub_u32_e32 v224, v222, v224
	v_mul_u32_u24_e32 v225, 49933, v224
	v_lshrrev_b32_e32 v225, 22, v225
	v_mul_u32_u24_e32 v226, 84, v225
	v_sub_u32_e32 v226, v224, v226
	v_add_u32_e32 v227, 1, v223
	v_and_b32_e32 v227, 3, v227
	v_sub_u32_e32 v226, v226, v227
	v_subrev_u32_e32 v226, 24, v226
	v_cmp_gt_u32_e32 vcc, 31, v226
	s_nop 1
	v_cndmask_b32_e32 v227, 0, v226, vcc
	v_mad_u32_u24 v227, v225, 31, v227
	v_lshlrev_b32_e32 v227, 2, v227
	global_load_dword v227, v227, s[38:39]
	v_lshlrev_b32_e32 v222, 2, v222
	s_waitcnt vmcnt(0)
	v_mul_f32_e32 v227, 0x3fb8aa3b, v227
	v_cndmask_b32_e32 v227, 0, v227, vcc
	v_cmp_gt_u32_e32 vcc, 0x4ec0, v222
	s_and_saveexec_b64 s[40:41], vcc
	ds_write_b32 v222, v227 offset:35840
	s_mov_b64 exec, s[40:41]
.Lna_unit:
	s_lshr_b32 s36, s10, 4
	s_and_b32 s37, s10, 15
	s_mul_i32 s38, s36, 0x88000
	s_add_u32 s38, s38, 0x4700000
	s_add_u32 s12, s4, s38
	s_addc_u32 s13, s5, 0
	s_add_u32 s38, s38, 0x1100000
	s_add_u32 s14, s4, s38
	s_addc_u32 s15, s5, 0
	s_add_u32 s16, s12, 0x80000
	s_addc_u32 s17, s13, 0
	s_add_u32 s18, s14, 0x2000
	s_addc_u32 s19, s15, 0
	s_lshr_b32 s40, s8, 1
	s_add_i32 s41, s40, 1
	s_add_i32 s38, s37, -1
	s_cmp_lt_u32 s38, 14
	s_cselect_b32 s22, 12, 8
	s_cselect_b32 s39, 1, 0
	s_cselect_b32 s23, s41, 0
	s_lshl_b32 s41, s37, 2
	s_add_i32 s42, s41, -4
	s_max_i32 s42, s42, 0
	s_min_i32 s42, s42, 56
	s_sub_i32 s42, s42, s39
	s_add_i32 s43, s41, s40
	s_sub_i32 s43, s42, s43
	s_add_i32 s43, s43, 7
	s_mul_i32 s25, s43, 0x150
	s_ashr_i32 s43, s42, 31
	s_lshl_b64 s[44:45], s[42:43], 13
	s_add_u32 s12, s12, s44
	s_addc_u32 s13, s13, s45
	s_lshl_b64 s[44:45], s[42:43], 7
	s_add_u32 s14, s14, s44
	s_addc_u32 s15, s15, s45
	s_lshl_b32 s38, s36, 12
	s_lshl_b32 s39, s37, 8
	s_add_u32 s38, s38, s39
	s_lshl_b32 s38, s38, 7
	s_add_u32 s38, s38, 0x6900000
	s_add_u32 s34, s4, s38
	s_addc_u32 s35, s5, 0
	s_lshr_b32 s38, s36, 3
	s_lshl_b32 s38, s38, 12
	s_add_u32 s38, s38, s39
	s_lshl_b32 s38, s38, 10
	s_and_b32 s40, s36, 7
	s_lshl_b32 s40, s40, 7
	s_add_u32 s38, s38, s40
	s_add_u32 s38, s38, 0x8900000
	s_add_u32 s30, s4, s38
	s_addc_u32 s31, s5, 0
	global_load_dwordx4 v[98:101], v219, s[34:35] offset:0
	global_load_dwordx4 v[102:105], v219, s[34:35] offset:32
	global_load_dwordx4 v[106:109], v219, s[34:35] offset:64
	global_load_dwordx4 v[110:113], v219, s[34:35] offset:96
	global_load_dwordx4 v[146:149], v206, s[12:13]
	s_add_u32 s12, s12, 0x2000
	s_addc_u32 s13, s13, 0
	global_load_dwordx4 v[230:233], v206, s[12:13]
	global_load_dwordx4 v[234:237], v207, s[14:15]
	s_add_u32 s12, s12, 0x2000
	s_addc_u32 s13, s13, 0
	s_add_u32 s14, s14, 0x80
	s_addc_u32 s15, s15, 0
	global_load_dwordx4 v[188:191], v206, s[12:13]
	global_load_dwordx4 v[192:195], v207, s[14:15]
	s_add_u32 s12, s12, 0x2000
	s_addc_u32 s13, s13, 0
	s_add_u32 s14, s14, 0x80
	s_addc_u32 s15, s15, 0
	s_mov_b32 s20, 3
	s_mov_b32 s21, 2
	v_mov_b32_e32 v2, 0
	v_mov_b32_e32 v3, 0
	v_mov_b32_e32 v4, 0
	v_mov_b32_e32 v5, 0
	v_mov_b32_e32 v6, 0
	v_mov_b32_e32 v7, 0
	v_mov_b32_e32 v8, 0
	v_mov_b32_e32 v9, 0
	v_mov_b32_e32 v10, 0
	v_mov_b32_e32 v11, 0
	v_mov_b32_e32 v12, 0
	v_mov_b32_e32 v13, 0
	v_mov_b32_e32 v14, 0
	v_mov_b32_e32 v15, 0
	v_mov_b32_e32 v16, 0
	v_mov_b32_e32 v17, 0
	v_mov_b32_e32 v18, 0
	v_mov_b32_e32 v19, 0
	v_mov_b32_e32 v20, 0
	v_mov_b32_e32 v21, 0
	v_mov_b32_e32 v22, 0
	v_mov_b32_e32 v23, 0
	v_mov_b32_e32 v24, 0
	v_mov_b32_e32 v25, 0
	v_mov_b32_e32 v26, 0
	v_mov_b32_e32 v27, 0
	v_mov_b32_e32 v28, 0
	v_mov_b32_e32 v29, 0
	v_mov_b32_e32 v30, 0
	v_mov_b32_e32 v31, 0
	v_mov_b32_e32 v32, 0
	v_mov_b32_e32 v33, 0
	v_mov_b32_e32 v212, 0
	v_mov_b32_e32 v213, 0
	v_mov_b32_e32 v214, 0
	v_mov_b32_e32 v220, 0xff7fffff
	v_mov_b32_e32 v221, 0
	s_mov_b64 s[26:27], -1
	v_and_b32_e32 v216, 31, v0
	v_bfe_u32 v217, v0, 5, 1
	s_lshl_b32 s36, s11, 5
	v_add_u32_e32 v222, s36, v216
	v_subrev_u32_e32 v223, 8, v222
	v_med3_i32 v223, v223, 0, 48
	v_lshl_add_u32 v224, v217, 2, s36
	v_sub_u32_e32 v224, v224, v223
	v_add_u32_e32 v225, 0, v224
	v_cmp_gt_u32_e32 vcc, 16, v225
	s_nop 1
	v_cndmask_b32_e32 v114, v229, v228, vcc
	v_add_u32_e32 v225, 1, v224
	v_cmp_gt_u32_e32 vcc, 16, v225
	s_nop 1
	v_cndmask_b32_e32 v115, v229, v228, vcc
	v_add_u32_e32 v225, 2, v224
	v_cmp_gt_u32_e32 vcc, 16, v225
	s_nop 1
	v_cndmask_b32_e32 v116, v229, v228, vcc
	v_add_u32_e32 v225, 3, v224
	v_cmp_gt_u32_e32 vcc, 16, v225
	s_nop 1
	v_cndmask_b32_e32 v117, v229, v228, vcc
	v_add_u32_e32 v225, 8, v224
	v_cmp_gt_u32_e32 vcc, 16, v225
	s_nop 1
	v_cndmask_b32_e32 v118, v229, v228, vcc
	v_add_u32_e32 v225, 9, v224
	v_cmp_gt_u32_e32 vcc, 16, v225
	s_nop 1
	v_cndmask_b32_e32 v119, v229, v228, vcc
	v_add_u32_e32 v225, 10, v224
	v_cmp_gt_u32_e32 vcc, 16, v225
	s_nop 1
	v_cndmask_b32_e32 v120, v229, v228, vcc
	v_add_u32_e32 v225, 11, v224
	v_cmp_gt_u32_e32 vcc, 16, v225
	s_nop 1
	v_cndmask_b32_e32 v121, v229, v228, vcc
	v_add_u32_e32 v225, 16, v224
	v_cmp_gt_u32_e32 vcc, 16, v225
	s_nop 1
	v_cndmask_b32_e32 v122, v229, v228, vcc
	v_add_u32_e32 v225, 17, v224
	v_cmp_gt_u32_e32 vcc, 16, v225
	s_nop 1
	v_cndmask_b32_e32 v123, v229, v228, vcc
	v_add_u32_e32 v225, 18, v224
	v_cmp_gt_u32_e32 vcc, 16, v225
	s_nop 1
	v_cndmask_b32_e32 v124, v229, v228, vcc
	v_add_u32_e32 v225, 19, v224
	v_cmp_gt_u32_e32 vcc, 16, v225
	s_nop 1
	v_cndmask_b32_e32 v125, v229, v228, vcc
	v_add_u32_e32 v225, 24, v224
	v_cmp_gt_u32_e32 vcc, 16, v225
	s_nop 1
	v_cndmask_b32_e32 v126, v229, v228, vcc
	v_add_u32_e32 v225, 25, v224
	v_cmp_gt_u32_e32 vcc, 16, v225
	s_nop 1
	v_cndmask_b32_e32 v127, v229, v228, vcc
	v_add_u32_e32 v225, 26, v224
	v_cmp_gt_u32_e32 vcc, 16, v225
	s_nop 1
	v_cndmask_b32_e32 v128, v229, v228, vcc
	v_add_u32_e32 v225, 27, v224
	v_cmp_gt_u32_e32 vcc, 16, v225
	s_nop 1
	v_cndmask_b32_e32 v129, v229, v228, vcc
	s_cmp_eq_u32 s11, 0
	s_cselect_b32 s37, 32, 24
	v_lshl_add_u32 v224, v217, 2, s37
	v_sub_u32_e32 v224, v224, v223
	v_add_u32_e32 v225, 0, v224
	v_cmp_gt_u32_e32 vcc, 16, v225
	s_nop 1
	v_cndmask_b32_e32 v130, v229, v228, vcc
	v_add_u32_e32 v225, 1, v224
	v_cmp_gt_u32_e32 vcc, 16, v225
	s_nop 1
	v_cndmask_b32_e32 v131, v229, v228, vcc
	v_add_u32_e32 v225, 2, v224
	v_cmp_gt_u32_e32 vcc, 16, v225
	s_nop 1
	v_cndmask_b32_e32 v132, v229, v228, vcc
	v_add_u32_e32 v225, 3, v224
	v_cmp_gt_u32_e32 vcc, 16, v225
	s_nop 1
	v_cndmask_b32_e32 v133, v229, v228, vcc
	v_mov_b32_e32 v134, 0
	v_mov_b32_e32 v135, 0
	v_mov_b32_e32 v136, 0
	v_mov_b32_e32 v137, 0
	v_mov_b32_e32 v138, 0
	v_mov_b32_e32 v139, 0
	v_mov_b32_e32 v140, 0
	v_mov_b32_e32 v141, 0
	v_mov_b32_e32 v142, 0
	v_mov_b32_e32 v143, 0
	v_mov_b32_e32 v144, 0
	v_mov_b32_e32 v145, 0
	s_waitcnt vmcnt(4)
	ds_write_b128 v204, v[146:149]
	s_waitcnt lgkmcnt(0)
	s_barrier
	s_mov_b32 s24, -1
	s_lshr_b32 s33, s22, 1
.Lna_wloop:
	s_sub_i32 s36, s24, s23
	s_cmp_lt_u32 s36, 8
	s_cselect_b64 s[40:41], -1, 0
	s_add_i32 s36, s36, 1
	s_cmp_lt_u32 s36, 8
	s_cselect_b64 s[42:43], -1, 0
	s_and_b64 s[44:45], s[40:41], s[42:43]
	s_cmp_eq_u64 s[44:45], 0
	s_cbranch_scc1 .Lna_slow_w1
	ds_read_b128 v[146:149], v199 offset:0
	ds_read_b128 v[150:153], v200 offset:0
	ds_read_b128 v[154:157], v199 offset:32
	ds_read_b128 v[158:161], v200 offset:32
	v_add_u32_e32 v210, s25, v208
	v_add_u32_e32 v211, s25, v209
	v_exp_f32_e32 v66, v66
	v_exp_f32_e32 v67, v67
	v_exp_f32_e32 v68, v68
	v_exp_f32_e32 v69, v69
	s_waitcnt lgkmcnt(3)
	v_mfma_f32_32x32x16_bf16 v[34:49], v[146:149], v[98:101], v[114:129]
	ds_read_b128 v[146:149], v199 offset:64
	v_add_f32_e32 v213, v213, v66
	v_add_f32_e32 v214, v214, v67
	v_add_f32_e32 v213, v213, v68
	v_add_f32_e32 v214, v214, v69
	v_exp_f32_e32 v70, v70
	v_exp_f32_e32 v71, v71
	s_waitcnt lgkmcnt(3)
	v_mfma_f32_32x32x16_bf16 v[50:65], v[150:153], v[98:101], v[130:145]
	ds_read_b128 v[150:153], v200 offset:64
	v_exp_f32_e32 v72, v72
	v_exp_f32_e32 v73, v73
	v_add_f32_e32 v213, v213, v70
	v_add_f32_e32 v214, v214, v71
	s_waitcnt lgkmcnt(3)
	v_mfma_f32_32x32x16_bf16 v[34:49], v[154:157], v[102:105], v[34:49]
	ds_read_b128 v[154:157], v199 offset:96
	v_add_f32_e32 v213, v213, v72
	v_add_f32_e32 v214, v214, v73
	v_cvt_pk_bf16_f32 v66, v66, v67
	v_cvt_pk_bf16_f32 v67, v68, v69
	v_cvt_pk_bf16_f32 v68, v70, v71
	v_cvt_pk_bf16_f32 v69, v72, v73
	v_exp_f32_e32 v74, v74
	s_waitcnt lgkmcnt(3)
	v_mfma_f32_32x32x16_bf16 v[50:65], v[158:161], v[102:105], v[50:65]
	ds_read_b128 v[158:161], v200 offset:96
	v_exp_f32_e32 v75, v75
	v_exp_f32_e32 v76, v76
	v_exp_f32_e32 v77, v77
	s_waitcnt lgkmcnt(3)
	v_mfma_f32_32x32x16_bf16 v[34:49], v[146:149], v[106:109], v[34:49]
	ds_read_b64 v[162:163], v201 offset:8704
	ds_read_b64 v[164:165], v201 offset:8720
	v_add_f32_e32 v213, v213, v74
	v_add_f32_e32 v214, v214, v75
	v_add_f32_e32 v213, v213, v76
	v_add_f32_e32 v214, v214, v77
	v_exp_f32_e32 v78, v78
	v_exp_f32_e32 v79, v79
	s_waitcnt lgkmcnt(4)
	v_mfma_f32_32x32x16_bf16 v[50:65], v[150:153], v[106:109], v[50:65]
	ds_read_b64 v[166:167], v201 offset:13056
	ds_read_b64 v[168:169], v201 offset:13072
	v_exp_f32_e32 v80, v80
	v_exp_f32_e32 v81, v81
	v_add_f32_e32 v213, v213, v78
	v_add_f32_e32 v214, v214, v79
	s_waitcnt lgkmcnt(5)
	v_mfma_f32_32x32x16_bf16 v[34:49], v[154:157], v[110:113], v[34:49]
	ds_read_b64 v[170:171], v201 offset:8736
	ds_read_b64 v[172:173], v201 offset:8752
	v_add_f32_e32 v213, v213, v80
	v_add_f32_e32 v214, v214, v81
	v_cvt_pk_bf16_f32 v74, v74, v75
	v_cvt_pk_bf16_f32 v75, v76, v77
	v_cvt_pk_bf16_f32 v76, v78, v79
	v_cvt_pk_bf16_f32 v77, v80, v81
	v_exp_f32_e32 v82, v82
	s_waitcnt lgkmcnt(6)
	v_mfma_f32_32x32x16_bf16 v[50:65], v[158:161], v[110:113], v[50:65]
	ds_read_b64 v[174:175], v201 offset:13088
	ds_read_b64 v[176:177], v201 offset:13104
	ds_read_b128 v[146:149], v210 offset:0
	ds_read_b128 v[150:153], v210 offset:32
	ds_read_b128 v[154:157], v210 offset:64
	ds_read_b128 v[158:161], v210 offset:96
	ds_read_b128 v[180:183], v211
	v_exp_f32_e32 v83, v83
	v_exp_f32_e32 v84, v84
	v_exp_f32_e32 v85, v85
	s_waitcnt lgkmcnt(11)
	v_mfma_f32_32x32x16_bf16 v[2:17], v[162:165], v[66:69], v[2:17]
	ds_read_b64 v[162:163], v202 offset:8704
	ds_read_b64 v[164:165], v203 offset:8704
	v_add_f32_e32 v213, v213, v82
	v_add_f32_e32 v214, v214, v83
	v_add_f32_e32 v213, v213, v84
	v_add_f32_e32 v214, v214, v85
	v_cvt_pk_bf16_f32 v184, v82, v83
	v_cvt_pk_bf16_f32 v185, v84, v85
	s_waitcnt lgkmcnt(11)
	v_mfma_f32_32x32x16_bf16 v[18:33], v[166:169], v[66:69], v[18:33]
	ds_read_b64 v[166:167], v202 offset:13056
	ds_read_b64 v[168:169], v203 offset:13056
	s_waitcnt lgkmcnt(4)
	v_add_f32_e32 v34, v34, v146
	v_add_f32_e32 v35, v35, v147
	v_add_f32_e32 v36, v36, v148
	v_add_f32_e32 v37, v37, v149
	v_add_f32_e32 v38, v38, v150
	v_add_f32_e32 v39, v39, v151
	v_add_f32_e32 v40, v40, v152
	v_add_f32_e32 v41, v41, v153
	v_mfma_f32_32x32x16_bf16 v[2:17], v[170:173], v[74:77], v[2:17]
	v_add_f32_e32 v42, v42, v154
	v_add_f32_e32 v43, v43, v155
	v_add_f32_e32 v44, v44, v156
	v_add_f32_e32 v45, v45, v157
	v_add_f32_e32 v46, v46, v158
	v_add_f32_e32 v47, v47, v159
	v_add_f32_e32 v48, v48, v160
	v_mfma_f32_32x32x16_bf16 v[18:33], v[174:177], v[74:77], v[18:33]
	s_waitcnt vmcnt(2)
	ds_write_b128 v204, v[230:233] offset:9216
	ds_write_b64 v205, v[234:235] offset:0
	ds_write_b64 v205, v[236:237] offset:8
	global_load_dwordx4 v[230:233], v206, s[12:13]
	s_add_i32 s20, s20, 1
	s_add_u32 s12, s12, 0x2000
	s_addc_u32 s13, s13, 0
	s_cmp_eq_u32 s20, s22
	s_cselect_b32 s12, s16, s12
	s_cselect_b32 s13, s17, s13
	global_load_dwordx4 v[234:237], v207, s[14:15]
	s_add_i32 s21, s21, 1
	s_add_u32 s14, s14, 0x80
	s_addc_u32 s15, s15, 0
	s_cmp_eq_u32 s21, s22
	s_cselect_b32 s14, s18, s14
	s_cselect_b32 s15, s19, s15
	v_add_f32_e32 v49, v49, v161
	v_add_f32_e32 v50, v50, v180
	v_add_f32_e32 v51, v51, v181
	v_add_f32_e32 v52, v52, v182
	v_add_f32_e32 v53, v53, v183
	v_max3_f32 v216, v34, v35, v36
	v_max3_f32 v217, v44, v45, v46
	s_waitcnt lgkmcnt(5)
	v_mfma_f32_32x32x16_bf16 v[2:17], v[162:165], v[184:187], v[2:17]
	v_max3_f32 v216, v216, v37, v38
	v_max3_f32 v217, v217, v47, v48
	v_max3_f32 v216, v216, v39, v40
	v_max3_f32 v217, v217, v49, v50
	v_max3_f32 v216, v216, v41, v42
	v_max3_f32 v217, v217, v51, v52
	v_max_f32_e32 v216, v216, v43
	s_waitcnt lgkmcnt(3)
	v_mfma_f32_32x32x16_bf16 v[18:33], v[166:169], v[184:187], v[18:33]
	v_max_f32_e32 v217, v217, v53
	v_max_f32_e32 v216, v216, v217
	v_mov_b32_e32 v217, v216
	s_nop 1
	v_permlane32_swap_b32_e32 v216, v217
	v_max_f32_e32 v215, v216, v217
	v_cmp_lt_f32_e32 vcc, 4.0, v215
	s_or_b64 s[28:29], vcc, s[26:27]
	s_cmp_lg_u64 s[28:29], 0
	s_cbranch_scc0 .Lna_nr_w1f
	s_nop 15
	v_max_f32_e32 v216, v215, v220
	v_exp_f32_e64 v217, -v216
	v_add_f32_e32 v212, v212, v216
	v_and_b32_e32 v217, v217, v221
	v_sub_f32_e32 v34, v34, v216
	v_sub_f32_e32 v35, v35, v216
	v_sub_f32_e32 v36, v36, v216
	v_sub_f32_e32 v37, v37, v216
	v_sub_f32_e32 v38, v38, v216
	v_sub_f32_e32 v39, v39, v216
	v_sub_f32_e32 v40, v40, v216
	v_sub_f32_e32 v41, v41, v216
	v_sub_f32_e32 v42, v42, v216
	v_sub_f32_e32 v43, v43, v216
	v_sub_f32_e32 v44, v44, v216
	v_sub_f32_e32 v45, v45, v216
	v_sub_f32_e32 v46, v46, v216
	v_sub_f32_e32 v47, v47, v216
	v_sub_f32_e32 v48, v48, v216
	v_sub_f32_e32 v49, v49, v216
	v_sub_f32_e32 v50, v50, v216
	v_sub_f32_e32 v51, v51, v216
	v_sub_f32_e32 v52, v52, v216
	v_sub_f32_e32 v53, v53, v216
	v_sub_f32_e32 v114, v114, v216
	v_sub_f32_e32 v115, v115, v216
	v_sub_f32_e32 v116, v116, v216
	v_sub_f32_e32 v117, v117, v216
	v_sub_f32_e32 v118, v118, v216
	v_sub_f32_e32 v119, v119, v216
	v_sub_f32_e32 v120, v120, v216
	v_sub_f32_e32 v121, v121, v216
	v_sub_f32_e32 v122, v122, v216
	v_sub_f32_e32 v123, v123, v216
	v_sub_f32_e32 v124, v124, v216
	v_sub_f32_e32 v125, v125, v216
	v_sub_f32_e32 v126, v126, v216
	v_sub_f32_e32 v127, v127, v216
	v_sub_f32_e32 v128, v128, v216
	v_sub_f32_e32 v129, v129, v216
	v_sub_f32_e32 v130, v130, v216
	v_sub_f32_e32 v131, v131, v216
	v_sub_f32_e32 v132, v132, v216
	v_sub_f32_e32 v133, v133, v216
	v_mul_f32_e32 v213, v213, v217
	v_mul_f32_e32 v214, v214, v217
	v_mul_f32_e32 v2, v2, v217
	v_mul_f32_e32 v3, v3, v217
	v_mul_f32_e32 v4, v4, v217
	v_mul_f32_e32 v5, v5, v217
	v_mul_f32_e32 v6, v6, v217
	v_mul_f32_e32 v7, v7, v217
	v_mul_f32_e32 v8, v8, v217
	v_mul_f32_e32 v9, v9, v217
	v_mul_f32_e32 v10, v10, v217
	v_mul_f32_e32 v11, v11, v217
	v_mul_f32_e32 v12, v12, v217
	v_mul_f32_e32 v13, v13, v217
	v_mul_f32_e32 v14, v14, v217
	v_mul_f32_e32 v15, v15, v217
	v_mul_f32_e32 v16, v16, v217
	v_mul_f32_e32 v17, v17, v217
	v_mul_f32_e32 v18, v18, v217
	v_mul_f32_e32 v19, v19, v217
	v_mul_f32_e32 v20, v20, v217
	v_mul_f32_e32 v21, v21, v217
	v_mul_f32_e32 v22, v22, v217
	v_mul_f32_e32 v23, v23, v217
	v_mul_f32_e32 v24, v24, v217
	v_mul_f32_e32 v25, v25, v217
	v_mul_f32_e32 v26, v26, v217
	v_mul_f32_e32 v27, v27, v217
	v_mul_f32_e32 v28, v28, v217
	v_mul_f32_e32 v29, v29, v217
	v_mul_f32_e32 v30, v30, v217
	v_mul_f32_e32 v31, v31, v217
	v_mul_f32_e32 v32, v32, v217
	v_mul_f32_e32 v33, v33, v217
	v_mov_b32_e32 v220, 0
	v_mov_b32_e32 v221, -1
	s_mov_b64 s[26:27], 0

.Lna_nr_w1s:
.Lna_sl_b_w1s:
	s_waitcnt vmcnt(2)
	ds_write_b128 v204, v[230:233] offset:9216
	ds_write_b64 v205, v[234:235] offset:0
	ds_write_b64 v205, v[236:237] offset:8
	global_load_dwordx4 v[230:233], v206, s[12:13]
	s_add_i32 s20, s20, 1
	s_add_u32 s12, s12, 0x2000
	s_addc_u32 s13, s13, 0
	s_cmp_eq_u32 s20, s22
	s_cselect_b32 s12, s16, s12
	s_cselect_b32 s13, s17, s13
	global_load_dwordx4 v[234:237], v207, s[14:15]
	s_add_i32 s21, s21, 1
	s_add_u32 s14, s14, 0x80
	s_addc_u32 s15, s15, 0
	s_cmp_eq_u32 s21, s22
	s_cselect_b32 s14, s18, s14
	s_cselect_b32 s15, s19, s15
	s_waitcnt lgkmcnt(0)
	s_barrier
.Lna_done_w1:
	s_add_i32 s24, s24, 1
	s_add_i32 s25, s25, 0x150
	s_sub_i32 s36, s24, s23
	s_cmp_lt_u32 s36, 8
	s_cselect_b64 s[40:41], -1, 0
	s_add_i32 s36, s36, 1
	s_cmp_lt_u32 s36, 8
	s_cselect_b64 s[42:43], -1, 0
	s_and_b64 s[44:45], s[40:41], s[42:43]
	s_cmp_eq_u64 s[44:45], 0
	s_cbranch_scc1 .Lna_slow_w0
	ds_read_b128 v[146:149], v199 offset:9216
	ds_read_b128 v[150:153], v200 offset:9216
	ds_read_b128 v[154:157], v199 offset:9248
	ds_read_b128 v[158:161], v200 offset:9248
	v_add_u32_e32 v210, s25, v208
	v_add_u32_e32 v211, s25, v209
	v_exp_f32_e32 v34, v34
	v_exp_f32_e32 v35, v35
	v_exp_f32_e32 v36, v36
	v_exp_f32_e32 v37, v37
	s_waitcnt lgkmcnt(3)
	v_mfma_f32_32x32x16_bf16 v[66:81], v[146:149], v[98:101], v[114:129]
	ds_read_b128 v[146:149], v199 offset:9280
	v_add_f32_e32 v213, v213, v34
	v_add_f32_e32 v214, v214, v35
	v_add_f32_e32 v213, v213, v36
	v_add_f32_e32 v214, v214, v37
	v_exp_f32_e32 v38, v38
	v_exp_f32_e32 v39, v39
	s_waitcnt lgkmcnt(3)
	v_mfma_f32_32x32x16_bf16 v[82:97], v[150:153], v[98:101], v[130:145]
	ds_read_b128 v[150:153], v200 offset:9280
	v_exp_f32_e32 v40, v40
	v_exp_f32_e32 v41, v41
	v_add_f32_e32 v213, v213, v38
	v_add_f32_e32 v214, v214, v39
	s_waitcnt lgkmcnt(3)
	v_mfma_f32_32x32x16_bf16 v[66:81], v[154:157], v[102:105], v[66:81]
	ds_read_b128 v[154:157], v199 offset:9312
	v_add_f32_e32 v213, v213, v40
	v_add_f32_e32 v214, v214, v41
	v_cvt_pk_bf16_f32 v34, v34, v35
	v_cvt_pk_bf16_f32 v35, v36, v37
	v_cvt_pk_bf16_f32 v36, v38, v39
	v_cvt_pk_bf16_f32 v37, v40, v41
	v_exp_f32_e32 v42, v42
	s_waitcnt lgkmcnt(3)
	v_mfma_f32_32x32x16_bf16 v[82:97], v[158:161], v[102:105], v[82:97]
	ds_read_b128 v[158:161], v200 offset:9312
	v_exp_f32_e32 v43, v43
	v_exp_f32_e32 v44, v44
	v_exp_f32_e32 v45, v45
	s_waitcnt lgkmcnt(3)
	v_mfma_f32_32x32x16_bf16 v[66:81], v[146:149], v[106:109], v[66:81]
	ds_read_b64 v[162:163], v201 offset:0
	ds_read_b64 v[164:165], v201 offset:16
	v_add_f32_e32 v213, v213, v42
	v_add_f32_e32 v214, v214, v43
	v_add_f32_e32 v213, v213, v44
	v_add_f32_e32 v214, v214, v45
	v_exp_f32_e32 v46, v46
	v_exp_f32_e32 v47, v47
	s_waitcnt lgkmcnt(4)
	v_mfma_f32_32x32x16_bf16 v[82:97], v[150:153], v[106:109], v[82:97]
	ds_read_b64 v[166:167], v201 offset:4352
	ds_read_b64 v[168:169], v201 offset:4368
	v_exp_f32_e32 v48, v48
	v_exp_f32_e32 v49, v49
	v_add_f32_e32 v213, v213, v46
	v_add_f32_e32 v214, v214, v47
	s_waitcnt lgkmcnt(5)
	v_mfma_f32_32x32x16_bf16 v[66:81], v[154:157], v[110:113], v[66:81]
	ds_read_b64 v[170:171], v201 offset:32
	ds_read_b64 v[172:173], v201 offset:48
	v_add_f32_e32 v213, v213, v48
	v_add_f32_e32 v214, v214, v49
	v_cvt_pk_bf16_f32 v42, v42, v43
	v_cvt_pk_bf16_f32 v43, v44, v45
	v_cvt_pk_bf16_f32 v44, v46, v47
	v_cvt_pk_bf16_f32 v45, v48, v49
	v_exp_f32_e32 v50, v50
	s_waitcnt lgkmcnt(6)
	v_mfma_f32_32x32x16_bf16 v[82:97], v[158:161], v[110:113], v[82:97]
	ds_read_b64 v[174:175], v201 offset:4384
	ds_read_b64 v[176:177], v201 offset:4400
	ds_read_b128 v[146:149], v210 offset:0
	ds_read_b128 v[150:153], v210 offset:32
	ds_read_b128 v[154:157], v210 offset:64
	ds_read_b128 v[158:161], v210 offset:96
	ds_read_b128 v[180:183], v211
	v_exp_f32_e32 v51, v51
	v_exp_f32_e32 v52, v52
	v_exp_f32_e32 v53, v53
	s_waitcnt lgkmcnt(11)
	v_mfma_f32_32x32x16_bf16 v[2:17], v[162:165], v[34:37], v[2:17]
	ds_read_b64 v[162:163], v202 offset:0
	ds_read_b64 v[164:165], v203 offset:0
	v_add_f32_e32 v213, v213, v50
	v_add_f32_e32 v214, v214, v51
	v_add_f32_e32 v213, v213, v52
	v_add_f32_e32 v214, v214, v53
	v_cvt_pk_bf16_f32 v184, v50, v51
	v_cvt_pk_bf16_f32 v185, v52, v53
	s_waitcnt lgkmcnt(11)
	v_mfma_f32_32x32x16_bf16 v[18:33], v[166:169], v[34:37], v[18:33]
	ds_read_b64 v[166:167], v202 offset:4352
	ds_read_b64 v[168:169], v203 offset:4352
	s_waitcnt lgkmcnt(4)
	v_add_f32_e32 v66, v66, v146
	v_add_f32_e32 v67, v67, v147
	v_add_f32_e32 v68, v68, v148
	v_add_f32_e32 v69, v69, v149
	v_add_f32_e32 v70, v70, v150
	v_add_f32_e32 v71, v71, v151
	v_add_f32_e32 v72, v72, v152
	v_add_f32_e32 v73, v73, v153
	v_mfma_f32_32x32x16_bf16 v[2:17], v[170:173], v[42:45], v[2:17]
	v_add_f32_e32 v74, v74, v154
	v_add_f32_e32 v75, v75, v155
	v_add_f32_e32 v76, v76, v156
	v_add_f32_e32 v77, v77, v157
	v_add_f32_e32 v78, v78, v158
	v_add_f32_e32 v79, v79, v159
	v_add_f32_e32 v80, v80, v160
	v_mfma_f32_32x32x16_bf16 v[18:33], v[174:177], v[42:45], v[18:33]
	s_waitcnt vmcnt(2)
	ds_write_b128 v204, v[188:191] offset:0
	ds_write_b64 v205, v[192:193] offset:8704
	ds_write_b64 v205, v[194:195] offset:8712
	global_load_dwordx4 v[188:191], v206, s[12:13]
	s_add_i32 s20, s20, 1
	s_add_u32 s12, s12, 0x2000
	s_addc_u32 s13, s13, 0
	s_cmp_eq_u32 s20, s22
	s_cselect_b32 s12, s16, s12
	s_cselect_b32 s13, s17, s13
	global_load_dwordx4 v[192:195], v207, s[14:15]
	s_add_i32 s21, s21, 1
	s_add_u32 s14, s14, 0x80
	s_addc_u32 s15, s15, 0
	s_cmp_eq_u32 s21, s22
	s_cselect_b32 s14, s18, s14
	s_cselect_b32 s15, s19, s15
	v_add_f32_e32 v81, v81, v161
	v_add_f32_e32 v82, v82, v180
	v_add_f32_e32 v83, v83, v181
	v_add_f32_e32 v84, v84, v182
	v_add_f32_e32 v85, v85, v183
	v_max3_f32 v216, v66, v67, v68
	v_max3_f32 v217, v76, v77, v78
	s_waitcnt lgkmcnt(5)
	v_mfma_f32_32x32x16_bf16 v[2:17], v[162:165], v[184:187], v[2:17]
	v_max3_f32 v216, v216, v69, v70
	v_max3_f32 v217, v217, v79, v80
	v_max3_f32 v216, v216, v71, v72
	v_max3_f32 v217, v217, v81, v82
	v_max3_f32 v216, v216, v73, v74
	v_max3_f32 v217, v217, v83, v84
	v_max_f32_e32 v216, v216, v75
	s_waitcnt lgkmcnt(3)
	v_mfma_f32_32x32x16_bf16 v[18:33], v[166:169], v[184:187], v[18:33]
	v_max_f32_e32 v217, v217, v85
	v_max_f32_e32 v216, v216, v217
	v_mov_b32_e32 v217, v216
	s_nop 1
	v_permlane32_swap_b32_e32 v216, v217
	v_max_f32_e32 v215, v216, v217
	v_cmp_lt_f32_e32 vcc, 4.0, v215
	s_or_b64 s[28:29], vcc, s[26:27]
	s_cmp_lg_u64 s[28:29], 0
	s_cbranch_scc0 .Lna_nr_w0f
	s_nop 15
	v_max_f32_e32 v216, v215, v220
	v_exp_f32_e64 v217, -v216
	v_add_f32_e32 v212, v212, v216
	v_and_b32_e32 v217, v217, v221
	v_sub_f32_e32 v66, v66, v216
	v_sub_f32_e32 v67, v67, v216
	v_sub_f32_e32 v68, v68, v216
	v_sub_f32_e32 v69, v69, v216
	v_sub_f32_e32 v70, v70, v216
	v_sub_f32_e32 v71, v71, v216
	v_sub_f32_e32 v72, v72, v216
	v_sub_f32_e32 v73, v73, v216
	v_sub_f32_e32 v74, v74, v216
	v_sub_f32_e32 v75, v75, v216
	v_sub_f32_e32 v76, v76, v216
	v_sub_f32_e32 v77, v77, v216
	v_sub_f32_e32 v78, v78, v216
	v_sub_f32_e32 v79, v79, v216
	v_sub_f32_e32 v80, v80, v216
	v_sub_f32_e32 v81, v81, v216
	v_sub_f32_e32 v82, v82, v216
	v_sub_f32_e32 v83, v83, v216
	v_sub_f32_e32 v84, v84, v216
	v_sub_f32_e32 v85, v85, v216
	v_sub_f32_e32 v114, v114, v216
	v_sub_f32_e32 v115, v115, v216
	v_sub_f32_e32 v116, v116, v216
	v_sub_f32_e32 v117, v117, v216
	v_sub_f32_e32 v118, v118, v216
	v_sub_f32_e32 v119, v119, v216
	v_sub_f32_e32 v120, v120, v216
	v_sub_f32_e32 v121, v121, v216
	v_sub_f32_e32 v122, v122, v216
	v_sub_f32_e32 v123, v123, v216
	v_sub_f32_e32 v124, v124, v216
	v_sub_f32_e32 v125, v125, v216
	v_sub_f32_e32 v126, v126, v216
	v_sub_f32_e32 v127, v127, v216
	v_sub_f32_e32 v128, v128, v216
	v_sub_f32_e32 v129, v129, v216
	v_sub_f32_e32 v130, v130, v216
	v_sub_f32_e32 v131, v131, v216
	v_sub_f32_e32 v132, v132, v216
	v_sub_f32_e32 v133, v133, v216
	v_mul_f32_e32 v213, v213, v217
	v_mul_f32_e32 v214, v214, v217
	v_mul_f32_e32 v2, v2, v217
	v_mul_f32_e32 v3, v3, v217
	v_mul_f32_e32 v4, v4, v217
	v_mul_f32_e32 v5, v5, v217
	v_mul_f32_e32 v6, v6, v217
	v_mul_f32_e32 v7, v7, v217
	v_mul_f32_e32 v8, v8, v217
	v_mul_f32_e32 v9, v9, v217
	v_mul_f32_e32 v10, v10, v217
	v_mul_f32_e32 v11, v11, v217
	v_mul_f32_e32 v12, v12, v217
	v_mul_f32_e32 v13, v13, v217
	v_mul_f32_e32 v14, v14, v217
	v_mul_f32_e32 v15, v15, v217
	v_mul_f32_e32 v16, v16, v217
	v_mul_f32_e32 v17, v17, v217
	v_mul_f32_e32 v18, v18, v217
	v_mul_f32_e32 v19, v19, v217
	v_mul_f32_e32 v20, v20, v217
	v_mul_f32_e32 v21, v21, v217
	v_mul_f32_e32 v22, v22, v217
	v_mul_f32_e32 v23, v23, v217
	v_mul_f32_e32 v24, v24, v217
	v_mul_f32_e32 v25, v25, v217
	v_mul_f32_e32 v26, v26, v217
	v_mul_f32_e32 v27, v27, v217
	v_mul_f32_e32 v28, v28, v217
	v_mul_f32_e32 v29, v29, v217
	v_mul_f32_e32 v30, v30, v217
	v_mul_f32_e32 v31, v31, v217
	v_mul_f32_e32 v32, v32, v217
	v_mul_f32_e32 v33, v33, v217
	v_mov_b32_e32 v220, 0
	v_mov_b32_e32 v221, -1
	s_mov_b64 s[26:27], 0

.Lna_nr_w0s:
.Lna_sl_b_w0s:
	s_waitcnt vmcnt(2)
	ds_write_b128 v204, v[188:191] offset:0
	ds_write_b64 v205, v[192:193] offset:8704
	ds_write_b64 v205, v[194:195] offset:8712
	global_load_dwordx4 v[188:191], v206, s[12:13]
	s_add_i32 s20, s20, 1
	s_add_u32 s12, s12, 0x2000
	s_addc_u32 s13, s13, 0
	s_cmp_eq_u32 s20, s22
	s_cselect_b32 s12, s16, s12
	s_cselect_b32 s13, s17, s13
	global_load_dwordx4 v[192:195], v207, s[14:15]
	s_add_i32 s21, s21, 1
	s_add_u32 s14, s14, 0x80
	s_addc_u32 s15, s15, 0
	s_cmp_eq_u32 s21, s22
	s_cselect_b32 s14, s18, s14
	s_cselect_b32 s15, s19, s15
	s_waitcnt lgkmcnt(0)
	s_barrier
.Lna_done_w0:
	s_add_i32 s24, s24, 1
	s_add_i32 s25, s25, 0x150
	s_add_i32 s33, s33, -1
	s_cmp_lg_u32 s33, 0
	s_cbranch_scc1 .Lna_wloop
	v_sub_f32_e32 v114, 0, v212
	v_mov_b32_e32 v115, v114
	v_mov_b32_e32 v116, v114
	v_mov_b32_e32 v117, v114
	v_mov_b32_e32 v118, v114
	v_mov_b32_e32 v119, v114
	v_mov_b32_e32 v120, v114
	v_mov_b32_e32 v121, v114
	v_mov_b32_e32 v122, v114
	v_mov_b32_e32 v123, v114
	v_mov_b32_e32 v124, v114
	v_mov_b32_e32 v125, v114
	v_mov_b32_e32 v126, v114
	v_mov_b32_e32 v127, v114
	v_mov_b32_e32 v128, v114
	v_mov_b32_e32 v129, v114
	v_mov_b32_e32 v130, v114
	v_mov_b32_e32 v131, v114
	v_mov_b32_e32 v132, v114
	v_mov_b32_e32 v133, v114
	v_mov_b32_e32 v134, v114
	v_mov_b32_e32 v135, v114
	v_mov_b32_e32 v136, v114
	v_mov_b32_e32 v137, v114
	v_mov_b32_e32 v138, v114
	v_mov_b32_e32 v139, v114
	v_mov_b32_e32 v140, v114
	v_mov_b32_e32 v141, v114
	v_mov_b32_e32 v142, v114
	v_mov_b32_e32 v143, v114
	v_mov_b32_e32 v144, v114
	v_mov_b32_e32 v145, v114
	s_sub_i32 s36, s24, s23
	s_cmp_lt_u32 s36, 8
	s_cselect_b64 s[40:41], -1, 0
	s_mov_b64 s[42:43], -1
	s_cmp_eq_u64 s[40:41], 0
	s_cbranch_scc1 .Lna_slow_wc
	ds_read_b128 v[146:149], v199 offset:0
	ds_read_b128 v[150:153], v200 offset:0
	ds_read_b128 v[154:157], v199 offset:32
	ds_read_b128 v[158:161], v200 offset:32
	v_exp_f32_e32 v66, v66
	v_exp_f32_e32 v67, v67
	v_exp_f32_e32 v68, v68
	v_exp_f32_e32 v69, v69
	s_waitcnt lgkmcnt(3)
	v_mfma_f32_32x32x16_bf16 v[34:49], v[146:149], v[98:101], v[114:129]
	ds_read_b128 v[146:149], v199 offset:64
	v_add_f32_e32 v213, v213, v66
	v_add_f32_e32 v214, v214, v67
	v_add_f32_e32 v213, v213, v68
	v_add_f32_e32 v214, v214, v69
	v_exp_f32_e32 v70, v70
	s_waitcnt lgkmcnt(3)
	v_mfma_f32_32x32x16_bf16 v[50:65], v[150:153], v[98:101], v[130:145]
	ds_read_b128 v[150:153], v200 offset:64
	v_exp_f32_e32 v71, v71
	v_exp_f32_e32 v72, v72
	v_exp_f32_e32 v73, v73
	s_waitcnt lgkmcnt(3)
	v_mfma_f32_32x32x16_bf16 v[34:49], v[154:157], v[102:105], v[34:49]
	ds_read_b128 v[154:157], v199 offset:96
	v_add_f32_e32 v213, v213, v70
	v_add_f32_e32 v214, v214, v71
	v_add_f32_e32 v213, v213, v72
	v_add_f32_e32 v214, v214, v73
	v_cvt_pk_bf16_f32 v66, v66, v67
	s_waitcnt lgkmcnt(3)
	v_mfma_f32_32x32x16_bf16 v[50:65], v[158:161], v[102:105], v[50:65]
	ds_read_b128 v[158:161], v200 offset:96
	v_cvt_pk_bf16_f32 v67, v68, v69
	v_cvt_pk_bf16_f32 v68, v70, v71
	v_cvt_pk_bf16_f32 v69, v72, v73
	v_exp_f32_e32 v74, v74
	v_exp_f32_e32 v75, v75
	s_waitcnt lgkmcnt(3)
	v_mfma_f32_32x32x16_bf16 v[34:49], v[146:149], v[106:109], v[34:49]
	ds_read_b64 v[162:163], v201 offset:8704
	ds_read_b64 v[164:165], v201 offset:8720
	v_exp_f32_e32 v76, v76
	v_exp_f32_e32 v77, v77
	v_add_f32_e32 v213, v213, v74
	s_waitcnt lgkmcnt(4)
	v_mfma_f32_32x32x16_bf16 v[50:65], v[150:153], v[106:109], v[50:65]
	ds_read_b64 v[166:167], v201 offset:13056
	ds_read_b64 v[168:169], v201 offset:13072
	v_add_f32_e32 v214, v214, v75
	v_add_f32_e32 v213, v213, v76
	v_add_f32_e32 v214, v214, v77
	v_exp_f32_e32 v78, v78
	v_exp_f32_e32 v79, v79
	s_waitcnt lgkmcnt(5)
	v_mfma_f32_32x32x16_bf16 v[34:49], v[154:157], v[110:113], v[34:49]
	ds_read_b64 v[170:171], v201 offset:8736
	ds_read_b64 v[172:173], v201 offset:8752
	v_exp_f32_e32 v80, v80
	v_exp_f32_e32 v81, v81
	v_add_f32_e32 v213, v213, v78
	v_add_f32_e32 v214, v214, v79
	s_waitcnt lgkmcnt(6)
	v_mfma_f32_32x32x16_bf16 v[50:65], v[158:161], v[110:113], v[50:65]
	ds_read_b64 v[174:175], v201 offset:13088
	ds_read_b64 v[176:177], v201 offset:13104
	v_add_f32_e32 v213, v213, v80
	v_add_f32_e32 v214, v214, v81
	v_cvt_pk_bf16_f32 v74, v74, v75
	v_cvt_pk_bf16_f32 v75, v76, v77
	v_cvt_pk_bf16_f32 v76, v78, v79
	v_cvt_pk_bf16_f32 v77, v80, v81
	s_waitcnt lgkmcnt(6)
	v_mfma_f32_32x32x16_bf16 v[2:17], v[162:165], v[66:69], v[2:17]
	ds_read_b64 v[162:163], v202 offset:8704
	ds_read_b64 v[164:165], v203 offset:8704
	v_exp_f32_e32 v82, v82
	v_exp_f32_e32 v83, v83
	v_exp_f32_e32 v84, v84
	s_waitcnt lgkmcnt(6)
	v_mfma_f32_32x32x16_bf16 v[18:33], v[166:169], v[66:69], v[18:33]
	ds_read_b64 v[166:167], v202 offset:13056
	ds_read_b64 v[168:169], v203 offset:13056
	v_exp_f32_e32 v85, v85
	v_add_f32_e32 v213, v213, v82
	v_add_f32_e32 v214, v214, v83
	v_add_f32_e32 v213, v213, v84
	v_add_f32_e32 v214, v214, v85
	s_waitcnt lgkmcnt(6)
	v_mfma_f32_32x32x16_bf16 v[2:17], v[170:173], v[74:77], v[2:17]
	v_cvt_pk_bf16_f32 v184, v82, v83
	v_cvt_pk_bf16_f32 v185, v84, v85
	v_max3_f32 v216, v34, v35, v36
	v_max3_f32 v217, v50, v51, v52
	v_max3_f32 v216, v216, v37, v38
	v_max3_f32 v217, v217, v53, v54
	s_waitcnt lgkmcnt(4)
	v_mfma_f32_32x32x16_bf16 v[18:33], v[174:177], v[74:77], v[18:33]
	s_waitcnt vmcnt(2)
	ds_write_b128 v204, v[230:233] offset:9216
	ds_write_b64 v205, v[234:235] offset:0
	ds_write_b64 v205, v[236:237] offset:8
	global_load_dwordx4 v[230:233], v206, s[12:13]
	s_add_u32 s12, s12, 0x2000
	s_addc_u32 s13, s13, 0
	global_load_dwordx4 v[234:237], v207, s[14:15]
	s_add_u32 s14, s14, 0x80
	s_addc_u32 s15, s15, 0
	v_max3_f32 v216, v216, v39, v40
	v_max3_f32 v217, v217, v55, v56
	v_max3_f32 v216, v216, v41, v42
	v_max3_f32 v217, v217, v57, v58
	v_max3_f32 v216, v216, v43, v44
	v_max3_f32 v217, v217, v59, v60
	s_waitcnt lgkmcnt(5)
	v_mfma_f32_32x32x16_bf16 v[2:17], v[162:165], v[184:187], v[2:17]
	v_max3_f32 v216, v216, v45, v46
	v_max3_f32 v217, v217, v61, v62
	v_max3_f32 v216, v216, v47, v48
	v_max3_f32 v217, v217, v63, v64
	v_max_f32_e32 v216, v216, v49
	v_max_f32_e32 v217, v217, v65
	s_waitcnt lgkmcnt(3)
	v_mfma_f32_32x32x16_bf16 v[18:33], v[166:169], v[184:187], v[18:33]
	v_max_f32_e32 v216, v216, v217
	v_mov_b32_e32 v217, v216
	s_nop 1
	v_permlane32_swap_b32_e32 v216, v217
	v_max_f32_e32 v215, v216, v217
	v_cmp_lt_f32_e32 vcc, 4.0, v215
	s_cbranch_vccz .Lna_nr_wcf
	s_nop 15
	v_max_f32_e32 v216, v215, v220
	v_exp_f32_e64 v217, -v216
	v_add_f32_e32 v212, v212, v216
	v_and_b32_e32 v217, v217, v221
	v_sub_f32_e32 v34, v34, v216
	v_sub_f32_e32 v35, v35, v216
	v_sub_f32_e32 v36, v36, v216
	v_sub_f32_e32 v37, v37, v216
	v_sub_f32_e32 v38, v38, v216
	v_sub_f32_e32 v39, v39, v216
	v_sub_f32_e32 v40, v40, v216
	v_sub_f32_e32 v41, v41, v216
	v_sub_f32_e32 v42, v42, v216
	v_sub_f32_e32 v43, v43, v216
	v_sub_f32_e32 v44, v44, v216
	v_sub_f32_e32 v45, v45, v216
	v_sub_f32_e32 v46, v46, v216
	v_sub_f32_e32 v47, v47, v216
	v_sub_f32_e32 v48, v48, v216
	v_sub_f32_e32 v49, v49, v216
	v_sub_f32_e32 v50, v50, v216
	v_sub_f32_e32 v51, v51, v216
	v_sub_f32_e32 v52, v52, v216
	v_sub_f32_e32 v53, v53, v216
	v_sub_f32_e32 v54, v54, v216
	v_sub_f32_e32 v55, v55, v216
	v_sub_f32_e32 v56, v56, v216
	v_sub_f32_e32 v57, v57, v216
	v_sub_f32_e32 v58, v58, v216
	v_sub_f32_e32 v59, v59, v216
	v_sub_f32_e32 v60, v60, v216
	v_sub_f32_e32 v61, v61, v216
	v_sub_f32_e32 v62, v62, v216
	v_sub_f32_e32 v63, v63, v216
	v_sub_f32_e32 v64, v64, v216
	v_sub_f32_e32 v65, v65, v216
	v_sub_f32_e32 v114, v114, v216
	v_sub_f32_e32 v115, v115, v216
	v_sub_f32_e32 v116, v116, v216
	v_sub_f32_e32 v117, v117, v216
	v_sub_f32_e32 v118, v118, v216
	v_sub_f32_e32 v119, v119, v216
	v_sub_f32_e32 v120, v120, v216
	v_sub_f32_e32 v121, v121, v216
	v_sub_f32_e32 v122, v122, v216
	v_sub_f32_e32 v123, v123, v216
	v_sub_f32_e32 v124, v124, v216
	v_sub_f32_e32 v125, v125, v216
	v_sub_f32_e32 v126, v126, v216
	v_sub_f32_e32 v127, v127, v216
	v_sub_f32_e32 v128, v128, v216
	v_sub_f32_e32 v129, v129, v216
	v_sub_f32_e32 v130, v130, v216
	v_sub_f32_e32 v131, v131, v216
	v_sub_f32_e32 v132, v132, v216
	v_sub_f32_e32 v133, v133, v216
	v_sub_f32_e32 v134, v134, v216
	v_sub_f32_e32 v135, v135, v216
	v_sub_f32_e32 v136, v136, v216
	v_sub_f32_e32 v137, v137, v216
	v_sub_f32_e32 v138, v138, v216
	v_sub_f32_e32 v139, v139, v216
	v_sub_f32_e32 v140, v140, v216
	v_sub_f32_e32 v141, v141, v216
	v_sub_f32_e32 v142, v142, v216
	v_sub_f32_e32 v143, v143, v216
	v_sub_f32_e32 v144, v144, v216
	v_sub_f32_e32 v145, v145, v216
	v_mul_f32_e32 v213, v213, v217
	v_mul_f32_e32 v214, v214, v217
	v_mul_f32_e32 v2, v2, v217
	v_mul_f32_e32 v3, v3, v217
	v_mul_f32_e32 v4, v4, v217
	v_mul_f32_e32 v5, v5, v217
	v_mul_f32_e32 v6, v6, v217
	v_mul_f32_e32 v7, v7, v217
	v_mul_f32_e32 v8, v8, v217
	v_mul_f32_e32 v9, v9, v217
	v_mul_f32_e32 v10, v10, v217
	v_mul_f32_e32 v11, v11, v217
	v_mul_f32_e32 v12, v12, v217
	v_mul_f32_e32 v13, v13, v217
	v_mul_f32_e32 v14, v14, v217
	v_mul_f32_e32 v15, v15, v217
	v_mul_f32_e32 v16, v16, v217
	v_mul_f32_e32 v17, v17, v217
	v_mul_f32_e32 v18, v18, v217
	v_mul_f32_e32 v19, v19, v217
	v_mul_f32_e32 v20, v20, v217
	v_mul_f32_e32 v21, v21, v217
	v_mul_f32_e32 v22, v22, v217
	v_mul_f32_e32 v23, v23, v217
	v_mul_f32_e32 v24, v24, v217
	v_mul_f32_e32 v25, v25, v217
	v_mul_f32_e32 v26, v26, v217
	v_mul_f32_e32 v27, v27, v217
	v_mul_f32_e32 v28, v28, v217
	v_mul_f32_e32 v29, v29, v217
	v_mul_f32_e32 v30, v30, v217
	v_mul_f32_e32 v31, v31, v217
	v_mul_f32_e32 v32, v32, v217
	v_mul_f32_e32 v33, v33, v217

.Lna_nr_wcs:
.Lna_sl_b_wcs:
	s_waitcnt vmcnt(2)
	ds_write_b128 v204, v[230:233] offset:9216
	ds_write_b64 v205, v[234:235] offset:0
	ds_write_b64 v205, v[236:237] offset:8
	global_load_dwordx4 v[230:233], v206, s[12:13]
	s_add_u32 s12, s12, 0x2000
	s_addc_u32 s13, s13, 0
	global_load_dwordx4 v[234:237], v207, s[14:15]
	s_add_u32 s14, s14, 0x80
	s_addc_u32 s15, s15, 0
	s_waitcnt lgkmcnt(0)
	s_barrier
.Lna_done_wc:
	ds_read_b128 v[146:149], v199 offset:9216
	ds_read_b128 v[150:153], v200 offset:9216
	ds_read_b128 v[154:157], v199 offset:9248
	ds_read_b128 v[158:161], v200 offset:9248
	v_exp_f32_e32 v34, v34
	v_exp_f32_e32 v35, v35
	v_exp_f32_e32 v36, v36
	v_exp_f32_e32 v37, v37
	s_waitcnt lgkmcnt(3)
	v_mfma_f32_32x32x16_bf16 v[66:81], v[146:149], v[98:101], v[114:129]
	ds_read_b128 v[146:149], v199 offset:9280
	v_add_f32_e32 v213, v213, v34
	v_add_f32_e32 v214, v214, v35
	v_add_f32_e32 v213, v213, v36
	v_add_f32_e32 v214, v214, v37
	v_exp_f32_e32 v38, v38
	v_exp_f32_e32 v39, v39
	s_waitcnt lgkmcnt(3)
	v_mfma_f32_32x32x16_bf16 v[82:97], v[150:153], v[98:101], v[130:145]
	ds_read_b128 v[150:153], v200 offset:9280
	v_exp_f32_e32 v40, v40
	v_exp_f32_e32 v41, v41
	v_add_f32_e32 v213, v213, v38
	v_add_f32_e32 v214, v214, v39
	v_add_f32_e32 v213, v213, v40
	v_add_f32_e32 v214, v214, v41
	s_waitcnt lgkmcnt(3)
	v_mfma_f32_32x32x16_bf16 v[66:81], v[154:157], v[102:105], v[66:81]
	ds_read_b128 v[154:157], v199 offset:9312
	v_cvt_pk_bf16_f32 v34, v34, v35
	v_cvt_pk_bf16_f32 v35, v36, v37
	v_cvt_pk_bf16_f32 v36, v38, v39
	v_cvt_pk_bf16_f32 v37, v40, v41
	v_exp_f32_e32 v42, v42
	v_exp_f32_e32 v43, v43
	s_waitcnt lgkmcnt(3)
	v_mfma_f32_32x32x16_bf16 v[82:97], v[158:161], v[102:105], v[82:97]
	ds_read_b128 v[158:161], v200 offset:9312
	v_exp_f32_e32 v44, v44
	v_exp_f32_e32 v45, v45
	v_add_f32_e32 v213, v213, v42
	v_add_f32_e32 v214, v214, v43
	v_add_f32_e32 v213, v213, v44
	v_add_f32_e32 v214, v214, v45
	s_waitcnt lgkmcnt(3)
	v_mfma_f32_32x32x16_bf16 v[66:81], v[146:149], v[106:109], v[66:81]
	ds_read_b64 v[162:163], v201 offset:0
	ds_read_b64 v[164:165], v201 offset:16
	v_exp_f32_e32 v46, v46
	v_exp_f32_e32 v47, v47
	v_exp_f32_e32 v48, v48
	v_exp_f32_e32 v49, v49
	s_waitcnt lgkmcnt(4)
	v_mfma_f32_32x32x16_bf16 v[82:97], v[150:153], v[106:109], v[82:97]
	ds_read_b64 v[166:167], v201 offset:4352
	ds_read_b64 v[168:169], v201 offset:4368
	v_add_f32_e32 v213, v213, v46
	v_add_f32_e32 v214, v214, v47
	v_add_f32_e32 v213, v213, v48
	v_add_f32_e32 v214, v214, v49
	v_cvt_pk_bf16_f32 v42, v42, v43
	v_cvt_pk_bf16_f32 v43, v44, v45
	v_cvt_pk_bf16_f32 v44, v46, v47
	v_cvt_pk_bf16_f32 v45, v48, v49
	s_waitcnt lgkmcnt(5)
	v_mfma_f32_32x32x16_bf16 v[66:81], v[154:157], v[110:113], v[66:81]
	ds_read_b64 v[170:171], v201 offset:32
	ds_read_b64 v[172:173], v201 offset:48
	v_exp_f32_e32 v50, v50
	v_exp_f32_e32 v51, v51
	v_exp_f32_e32 v52, v52
	v_exp_f32_e32 v53, v53
	s_waitcnt lgkmcnt(6)
	v_mfma_f32_32x32x16_bf16 v[82:97], v[158:161], v[110:113], v[82:97]
	ds_read_b64 v[174:175], v201 offset:4384
	ds_read_b64 v[176:177], v201 offset:4400
	v_add_f32_e32 v213, v213, v50
	v_add_f32_e32 v214, v214, v51
	v_add_f32_e32 v213, v213, v52
	v_add_f32_e32 v214, v214, v53
	v_exp_f32_e32 v54, v54
	v_exp_f32_e32 v55, v55
	s_waitcnt lgkmcnt(6)
	v_mfma_f32_32x32x16_bf16 v[2:17], v[162:165], v[34:37], v[2:17]
	ds_read_b64 v[162:163], v202 offset:0
	ds_read_b64 v[164:165], v203 offset:0
	v_exp_f32_e32 v56, v56
	v_exp_f32_e32 v57, v57
	v_add_f32_e32 v213, v213, v54
	v_add_f32_e32 v214, v214, v55
	v_add_f32_e32 v213, v213, v56
	s_waitcnt lgkmcnt(6)
	v_mfma_f32_32x32x16_bf16 v[18:33], v[166:169], v[34:37], v[18:33]
	ds_read_b64 v[166:167], v202 offset:4352
	ds_read_b64 v[168:169], v203 offset:4352
	v_add_f32_e32 v214, v214, v57
	v_cvt_pk_bf16_f32 v50, v50, v51
	v_cvt_pk_bf16_f32 v51, v52, v53
	v_cvt_pk_bf16_f32 v52, v54, v55
	v_cvt_pk_bf16_f32 v53, v56, v57
	v_exp_f32_e32 v58, v58
	v_exp_f32_e32 v59, v59
	s_waitcnt lgkmcnt(6)
	v_mfma_f32_32x32x16_bf16 v[2:17], v[170:173], v[42:45], v[2:17]
	ds_read_b64 v[170:171], v203 offset:16
	ds_read_b64 v[172:173], v203 offset:32
	v_exp_f32_e32 v60, v60
	v_exp_f32_e32 v61, v61
	v_add_f32_e32 v213, v213, v58
	v_add_f32_e32 v214, v214, v59
	v_add_f32_e32 v213, v213, v60
	s_waitcnt lgkmcnt(6)
	v_mfma_f32_32x32x16_bf16 v[18:33], v[174:177], v[42:45], v[18:33]
	ds_read_b64 v[174:175], v203 offset:4368
	ds_read_b64 v[176:177], v203 offset:4384
	s_waitcnt vmcnt(2)
	ds_write_b128 v204, v[188:191] offset:0
	ds_write_b64 v205, v[192:193] offset:8704
	ds_write_b64 v205, v[194:195] offset:8712
	global_load_dwordx4 v[192:195], v207, s[14:15]
	s_add_u32 s14, s14, 0x80
	s_addc_u32 s15, s15, 0
	v_add_f32_e32 v214, v214, v61
	v_exp_f32_e32 v62, v62
	v_exp_f32_e32 v63, v63
	v_exp_f32_e32 v64, v64
	v_exp_f32_e32 v65, v65
	s_waitcnt lgkmcnt(9)
	v_mfma_f32_32x32x16_bf16 v[2:17], v[162:165], v[50:53], v[2:17]
	v_add_f32_e32 v213, v213, v62
	v_add_f32_e32 v214, v214, v63
	v_add_f32_e32 v213, v213, v64
	v_add_f32_e32 v214, v214, v65
	v_cvt_pk_bf16_f32 v58, v58, v59
	v_cvt_pk_bf16_f32 v59, v60, v61
	v_cvt_pk_bf16_f32 v60, v62, v63
	s_waitcnt lgkmcnt(7)
	v_mfma_f32_32x32x16_bf16 v[18:33], v[166:169], v[50:53], v[18:33]
	v_cvt_pk_bf16_f32 v61, v64, v65
	v_max3_f32 v216, v66, v67, v68
	v_max3_f32 v217, v82, v83, v84
	v_max3_f32 v216, v216, v69, v70
	v_max3_f32 v217, v217, v85, v86
	v_max3_f32 v216, v216, v71, v72
	v_max3_f32 v217, v217, v87, v88
	v_max3_f32 v216, v216, v73, v74
	s_waitcnt lgkmcnt(5)
	v_mfma_f32_32x32x16_bf16 v[2:17], v[170:173], v[58:61], v[2:17]
	v_max3_f32 v217, v217, v89, v90
	v_max3_f32 v216, v216, v75, v76
	v_max3_f32 v217, v217, v91, v92
	v_max3_f32 v216, v216, v77, v78
	v_max3_f32 v217, v217, v93, v94
	v_max3_f32 v216, v216, v79, v80
	v_max3_f32 v217, v217, v95, v96
	v_max_f32_e32 v216, v216, v81
	s_waitcnt lgkmcnt(3)
	v_mfma_f32_32x32x16_bf16 v[18:33], v[174:177], v[58:61], v[18:33]
	v_max_f32_e32 v217, v217, v97
	v_max_f32_e32 v216, v216, v217
	v_mov_b32_e32 v217, v216
	s_nop 1
	v_permlane32_swap_b32_e32 v216, v217
	v_max_f32_e32 v215, v216, v217
	v_cmp_lt_f32_e32 vcc, 4.0, v215
	s_cbranch_vccz .Lna_nr_c0
	s_nop 15
	v_max_f32_e32 v216, v215, v220
	v_exp_f32_e64 v217, -v216
	v_add_f32_e32 v212, v212, v216
	v_and_b32_e32 v217, v217, v221
	v_sub_f32_e32 v66, v66, v216
	v_sub_f32_e32 v67, v67, v216
	v_sub_f32_e32 v68, v68, v216
	v_sub_f32_e32 v69, v69, v216
	v_sub_f32_e32 v70, v70, v216
	v_sub_f32_e32 v71, v71, v216
	v_sub_f32_e32 v72, v72, v216
	v_sub_f32_e32 v73, v73, v216
	v_sub_f32_e32 v74, v74, v216
	v_sub_f32_e32 v75, v75, v216
	v_sub_f32_e32 v76, v76, v216
	v_sub_f32_e32 v77, v77, v216
	v_sub_f32_e32 v78, v78, v216
	v_sub_f32_e32 v79, v79, v216
	v_sub_f32_e32 v80, v80, v216
	v_sub_f32_e32 v81, v81, v216
	v_sub_f32_e32 v82, v82, v216
	v_sub_f32_e32 v83, v83, v216
	v_sub_f32_e32 v84, v84, v216
	v_sub_f32_e32 v85, v85, v216
	v_sub_f32_e32 v86, v86, v216
	v_sub_f32_e32 v87, v87, v216
	v_sub_f32_e32 v88, v88, v216
	v_sub_f32_e32 v89, v89, v216
	v_sub_f32_e32 v90, v90, v216
	v_sub_f32_e32 v91, v91, v216
	v_sub_f32_e32 v92, v92, v216
	v_sub_f32_e32 v93, v93, v216
	v_sub_f32_e32 v94, v94, v216
	v_sub_f32_e32 v95, v95, v216
	v_sub_f32_e32 v96, v96, v216
	v_sub_f32_e32 v97, v97, v216
	v_sub_f32_e32 v114, v114, v216
	v_sub_f32_e32 v115, v115, v216
	v_sub_f32_e32 v116, v116, v216
	v_sub_f32_e32 v117, v117, v216
	v_sub_f32_e32 v118, v118, v216
	v_sub_f32_e32 v119, v119, v216
	v_sub_f32_e32 v120, v120, v216
	v_sub_f32_e32 v121, v121, v216
	v_sub_f32_e32 v122, v122, v216
	v_sub_f32_e32 v123, v123, v216
	v_sub_f32_e32 v124, v124, v216
	v_sub_f32_e32 v125, v125, v216
	v_sub_f32_e32 v126, v126, v216
	v_sub_f32_e32 v127, v127, v216
	v_sub_f32_e32 v128, v128, v216
	v_sub_f32_e32 v129, v129, v216
	v_sub_f32_e32 v130, v130, v216
	v_sub_f32_e32 v131, v131, v216
	v_sub_f32_e32 v132, v132, v216
	v_sub_f32_e32 v133, v133, v216
	v_sub_f32_e32 v134, v134, v216
	v_sub_f32_e32 v135, v135, v216
	v_sub_f32_e32 v136, v136, v216
	v_sub_f32_e32 v137, v137, v216
	v_sub_f32_e32 v138, v138, v216
	v_sub_f32_e32 v139, v139, v216
	v_sub_f32_e32 v140, v140, v216
	v_sub_f32_e32 v141, v141, v216
	v_sub_f32_e32 v142, v142, v216
	v_sub_f32_e32 v143, v143, v216
	v_sub_f32_e32 v144, v144, v216
	v_sub_f32_e32 v145, v145, v216
	v_mul_f32_e32 v213, v213, v217
	v_mul_f32_e32 v214, v214, v217
	v_mul_f32_e32 v2, v2, v217
	v_mul_f32_e32 v3, v3, v217
	v_mul_f32_e32 v4, v4, v217
	v_mul_f32_e32 v5, v5, v217
	v_mul_f32_e32 v6, v6, v217
	v_mul_f32_e32 v7, v7, v217
	v_mul_f32_e32 v8, v8, v217
	v_mul_f32_e32 v9, v9, v217
	v_mul_f32_e32 v10, v10, v217
	v_mul_f32_e32 v11, v11, v217
	v_mul_f32_e32 v12, v12, v217
	v_mul_f32_e32 v13, v13, v217
	v_mul_f32_e32 v14, v14, v217
	v_mul_f32_e32 v15, v15, v217
	v_mul_f32_e32 v16, v16, v217
	v_mul_f32_e32 v17, v17, v217
	v_mul_f32_e32 v18, v18, v217
	v_mul_f32_e32 v19, v19, v217
	v_mul_f32_e32 v20, v20, v217
	v_mul_f32_e32 v21, v21, v217
	v_mul_f32_e32 v22, v22, v217
	v_mul_f32_e32 v23, v23, v217
	v_mul_f32_e32 v24, v24, v217
	v_mul_f32_e32 v25, v25, v217
	v_mul_f32_e32 v26, v26, v217
	v_mul_f32_e32 v27, v27, v217
	v_mul_f32_e32 v28, v28, v217
	v_mul_f32_e32 v29, v29, v217
	v_mul_f32_e32 v30, v30, v217
	v_mul_f32_e32 v31, v31, v217
	v_mul_f32_e32 v32, v32, v217
	v_mul_f32_e32 v33, v33, v217
.Lna_nr_c0:
	s_waitcnt lgkmcnt(0)
	s_barrier
	ds_read_b128 v[146:149], v199 offset:0
	ds_read_b128 v[150:153], v200 offset:0
	ds_read_b128 v[154:157], v199 offset:32
	ds_read_b128 v[158:161], v200 offset:32
	v_exp_f32_e32 v66, v66
	v_exp_f32_e32 v67, v67
	v_exp_f32_e32 v68, v68
	v_exp_f32_e32 v69, v69
	s_waitcnt lgkmcnt(3)
	v_mfma_f32_32x32x16_bf16 v[34:49], v[146:149], v[98:101], v[114:129]
	ds_read_b128 v[146:149], v199 offset:64
	v_add_f32_e32 v213, v213, v66
	v_add_f32_e32 v214, v214, v67
	v_add_f32_e32 v213, v213, v68
	v_add_f32_e32 v214, v214, v69
	v_exp_f32_e32 v70, v70
	v_exp_f32_e32 v71, v71
	s_waitcnt lgkmcnt(3)
	v_mfma_f32_32x32x16_bf16 v[50:65], v[150:153], v[98:101], v[130:145]
	ds_read_b128 v[150:153], v200 offset:64
	v_exp_f32_e32 v72, v72
	v_exp_f32_e32 v73, v73
	v_add_f32_e32 v213, v213, v70
	v_add_f32_e32 v214, v214, v71
	v_add_f32_e32 v213, v213, v72
	v_add_f32_e32 v214, v214, v73
	s_waitcnt lgkmcnt(3)
	v_mfma_f32_32x32x16_bf16 v[34:49], v[154:157], v[102:105], v[34:49]
	ds_read_b128 v[154:157], v199 offset:96
	v_cvt_pk_bf16_f32 v66, v66, v67
	v_cvt_pk_bf16_f32 v67, v68, v69
	v_cvt_pk_bf16_f32 v68, v70, v71
	v_cvt_pk_bf16_f32 v69, v72, v73
	v_exp_f32_e32 v74, v74
	v_exp_f32_e32 v75, v75
	s_waitcnt lgkmcnt(3)
	v_mfma_f32_32x32x16_bf16 v[50:65], v[158:161], v[102:105], v[50:65]
	ds_read_b128 v[158:161], v200 offset:96
	v_exp_f32_e32 v76, v76
	v_exp_f32_e32 v77, v77
	v_add_f32_e32 v213, v213, v74
	v_add_f32_e32 v214, v214, v75
	v_add_f32_e32 v213, v213, v76
	v_add_f32_e32 v214, v214, v77
	s_waitcnt lgkmcnt(3)
	v_mfma_f32_32x32x16_bf16 v[34:49], v[146:149], v[106:109], v[34:49]
	ds_read_b64 v[162:163], v201 offset:8704
	ds_read_b64 v[164:165], v201 offset:8720
	v_exp_f32_e32 v78, v78
	v_exp_f32_e32 v79, v79
	v_exp_f32_e32 v80, v80
	v_exp_f32_e32 v81, v81
	s_waitcnt lgkmcnt(4)
	v_mfma_f32_32x32x16_bf16 v[50:65], v[150:153], v[106:109], v[50:65]
	ds_read_b64 v[166:167], v201 offset:13056
	ds_read_b64 v[168:169], v201 offset:13072
	v_add_f32_e32 v213, v213, v78
	v_add_f32_e32 v214, v214, v79
	v_add_f32_e32 v213, v213, v80
	v_add_f32_e32 v214, v214, v81
	v_cvt_pk_bf16_f32 v74, v74, v75
	v_cvt_pk_bf16_f32 v75, v76, v77
	v_cvt_pk_bf16_f32 v76, v78, v79
	v_cvt_pk_bf16_f32 v77, v80, v81
	s_waitcnt lgkmcnt(5)
	v_mfma_f32_32x32x16_bf16 v[34:49], v[154:157], v[110:113], v[34:49]
	ds_read_b64 v[170:171], v201 offset:8736
	ds_read_b64 v[172:173], v201 offset:8752
	v_exp_f32_e32 v82, v82
	v_exp_f32_e32 v83, v83
	v_exp_f32_e32 v84, v84
	v_exp_f32_e32 v85, v85
	s_waitcnt lgkmcnt(6)
	v_mfma_f32_32x32x16_bf16 v[50:65], v[158:161], v[110:113], v[50:65]
	ds_read_b64 v[174:175], v201 offset:13088
	ds_read_b64 v[176:177], v201 offset:13104
	v_add_f32_e32 v213, v213, v82
	v_add_f32_e32 v214, v214, v83
	v_add_f32_e32 v213, v213, v84
	v_add_f32_e32 v214, v214, v85
	v_exp_f32_e32 v86, v86
	v_exp_f32_e32 v87, v87
	s_waitcnt lgkmcnt(6)
	v_mfma_f32_32x32x16_bf16 v[2:17], v[162:165], v[66:69], v[2:17]
	ds_read_b64 v[162:163], v202 offset:8704
	ds_read_b64 v[164:165], v203 offset:8704
	v_exp_f32_e32 v88, v88
	v_exp_f32_e32 v89, v89
	v_add_f32_e32 v213, v213, v86
	v_add_f32_e32 v214, v214, v87
	v_add_f32_e32 v213, v213, v88
	s_waitcnt lgkmcnt(6)
	v_mfma_f32_32x32x16_bf16 v[18:33], v[166:169], v[66:69], v[18:33]
	ds_read_b64 v[166:167], v202 offset:13056
	ds_read_b64 v[168:169], v203 offset:13056
	v_add_f32_e32 v214, v214, v89
	v_cvt_pk_bf16_f32 v82, v82, v83
	v_cvt_pk_bf16_f32 v83, v84, v85
	v_cvt_pk_bf16_f32 v84, v86, v87
	v_cvt_pk_bf16_f32 v85, v88, v89
	v_exp_f32_e32 v90, v90
	v_exp_f32_e32 v91, v91
	s_waitcnt lgkmcnt(6)
	v_mfma_f32_32x32x16_bf16 v[2:17], v[170:173], v[74:77], v[2:17]
	ds_read_b64 v[170:171], v203 offset:8720
	ds_read_b64 v[172:173], v203 offset:8736
	v_exp_f32_e32 v92, v92
	v_exp_f32_e32 v93, v93
	v_add_f32_e32 v213, v213, v90
	v_add_f32_e32 v214, v214, v91
	v_add_f32_e32 v213, v213, v92
	s_waitcnt lgkmcnt(6)
	v_mfma_f32_32x32x16_bf16 v[18:33], v[174:177], v[74:77], v[18:33]
	ds_read_b64 v[174:175], v203 offset:13072
	ds_read_b64 v[176:177], v203 offset:13088
	s_waitcnt vmcnt(1)
	ds_write_b128 v204, v[230:233] offset:9216
	ds_write_b64 v205, v[234:235] offset:0
	ds_write_b64 v205, v[236:237] offset:8
	v_add_f32_e32 v214, v214, v93
	v_exp_f32_e32 v94, v94
	v_exp_f32_e32 v95, v95
	v_exp_f32_e32 v96, v96
	v_exp_f32_e32 v97, v97
	s_waitcnt lgkmcnt(9)
	v_mfma_f32_32x32x16_bf16 v[2:17], v[162:165], v[82:85], v[2:17]
	v_add_f32_e32 v213, v213, v94
	v_add_f32_e32 v214, v214, v95
	v_add_f32_e32 v213, v213, v96
	v_add_f32_e32 v214, v214, v97
	v_cvt_pk_bf16_f32 v90, v90, v91
	v_cvt_pk_bf16_f32 v91, v92, v93
	v_cvt_pk_bf16_f32 v92, v94, v95
	s_waitcnt lgkmcnt(7)
	v_mfma_f32_32x32x16_bf16 v[18:33], v[166:169], v[82:85], v[18:33]
	v_cvt_pk_bf16_f32 v93, v96, v97
	v_max3_f32 v216, v34, v35, v36
	v_max3_f32 v217, v50, v51, v52
	v_max3_f32 v216, v216, v37, v38
	v_max3_f32 v217, v217, v53, v54
	v_max3_f32 v216, v216, v39, v40
	v_max3_f32 v217, v217, v55, v56
	v_max3_f32 v216, v216, v41, v42
	s_waitcnt lgkmcnt(5)
	v_mfma_f32_32x32x16_bf16 v[2:17], v[170:173], v[90:93], v[2:17]
	v_max3_f32 v217, v217, v57, v58
	v_max3_f32 v216, v216, v43, v44
	v_max3_f32 v217, v217, v59, v60
	v_max3_f32 v216, v216, v45, v46
	v_max3_f32 v217, v217, v61, v62
	v_max3_f32 v216, v216, v47, v48
	v_max3_f32 v217, v217, v63, v64
	v_max_f32_e32 v216, v216, v49
	s_waitcnt lgkmcnt(3)
	v_mfma_f32_32x32x16_bf16 v[18:33], v[174:177], v[90:93], v[18:33]
	v_max_f32_e32 v217, v217, v65
	v_max_f32_e32 v216, v216, v217
	v_mov_b32_e32 v217, v216
	s_nop 1
	v_permlane32_swap_b32_e32 v216, v217
	v_max_f32_e32 v215, v216, v217
	v_cmp_lt_f32_e32 vcc, 4.0, v215
	s_cbranch_vccz .Lna_nr_c1
	s_nop 15
	v_max_f32_e32 v216, v215, v220
	v_exp_f32_e64 v217, -v216
	v_add_f32_e32 v212, v212, v216
	v_and_b32_e32 v217, v217, v221
	v_sub_f32_e32 v34, v34, v216
	v_sub_f32_e32 v35, v35, v216
	v_sub_f32_e32 v36, v36, v216
	v_sub_f32_e32 v37, v37, v216
	v_sub_f32_e32 v38, v38, v216
	v_sub_f32_e32 v39, v39, v216
	v_sub_f32_e32 v40, v40, v216
	v_sub_f32_e32 v41, v41, v216
	v_sub_f32_e32 v42, v42, v216
	v_sub_f32_e32 v43, v43, v216
	v_sub_f32_e32 v44, v44, v216
	v_sub_f32_e32 v45, v45, v216
	v_sub_f32_e32 v46, v46, v216
	v_sub_f32_e32 v47, v47, v216
	v_sub_f32_e32 v48, v48, v216
	v_sub_f32_e32 v49, v49, v216
	v_sub_f32_e32 v50, v50, v216
	v_sub_f32_e32 v51, v51, v216
	v_sub_f32_e32 v52, v52, v216
	v_sub_f32_e32 v53, v53, v216
	v_sub_f32_e32 v54, v54, v216
	v_sub_f32_e32 v55, v55, v216
	v_sub_f32_e32 v56, v56, v216
	v_sub_f32_e32 v57, v57, v216
	v_sub_f32_e32 v58, v58, v216
	v_sub_f32_e32 v59, v59, v216
	v_sub_f32_e32 v60, v60, v216
	v_sub_f32_e32 v61, v61, v216
	v_sub_f32_e32 v62, v62, v216
	v_sub_f32_e32 v63, v63, v216
	v_sub_f32_e32 v64, v64, v216
	v_sub_f32_e32 v65, v65, v216
	v_sub_f32_e32 v114, v114, v216
	v_sub_f32_e32 v115, v115, v216
	v_sub_f32_e32 v116, v116, v216
	v_sub_f32_e32 v117, v117, v216
	v_sub_f32_e32 v118, v118, v216
	v_sub_f32_e32 v119, v119, v216
	v_sub_f32_e32 v120, v120, v216
	v_sub_f32_e32 v121, v121, v216
	v_sub_f32_e32 v122, v122, v216
	v_sub_f32_e32 v123, v123, v216
	v_sub_f32_e32 v124, v124, v216
	v_sub_f32_e32 v125, v125, v216
	v_sub_f32_e32 v126, v126, v216
	v_sub_f32_e32 v127, v127, v216
	v_sub_f32_e32 v128, v128, v216
	v_sub_f32_e32 v129, v129, v216
	v_sub_f32_e32 v130, v130, v216
	v_sub_f32_e32 v131, v131, v216
	v_sub_f32_e32 v132, v132, v216
	v_sub_f32_e32 v133, v133, v216
	v_sub_f32_e32 v134, v134, v216
	v_sub_f32_e32 v135, v135, v216
	v_sub_f32_e32 v136, v136, v216
	v_sub_f32_e32 v137, v137, v216
	v_sub_f32_e32 v138, v138, v216
	v_sub_f32_e32 v139, v139, v216
	v_sub_f32_e32 v140, v140, v216
	v_sub_f32_e32 v141, v141, v216
	v_sub_f32_e32 v142, v142, v216
	v_sub_f32_e32 v143, v143, v216
	v_sub_f32_e32 v144, v144, v216
	v_sub_f32_e32 v145, v145, v216
	v_mul_f32_e32 v213, v213, v217
	v_mul_f32_e32 v214, v214, v217
	v_mul_f32_e32 v2, v2, v217
	v_mul_f32_e32 v3, v3, v217
	v_mul_f32_e32 v4, v4, v217
	v_mul_f32_e32 v5, v5, v217
	v_mul_f32_e32 v6, v6, v217
	v_mul_f32_e32 v7, v7, v217
	v_mul_f32_e32 v8, v8, v217
	v_mul_f32_e32 v9, v9, v217
	v_mul_f32_e32 v10, v10, v217
	v_mul_f32_e32 v11, v11, v217
	v_mul_f32_e32 v12, v12, v217
	v_mul_f32_e32 v13, v13, v217
	v_mul_f32_e32 v14, v14, v217
	v_mul_f32_e32 v15, v15, v217
	v_mul_f32_e32 v16, v16, v217
	v_mul_f32_e32 v17, v17, v217
	v_mul_f32_e32 v18, v18, v217
	v_mul_f32_e32 v19, v19, v217
	v_mul_f32_e32 v20, v20, v217
	v_mul_f32_e32 v21, v21, v217
	v_mul_f32_e32 v22, v22, v217
	v_mul_f32_e32 v23, v23, v217
	v_mul_f32_e32 v24, v24, v217
	v_mul_f32_e32 v25, v25, v217
	v_mul_f32_e32 v26, v26, v217
	v_mul_f32_e32 v27, v27, v217
	v_mul_f32_e32 v28, v28, v217
	v_mul_f32_e32 v29, v29, v217
	v_mul_f32_e32 v30, v30, v217
	v_mul_f32_e32 v31, v31, v217
	v_mul_f32_e32 v32, v32, v217
	v_mul_f32_e32 v33, v33, v217
.Lna_nr_c1:
	s_waitcnt lgkmcnt(0)
	s_barrier
	ds_read_b128 v[146:149], v199 offset:9216
	ds_read_b128 v[150:153], v200 offset:9216
	ds_read_b128 v[154:157], v199 offset:9248
	ds_read_b128 v[158:161], v200 offset:9248
	v_exp_f32_e32 v34, v34
	v_exp_f32_e32 v35, v35
	v_exp_f32_e32 v36, v36
	v_exp_f32_e32 v37, v37
	s_waitcnt lgkmcnt(3)
	v_mfma_f32_32x32x16_bf16 v[66:81], v[146:149], v[98:101], v[114:129]
	ds_read_b128 v[146:149], v199 offset:9280
	v_add_f32_e32 v213, v213, v34
	v_add_f32_e32 v214, v214, v35
	v_add_f32_e32 v213, v213, v36
	v_add_f32_e32 v214, v214, v37
	v_exp_f32_e32 v38, v38
	v_exp_f32_e32 v39, v39
	s_waitcnt lgkmcnt(3)
	v_mfma_f32_32x32x16_bf16 v[82:97], v[150:153], v[98:101], v[130:145]
	ds_read_b128 v[150:153], v200 offset:9280
	v_exp_f32_e32 v40, v40
	v_exp_f32_e32 v41, v41
	v_add_f32_e32 v213, v213, v38
	v_add_f32_e32 v214, v214, v39
	v_add_f32_e32 v213, v213, v40
	v_add_f32_e32 v214, v214, v41
	s_waitcnt lgkmcnt(3)
	v_mfma_f32_32x32x16_bf16 v[66:81], v[154:157], v[102:105], v[66:81]
	ds_read_b128 v[154:157], v199 offset:9312
	v_cvt_pk_bf16_f32 v34, v34, v35
	v_cvt_pk_bf16_f32 v35, v36, v37
	v_cvt_pk_bf16_f32 v36, v38, v39
	v_cvt_pk_bf16_f32 v37, v40, v41
	v_exp_f32_e32 v42, v42
	v_exp_f32_e32 v43, v43
	s_waitcnt lgkmcnt(3)
	v_mfma_f32_32x32x16_bf16 v[82:97], v[158:161], v[102:105], v[82:97]
	ds_read_b128 v[158:161], v200 offset:9312
	v_exp_f32_e32 v44, v44
	v_exp_f32_e32 v45, v45
	v_add_f32_e32 v213, v213, v42
	v_add_f32_e32 v214, v214, v43
	v_add_f32_e32 v213, v213, v44
	v_add_f32_e32 v214, v214, v45
	s_waitcnt lgkmcnt(3)
	v_mfma_f32_32x32x16_bf16 v[66:81], v[146:149], v[106:109], v[66:81]
	ds_read_b64 v[162:163], v201 offset:0
	ds_read_b64 v[164:165], v201 offset:16
	v_exp_f32_e32 v46, v46
	v_exp_f32_e32 v47, v47
	v_exp_f32_e32 v48, v48
	v_exp_f32_e32 v49, v49
	s_waitcnt lgkmcnt(4)
	v_mfma_f32_32x32x16_bf16 v[82:97], v[150:153], v[106:109], v[82:97]
	ds_read_b64 v[166:167], v201 offset:4352
	ds_read_b64 v[168:169], v201 offset:4368
	v_add_f32_e32 v213, v213, v46
	v_add_f32_e32 v214, v214, v47
	v_add_f32_e32 v213, v213, v48
	v_add_f32_e32 v214, v214, v49
	v_cvt_pk_bf16_f32 v42, v42, v43
	v_cvt_pk_bf16_f32 v43, v44, v45
	v_cvt_pk_bf16_f32 v44, v46, v47
	v_cvt_pk_bf16_f32 v45, v48, v49
	s_waitcnt lgkmcnt(5)
	v_mfma_f32_32x32x16_bf16 v[66:81], v[154:157], v[110:113], v[66:81]
	ds_read_b64 v[170:171], v201 offset:32
	ds_read_b64 v[172:173], v201 offset:48
	v_exp_f32_e32 v50, v50
	v_exp_f32_e32 v51, v51
	v_exp_f32_e32 v52, v52
	v_exp_f32_e32 v53, v53
	s_waitcnt lgkmcnt(6)
	v_mfma_f32_32x32x16_bf16 v[82:97], v[158:161], v[110:113], v[82:97]
	ds_read_b64 v[174:175], v201 offset:4384
	ds_read_b64 v[176:177], v201 offset:4400
	v_add_f32_e32 v213, v213, v50
	v_add_f32_e32 v214, v214, v51
	v_add_f32_e32 v213, v213, v52
	v_add_f32_e32 v214, v214, v53
	v_exp_f32_e32 v54, v54
	v_exp_f32_e32 v55, v55
	s_waitcnt lgkmcnt(6)
	v_mfma_f32_32x32x16_bf16 v[2:17], v[162:165], v[34:37], v[2:17]
	ds_read_b64 v[162:163], v202 offset:0
	ds_read_b64 v[164:165], v203 offset:0
	v_exp_f32_e32 v56, v56
	v_exp_f32_e32 v57, v57
	v_add_f32_e32 v213, v213, v54
	v_add_f32_e32 v214, v214, v55
	v_add_f32_e32 v213, v213, v56
	s_waitcnt lgkmcnt(6)
	v_mfma_f32_32x32x16_bf16 v[18:33], v[166:169], v[34:37], v[18:33]
	ds_read_b64 v[166:167], v202 offset:4352
	ds_read_b64 v[168:169], v203 offset:4352
	v_add_f32_e32 v214, v214, v57
	v_cvt_pk_bf16_f32 v50, v50, v51
	v_cvt_pk_bf16_f32 v51, v52, v53
	v_cvt_pk_bf16_f32 v52, v54, v55
	v_cvt_pk_bf16_f32 v53, v56, v57
	v_exp_f32_e32 v58, v58
	v_exp_f32_e32 v59, v59
	s_waitcnt lgkmcnt(6)
	v_mfma_f32_32x32x16_bf16 v[2:17], v[170:173], v[42:45], v[2:17]
	ds_read_b64 v[170:171], v203 offset:16
	ds_read_b64 v[172:173], v203 offset:32
	v_exp_f32_e32 v60, v60
	v_exp_f32_e32 v61, v61
	v_add_f32_e32 v213, v213, v58
	v_add_f32_e32 v214, v214, v59
	v_add_f32_e32 v213, v213, v60
	s_waitcnt lgkmcnt(6)
	v_mfma_f32_32x32x16_bf16 v[18:33], v[174:177], v[42:45], v[18:33]
	ds_read_b64 v[174:175], v203 offset:4368
	ds_read_b64 v[176:177], v203 offset:4384
	s_waitcnt vmcnt(0)
	ds_write_b64 v205, v[192:193] offset:8704
	ds_write_b64 v205, v[194:195] offset:8712
	v_add_f32_e32 v214, v214, v61
	v_exp_f32_e32 v62, v62
	v_exp_f32_e32 v63, v63
	v_exp_f32_e32 v64, v64
	v_exp_f32_e32 v65, v65
	s_waitcnt lgkmcnt(8)
	v_mfma_f32_32x32x16_bf16 v[2:17], v[162:165], v[50:53], v[2:17]
	v_add_f32_e32 v213, v213, v62
	v_add_f32_e32 v214, v214, v63
	v_add_f32_e32 v213, v213, v64
	v_add_f32_e32 v214, v214, v65
	v_cvt_pk_bf16_f32 v58, v58, v59
	v_cvt_pk_bf16_f32 v59, v60, v61
	v_cvt_pk_bf16_f32 v60, v62, v63
	s_waitcnt lgkmcnt(6)
	v_mfma_f32_32x32x16_bf16 v[18:33], v[166:169], v[50:53], v[18:33]
	v_cvt_pk_bf16_f32 v61, v64, v65
	v_max3_f32 v216, v66, v67, v68
	v_max3_f32 v217, v82, v83, v84
	v_max3_f32 v216, v216, v69, v70
	v_max3_f32 v217, v217, v85, v86
	v_max3_f32 v216, v216, v71, v72
	v_max3_f32 v217, v217, v87, v88
	v_max3_f32 v216, v216, v73, v74
	s_waitcnt lgkmcnt(4)
	v_mfma_f32_32x32x16_bf16 v[2:17], v[170:173], v[58:61], v[2:17]
	v_max3_f32 v217, v217, v89, v90
	v_max3_f32 v216, v216, v75, v76
	v_max3_f32 v217, v217, v91, v92
	v_max3_f32 v216, v216, v77, v78
	v_max3_f32 v217, v217, v93, v94
	v_max3_f32 v216, v216, v79, v80
	v_max3_f32 v217, v217, v95, v96
	v_max_f32_e32 v216, v216, v81
	s_waitcnt lgkmcnt(2)
	v_mfma_f32_32x32x16_bf16 v[18:33], v[174:177], v[58:61], v[18:33]
	v_max_f32_e32 v217, v217, v97
	v_max_f32_e32 v216, v216, v217
	v_mov_b32_e32 v217, v216
	s_nop 1
	v_permlane32_swap_b32_e32 v216, v217
	v_max_f32_e32 v215, v216, v217
	v_cmp_lt_f32_e32 vcc, 4.0, v215
	s_cbranch_vccz .Lna_nr_c2
	s_nop 15
	v_max_f32_e32 v216, v215, v220
	v_exp_f32_e64 v217, -v216
	v_add_f32_e32 v212, v212, v216
	v_and_b32_e32 v217, v217, v221
	v_sub_f32_e32 v66, v66, v216
	v_sub_f32_e32 v67, v67, v216
	v_sub_f32_e32 v68, v68, v216
	v_sub_f32_e32 v69, v69, v216
	v_sub_f32_e32 v70, v70, v216
	v_sub_f32_e32 v71, v71, v216
	v_sub_f32_e32 v72, v72, v216
	v_sub_f32_e32 v73, v73, v216
	v_sub_f32_e32 v74, v74, v216
	v_sub_f32_e32 v75, v75, v216
	v_sub_f32_e32 v76, v76, v216
	v_sub_f32_e32 v77, v77, v216
	v_sub_f32_e32 v78, v78, v216
	v_sub_f32_e32 v79, v79, v216
	v_sub_f32_e32 v80, v80, v216
	v_sub_f32_e32 v81, v81, v216
	v_sub_f32_e32 v82, v82, v216
	v_sub_f32_e32 v83, v83, v216
	v_sub_f32_e32 v84, v84, v216
	v_sub_f32_e32 v85, v85, v216
	v_sub_f32_e32 v86, v86, v216
	v_sub_f32_e32 v87, v87, v216
	v_sub_f32_e32 v88, v88, v216
	v_sub_f32_e32 v89, v89, v216
	v_sub_f32_e32 v90, v90, v216
	v_sub_f32_e32 v91, v91, v216
	v_sub_f32_e32 v92, v92, v216
	v_sub_f32_e32 v93, v93, v216
	v_sub_f32_e32 v94, v94, v216
	v_sub_f32_e32 v95, v95, v216
	v_sub_f32_e32 v96, v96, v216
	v_sub_f32_e32 v97, v97, v216
	v_sub_f32_e32 v114, v114, v216
	v_sub_f32_e32 v115, v115, v216
	v_sub_f32_e32 v116, v116, v216
	v_sub_f32_e32 v117, v117, v216
	v_sub_f32_e32 v118, v118, v216
	v_sub_f32_e32 v119, v119, v216
	v_sub_f32_e32 v120, v120, v216
	v_sub_f32_e32 v121, v121, v216
	v_sub_f32_e32 v122, v122, v216
	v_sub_f32_e32 v123, v123, v216
	v_sub_f32_e32 v124, v124, v216
	v_sub_f32_e32 v125, v125, v216
	v_sub_f32_e32 v126, v126, v216
	v_sub_f32_e32 v127, v127, v216
	v_sub_f32_e32 v128, v128, v216
	v_sub_f32_e32 v129, v129, v216
	v_sub_f32_e32 v130, v130, v216
	v_sub_f32_e32 v131, v131, v216
	v_sub_f32_e32 v132, v132, v216
	v_sub_f32_e32 v133, v133, v216
	v_sub_f32_e32 v134, v134, v216
	v_sub_f32_e32 v135, v135, v216
	v_sub_f32_e32 v136, v136, v216
	v_sub_f32_e32 v137, v137, v216
	v_sub_f32_e32 v138, v138, v216
	v_sub_f32_e32 v139, v139, v216
	v_sub_f32_e32 v140, v140, v216
	v_sub_f32_e32 v141, v141, v216
	v_sub_f32_e32 v142, v142, v216
	v_sub_f32_e32 v143, v143, v216
	v_sub_f32_e32 v144, v144, v216
	v_sub_f32_e32 v145, v145, v216
	v_mul_f32_e32 v213, v213, v217
	v_mul_f32_e32 v214, v214, v217
	v_mul_f32_e32 v2, v2, v217
	v_mul_f32_e32 v3, v3, v217
	v_mul_f32_e32 v4, v4, v217
	v_mul_f32_e32 v5, v5, v217
	v_mul_f32_e32 v6, v6, v217
	v_mul_f32_e32 v7, v7, v217
	v_mul_f32_e32 v8, v8, v217
	v_mul_f32_e32 v9, v9, v217
	v_mul_f32_e32 v10, v10, v217
	v_mul_f32_e32 v11, v11, v217
	v_mul_f32_e32 v12, v12, v217
	v_mul_f32_e32 v13, v13, v217
	v_mul_f32_e32 v14, v14, v217
	v_mul_f32_e32 v15, v15, v217
	v_mul_f32_e32 v16, v16, v217
	v_mul_f32_e32 v17, v17, v217
	v_mul_f32_e32 v18, v18, v217
	v_mul_f32_e32 v19, v19, v217
	v_mul_f32_e32 v20, v20, v217
	v_mul_f32_e32 v21, v21, v217
	v_mul_f32_e32 v22, v22, v217
	v_mul_f32_e32 v23, v23, v217
	v_mul_f32_e32 v24, v24, v217
	v_mul_f32_e32 v25, v25, v217
	v_mul_f32_e32 v26, v26, v217
	v_mul_f32_e32 v27, v27, v217
	v_mul_f32_e32 v28, v28, v217
	v_mul_f32_e32 v29, v29, v217
	v_mul_f32_e32 v30, v30, v217
	v_mul_f32_e32 v31, v31, v217
	v_mul_f32_e32 v32, v32, v217
	v_mul_f32_e32 v33, v33, v217
.Lna_nr_c2:
	s_waitcnt lgkmcnt(0)
	s_barrier
	global_load_dwordx2 v[146:147], v218, s[30:31] offset:0
	global_load_dwordx2 v[148:149], v218, s[30:31] offset:16
	global_load_dwordx2 v[150:151], v218, s[30:31] offset:32
	global_load_dwordx2 v[152:153], v218, s[30:31] offset:48
	global_load_dwordx2 v[154:155], v218, s[30:31] offset:64
	global_load_dwordx2 v[156:157], v218, s[30:31] offset:80
	global_load_dwordx2 v[158:159], v218, s[30:31] offset:96
	global_load_dwordx2 v[160:161], v218, s[30:31] offset:112
	v_exp_f32_e32 v66, v66
	v_exp_f32_e32 v67, v67
	v_exp_f32_e32 v68, v68
	v_exp_f32_e32 v69, v69
	v_add_f32_e32 v213, v213, v66
	v_add_f32_e32 v214, v214, v67
	v_add_f32_e32 v213, v213, v68
	v_add_f32_e32 v214, v214, v69
	v_exp_f32_e32 v70, v70
	ds_read_b64 v[162:163], v201 offset:8704
	ds_read_b64 v[164:165], v201 offset:8720
	ds_read_b64 v[166:167], v201 offset:13056
	ds_read_b64 v[168:169], v201 offset:13072
	ds_read_b64 v[170:171], v201 offset:8736
	ds_read_b64 v[172:173], v201 offset:8752
	ds_read_b64 v[174:175], v201 offset:13088
	ds_read_b64 v[176:177], v201 offset:13104
	v_exp_f32_e32 v71, v71
	v_exp_f32_e32 v72, v72
	v_exp_f32_e32 v73, v73
	v_add_f32_e32 v213, v213, v70
	v_add_f32_e32 v214, v214, v71
	v_add_f32_e32 v213, v213, v72
	v_add_f32_e32 v214, v214, v73
	v_cvt_pk_bf16_f32 v66, v66, v67
	v_cvt_pk_bf16_f32 v67, v68, v69
	v_cvt_pk_bf16_f32 v68, v70, v71
	v_cvt_pk_bf16_f32 v69, v72, v73
	s_waitcnt lgkmcnt(6)
	s_nop 0
	v_mfma_f32_32x32x16_bf16 v[2:17], v[162:165], v[66:69], v[2:17]
	ds_read_b64 v[162:163], v202 offset:8704
	ds_read_b64 v[164:165], v203 offset:8704
	s_waitcnt lgkmcnt(6)
	v_mfma_f32_32x32x16_bf16 v[18:33], v[166:169], v[66:69], v[18:33]
	ds_read_b64 v[166:167], v202 offset:13056
	ds_read_b64 v[168:169], v203 offset:13056
	v_exp_f32_e32 v74, v74
	v_exp_f32_e32 v75, v75
	v_exp_f32_e32 v76, v76
	v_exp_f32_e32 v77, v77
	v_add_f32_e32 v213, v213, v74
	v_add_f32_e32 v214, v214, v75
	v_add_f32_e32 v213, v213, v76
	v_add_f32_e32 v214, v214, v77
	v_exp_f32_e32 v78, v78
	v_exp_f32_e32 v79, v79
	v_exp_f32_e32 v80, v80
	v_exp_f32_e32 v81, v81
	v_add_f32_e32 v213, v213, v78
	v_add_f32_e32 v214, v214, v79
	v_add_f32_e32 v213, v213, v80
	v_add_f32_e32 v214, v214, v81
	v_cvt_pk_bf16_f32 v74, v74, v75
	v_cvt_pk_bf16_f32 v75, v76, v77
	v_cvt_pk_bf16_f32 v76, v78, v79
	v_cvt_pk_bf16_f32 v77, v80, v81
	s_waitcnt lgkmcnt(6)
	s_nop 0
	v_mfma_f32_32x32x16_bf16 v[2:17], v[170:173], v[74:77], v[2:17]
	ds_read_b64 v[170:171], v203 offset:8720
	ds_read_b64 v[172:173], v203 offset:8736
	s_waitcnt lgkmcnt(6)
	v_mfma_f32_32x32x16_bf16 v[18:33], v[174:177], v[74:77], v[18:33]
	ds_read_b64 v[174:175], v203 offset:13072
	ds_read_b64 v[176:177], v203 offset:13088
	v_exp_f32_e32 v82, v82
	v_exp_f32_e32 v83, v83
	v_exp_f32_e32 v84, v84
	v_exp_f32_e32 v85, v85
	v_add_f32_e32 v213, v213, v82
	v_add_f32_e32 v214, v214, v83
	v_add_f32_e32 v213, v213, v84
	v_add_f32_e32 v214, v214, v85
	v_exp_f32_e32 v86, v86
	v_exp_f32_e32 v87, v87
	v_exp_f32_e32 v88, v88
	v_exp_f32_e32 v89, v89
	v_add_f32_e32 v213, v213, v86
	v_add_f32_e32 v214, v214, v87
	v_add_f32_e32 v213, v213, v88
	v_add_f32_e32 v214, v214, v89
	v_cvt_pk_bf16_f32 v82, v82, v83
	v_cvt_pk_bf16_f32 v83, v84, v85
	v_cvt_pk_bf16_f32 v84, v86, v87
	v_cvt_pk_bf16_f32 v85, v88, v89
	s_waitcnt lgkmcnt(6)
	s_nop 0
	v_mfma_f32_32x32x16_bf16 v[2:17], v[162:165], v[82:85], v[2:17]
	s_waitcnt lgkmcnt(4)
	v_mfma_f32_32x32x16_bf16 v[18:33], v[166:169], v[82:85], v[18:33]
	v_exp_f32_e32 v90, v90
	v_exp_f32_e32 v91, v91
	v_exp_f32_e32 v92, v92
	v_exp_f32_e32 v93, v93
	v_add_f32_e32 v213, v213, v90
	v_add_f32_e32 v214, v214, v91
	v_add_f32_e32 v213, v213, v92
	v_add_f32_e32 v214, v214, v93
	v_exp_f32_e32 v94, v94
	v_exp_f32_e32 v95, v95
	v_exp_f32_e32 v96, v96
	v_exp_f32_e32 v97, v97
	v_add_f32_e32 v213, v213, v94
	v_add_f32_e32 v214, v214, v95
	v_add_f32_e32 v213, v213, v96
	v_add_f32_e32 v214, v214, v97
	v_cvt_pk_bf16_f32 v90, v90, v91
	v_cvt_pk_bf16_f32 v91, v92, v93
	v_cvt_pk_bf16_f32 v92, v94, v95
	v_cvt_pk_bf16_f32 v93, v96, v97
	s_waitcnt lgkmcnt(2)
	s_nop 0
	v_mfma_f32_32x32x16_bf16 v[2:17], v[170:173], v[90:93], v[2:17]
	s_waitcnt lgkmcnt(0)
	v_mfma_f32_32x32x16_bf16 v[18:33], v[174:177], v[90:93], v[18:33]
	s_waitcnt lgkmcnt(0)
	s_barrier
	v_add_f32_e32 v213, v213, v214
	v_mov_b32_e32 v217, v213
	s_nop 1
	v_permlane32_swap_b32_e32 v213, v217
	v_add_f32_e32 v216, v213, v217
	v_div_scale_f32 v217, s[36:37], v216, v216, 1.0
	v_rcp_f32_e32 v223, v217
	v_div_scale_f32 v224, vcc, 1.0, v216, 1.0
	v_fma_f32 v225, -v217, v223, 1.0
	v_fmac_f32_e32 v223, v225, v223
	v_mul_f32_e32 v225, v224, v223
	v_fma_f32 v226, -v217, v225, v224
	v_fmac_f32_e32 v225, v226, v223
	v_fma_f32 v217, -v217, v225, v224
	v_div_fmas_f32 v217, v217, v223, v225
	v_div_fixup_f32 v216, v217, v216, 1.0
	s_nop 15
	v_mul_f32_e32 v2, v2, v216
	v_mul_f32_e32 v3, v3, v216
	v_mul_f32_e32 v4, v4, v216
	v_mul_f32_e32 v5, v5, v216
	v_mul_f32_e32 v6, v6, v216
	v_mul_f32_e32 v7, v7, v216
	v_mul_f32_e32 v8, v8, v216
	v_mul_f32_e32 v9, v9, v216
	v_mul_f32_e32 v10, v10, v216
	v_mul_f32_e32 v11, v11, v216
	v_mul_f32_e32 v12, v12, v216
	v_mul_f32_e32 v13, v13, v216
	v_mul_f32_e32 v14, v14, v216
	v_mul_f32_e32 v15, v15, v216
	v_mul_f32_e32 v16, v16, v216
	v_mul_f32_e32 v17, v17, v216
	v_mul_f32_e32 v18, v18, v216
	v_mul_f32_e32 v19, v19, v216
	v_mul_f32_e32 v20, v20, v216
	v_mul_f32_e32 v21, v21, v216
	v_mul_f32_e32 v22, v22, v216
	v_mul_f32_e32 v23, v23, v216
	v_mul_f32_e32 v24, v24, v216
	v_mul_f32_e32 v25, v25, v216
	v_mul_f32_e32 v26, v26, v216
	v_mul_f32_e32 v27, v27, v216
	v_mul_f32_e32 v28, v28, v216
	v_mul_f32_e32 v29, v29, v216
	v_mul_f32_e32 v30, v30, v216
	v_mul_f32_e32 v31, v31, v216
	v_mul_f32_e32 v32, v32, v216
	v_mul_f32_e32 v33, v33, v216
	s_waitcnt vmcnt(0)
	v_lshlrev_b32_e32 v223, 16, v146
	v_and_b32_e32 v224, 0xffff0000, v146
	v_lshlrev_b32_e32 v225, 16, v147
	v_and_b32_e32 v226, 0xffff0000, v147
	v_mul_f32_e32 v2, v2, v223
	v_mul_f32_e32 v3, v3, v224
	v_mul_f32_e32 v4, v4, v225
	v_mul_f32_e32 v5, v5, v226
	v_cvt_pk_bf16_f32 v146, v2, v3
	v_cvt_pk_bf16_f32 v147, v4, v5
	global_store_dwordx2 v218, v[146:147], s[30:31] offset:0
	v_lshlrev_b32_e32 v223, 16, v148
	v_and_b32_e32 v224, 0xffff0000, v148
	v_lshlrev_b32_e32 v225, 16, v149
	v_and_b32_e32 v226, 0xffff0000, v149
	v_mul_f32_e32 v6, v6, v223
	v_mul_f32_e32 v7, v7, v224
	v_mul_f32_e32 v8, v8, v225
	v_mul_f32_e32 v9, v9, v226
	v_cvt_pk_bf16_f32 v148, v6, v7
	v_cvt_pk_bf16_f32 v149, v8, v9
	global_store_dwordx2 v218, v[148:149], s[30:31] offset:16
	v_lshlrev_b32_e32 v223, 16, v150
	v_and_b32_e32 v224, 0xffff0000, v150
	v_lshlrev_b32_e32 v225, 16, v151
	v_and_b32_e32 v226, 0xffff0000, v151
	v_mul_f32_e32 v10, v10, v223
	v_mul_f32_e32 v11, v11, v224
	v_mul_f32_e32 v12, v12, v225
	v_mul_f32_e32 v13, v13, v226
	v_cvt_pk_bf16_f32 v150, v10, v11
	v_cvt_pk_bf16_f32 v151, v12, v13
	global_store_dwordx2 v218, v[150:151], s[30:31] offset:32
	v_lshlrev_b32_e32 v223, 16, v152
	v_and_b32_e32 v224, 0xffff0000, v152
	v_lshlrev_b32_e32 v225, 16, v153
	v_and_b32_e32 v226, 0xffff0000, v153
	v_mul_f32_e32 v14, v14, v223
	v_mul_f32_e32 v15, v15, v224
	v_mul_f32_e32 v16, v16, v225
	v_mul_f32_e32 v17, v17, v226
	v_cvt_pk_bf16_f32 v152, v14, v15
	v_cvt_pk_bf16_f32 v153, v16, v17
	global_store_dwordx2 v218, v[152:153], s[30:31] offset:48
	v_lshlrev_b32_e32 v223, 16, v154
	v_and_b32_e32 v224, 0xffff0000, v154
	v_lshlrev_b32_e32 v225, 16, v155
	v_and_b32_e32 v226, 0xffff0000, v155
	v_mul_f32_e32 v18, v18, v223
	v_mul_f32_e32 v19, v19, v224
	v_mul_f32_e32 v20, v20, v225
	v_mul_f32_e32 v21, v21, v226
	v_cvt_pk_bf16_f32 v154, v18, v19
	v_cvt_pk_bf16_f32 v155, v20, v21
	global_store_dwordx2 v218, v[154:155], s[30:31] offset:64
	v_lshlrev_b32_e32 v223, 16, v156
	v_and_b32_e32 v224, 0xffff0000, v156
	v_lshlrev_b32_e32 v225, 16, v157
	v_and_b32_e32 v226, 0xffff0000, v157
	v_mul_f32_e32 v22, v22, v223
	v_mul_f32_e32 v23, v23, v224
	v_mul_f32_e32 v24, v24, v225
	v_mul_f32_e32 v25, v25, v226
	v_cvt_pk_bf16_f32 v156, v22, v23
	v_cvt_pk_bf16_f32 v157, v24, v25
	global_store_dwordx2 v218, v[156:157], s[30:31] offset:80
	v_lshlrev_b32_e32 v223, 16, v158
	v_and_b32_e32 v224, 0xffff0000, v158
	v_lshlrev_b32_e32 v225, 16, v159
	v_and_b32_e32 v226, 0xffff0000, v159
	v_mul_f32_e32 v26, v26, v223
	v_mul_f32_e32 v27, v27, v224
	v_mul_f32_e32 v28, v28, v225
	v_mul_f32_e32 v29, v29, v226
	v_cvt_pk_bf16_f32 v158, v26, v27
	v_cvt_pk_bf16_f32 v159, v28, v29
	global_store_dwordx2 v218, v[158:159], s[30:31] offset:96
	v_lshlrev_b32_e32 v223, 16, v160
	v_and_b32_e32 v224, 0xffff0000, v160
	v_lshlrev_b32_e32 v225, 16, v161
	v_and_b32_e32 v226, 0xffff0000, v161
	v_mul_f32_e32 v30, v30, v223
	v_mul_f32_e32 v31, v31, v224
	v_mul_f32_e32 v32, v32, v225
	v_mul_f32_e32 v33, v33, v226
	v_cvt_pk_bf16_f32 v160, v30, v31
	v_cvt_pk_bf16_f32 v161, v32, v33
	global_store_dwordx2 v218, v[160:161], s[30:31] offset:112
	s_add_i32 s10, s10, s9
	s_cmpk_lt_i32 s10, 0x200
	s_cbranch_scc1 .Lna_unit
	s_mov_b32 s88, s9

.Lmla_loop:
	v_exp_f32_e32 v34, v34
	v_exp_f32_e32 v35, v35
	v_exp_f32_e32 v36, v36
	v_exp_f32_e32 v37, v37
	s_waitcnt lgkmcnt(5)
	v_mfma_f32_32x32x16_bf16 v[66:81], v[138:141], v[98:101], v[122:137]
	ds_read_b128 v[138:141], v220 offset:13408
	v_add_f32_e32 v231, v231, v34
	v_add_f32_e32 v232, v232, v35
	v_exp_f32_e32 v38, v38
	v_exp_f32_e32 v39, v39
	s_waitcnt lgkmcnt(5)
	v_mfma_f32_32x32x16_bf16 v[82:97], v[142:145], v[98:101], v[122:137]
	ds_read_b128 v[142:145], v220 offset:20064
	v_add_f32_e32 v231, v231, v36
	v_add_f32_e32 v232, v232, v37
	v_exp_f32_e32 v40, v40
	v_exp_f32_e32 v41, v41
	s_waitcnt lgkmcnt(5)
	v_mfma_f32_32x32x16_bf16 v[66:81], v[146:149], v[102:105], v[66:81]
	ds_read_b128 v[146:149], v220 offset:13440
	global_load_dwordx4 v[200:203], v226, s[4:5]
	global_load_dwordx4 v[204:207], v227, s[4:5]
	global_load_dwordx4 v[208:211], v228, s[4:5]
	s_add_u32 s4, s4, 0x6000
	s_addc_u32 s5, s5, 0
	global_load_dwordx4 v[212:215], v229, s[10:11]
	s_add_u32 s10, s10, 0x80
	s_addc_u32 s11, s11, 0
	v_add_f32_e32 v231, v231, v38
	v_add_f32_e32 v232, v232, v39
	v_add_f32_e32 v231, v231, v40
	v_add_f32_e32 v232, v232, v41
	v_cvt_pk_bf16_f32 v34, v34, v35
	v_cvt_pk_bf16_f32 v35, v36, v37
	s_waitcnt lgkmcnt(5)
	v_mfma_f32_32x32x16_bf16 v[82:97], v[150:153], v[102:105], v[82:97]
	ds_read_b128 v[150:153], v220 offset:20096
	v_cvt_pk_bf16_f32 v36, v38, v39
	v_cvt_pk_bf16_f32 v37, v40, v41
	v_exp_f32_e32 v42, v42
	v_exp_f32_e32 v43, v43
	s_waitcnt lgkmcnt(5)
	v_mfma_f32_32x32x16_bf16 v[66:81], v[154:157], v[106:109], v[66:81]
	ds_read_b128 v[154:157], v220 offset:13472
	v_exp_f32_e32 v44, v44
	v_exp_f32_e32 v45, v45
	v_add_f32_e32 v231, v231, v42
	v_add_f32_e32 v232, v232, v43
	s_waitcnt lgkmcnt(5)
	v_mfma_f32_32x32x16_bf16 v[82:97], v[158:161], v[106:109], v[82:97]
	ds_read_b128 v[158:161], v220 offset:20128
	v_exp_f32_e32 v46, v46
	v_exp_f32_e32 v47, v47
	v_add_f32_e32 v231, v231, v44
	v_add_f32_e32 v232, v232, v45
	v_exp_f32_e32 v48, v48
	s_waitcnt lgkmcnt(5)
	v_mfma_f32_32x32x16_bf16 v[66:81], v[138:141], v[110:113], v[66:81]
	ds_read_b64 v[162:163], v221 offset:0
	ds_read_b64 v[164:165], v221 offset:16
	v_exp_f32_e32 v49, v49
	v_add_f32_e32 v231, v231, v46
	v_add_f32_e32 v232, v232, v47
	v_add_f32_e32 v231, v231, v48
	s_waitcnt lgkmcnt(6)
	v_mfma_f32_32x32x16_bf16 v[82:97], v[142:145], v[110:113], v[82:97]
	ds_read_b64 v[166:167], v221 offset:4352
	ds_read_b64 v[168:169], v221 offset:4368
	v_add_f32_e32 v232, v232, v49
	v_cvt_pk_bf16_f32 v42, v42, v43
	v_cvt_pk_bf16_f32 v43, v44, v45
	v_cvt_pk_bf16_f32 v44, v46, v47
	v_cvt_pk_bf16_f32 v45, v48, v49
	v_exp_f32_e32 v50, v50
	s_waitcnt lgkmcnt(7)
	v_mfma_f32_32x32x16_bf16 v[66:81], v[146:149], v[114:117], v[66:81]
	ds_read_b64 v[170:171], v221 offset:32
	ds_read_b64 v[172:173], v221 offset:48
	v_exp_f32_e32 v51, v51
	v_exp_f32_e32 v52, v52
	v_exp_f32_e32 v53, v53
	s_waitcnt lgkmcnt(8)
	v_mfma_f32_32x32x16_bf16 v[82:97], v[150:153], v[114:117], v[82:97]
	ds_read_b64 v[174:175], v221 offset:4384
	ds_read_b64 v[176:177], v221 offset:4400
	v_add_f32_e32 v231, v231, v50
	v_add_f32_e32 v232, v232, v51
	v_exp_f32_e32 v54, v54
	v_exp_f32_e32 v55, v55
	s_waitcnt lgkmcnt(9)
	v_mfma_f32_32x32x16_bf16 v[66:81], v[154:157], v[118:121], v[66:81]
	ds_read_b64 v[180:181], v221 offset:64
	ds_read_b64 v[182:183], v221 offset:80
	v_add_f32_e32 v231, v231, v52
	v_add_f32_e32 v232, v232, v53
	v_exp_f32_e32 v56, v56
	v_exp_f32_e32 v57, v57
	s_waitcnt lgkmcnt(10)
	v_mfma_f32_32x32x16_bf16 v[82:97], v[158:161], v[118:121], v[82:97]
	ds_read_b64 v[184:185], v221 offset:4416
	ds_read_b64 v[186:187], v221 offset:4432
	v_add_f32_e32 v231, v231, v54
	v_add_f32_e32 v232, v232, v55
	v_add_f32_e32 v231, v231, v56
	v_add_f32_e32 v232, v232, v57
	v_cvt_pk_bf16_f32 v50, v50, v51
	v_cvt_pk_bf16_f32 v51, v52, v53
	v_cvt_pk_bf16_f32 v52, v54, v55
	s_waitcnt lgkmcnt(10)
	v_mfma_f32_32x32x16_bf16 v[2:17], v[162:165], v[34:37], v[2:17]
	ds_read_b64 v[188:189], v221 offset:96
	ds_read_b64 v[190:191], v221 offset:112
	v_cvt_pk_bf16_f32 v53, v56, v57
	v_exp_f32_e32 v58, v58
	v_exp_f32_e32 v59, v59
	v_exp_f32_e32 v60, v60
	s_waitcnt lgkmcnt(10)
	v_mfma_f32_32x32x16_bf16 v[18:33], v[166:169], v[34:37], v[18:33]
	ds_read_b64 v[192:193], v221 offset:4448
	ds_read_b64 v[194:195], v221 offset:4464
	v_exp_f32_e32 v61, v61
	v_add_f32_e32 v231, v231, v58
	v_add_f32_e32 v232, v232, v59
	v_exp_f32_e32 v62, v62
	s_waitcnt lgkmcnt(10)
	v_mfma_f32_32x32x16_bf16 v[2:17], v[170:173], v[42:45], v[2:17]
	v_exp_f32_e32 v63, v63
	v_add_f32_e32 v231, v231, v60
	v_add_f32_e32 v232, v232, v61
	v_exp_f32_e32 v64, v64
	s_waitcnt lgkmcnt(8)
	v_mfma_f32_32x32x16_bf16 v[18:33], v[174:177], v[42:45], v[18:33]
	s_waitcnt vmcnt(4)
	ds_write_b64 v225, v[216:217] offset:17408
	ds_write_b64 v225, v[218:219] offset:17416
	v_exp_f32_e32 v65, v65
	v_add_f32_e32 v231, v231, v62
	v_add_f32_e32 v232, v232, v63
	v_add_f32_e32 v231, v231, v64
	v_add_f32_e32 v232, v232, v65
	s_waitcnt lgkmcnt(8)
	v_mfma_f32_32x32x16_bf16 v[2:17], v[180:183], v[50:53], v[2:17]
	v_cvt_pk_bf16_f32 v58, v58, v59
	v_cvt_pk_bf16_f32 v59, v60, v61
	v_cvt_pk_bf16_f32 v60, v62, v63
	v_cvt_pk_bf16_f32 v61, v64, v65
	v_max3_f32 v234, v66, v67, v68
	v_max3_f32 v235, v82, v83, v84
	s_waitcnt lgkmcnt(6)
	v_mfma_f32_32x32x16_bf16 v[18:33], v[184:187], v[50:53], v[18:33]
	v_max3_f32 v234, v234, v69, v70
	v_max3_f32 v235, v235, v85, v86
	v_max3_f32 v234, v234, v71, v72
	v_max3_f32 v235, v235, v87, v88
	v_max3_f32 v234, v234, v73, v74
	v_max3_f32 v235, v235, v89, v90
	v_max3_f32 v234, v234, v75, v76
	s_waitcnt lgkmcnt(4)
	v_mfma_f32_32x32x16_bf16 v[2:17], v[188:191], v[58:61], v[2:17]
	v_max3_f32 v235, v235, v91, v92
	v_max3_f32 v234, v234, v77, v78
	v_max3_f32 v235, v235, v93, v94
	v_max3_f32 v234, v234, v79, v80
	v_max3_f32 v235, v235, v95, v96
	v_max3_f32 v234, v234, v81, v97
	s_waitcnt lgkmcnt(2)
	v_mfma_f32_32x32x16_bf16 v[18:33], v[192:195], v[58:61], v[18:33]
	v_max_f32_e32 v234, v234, v235
	v_mov_b32_e32 v235, v234
	s_nop 1
	v_permlane32_swap_b32_e32 v234, v235
	v_max_f32_e32 v233, v234, v235
	v_cmp_lt_f32_e32 vcc, 4.0, v233
	s_cbranch_vccz .Lmla_nr_p0
	s_nop 15
	v_max_f32_e32 v234, 0, v233
	v_exp_f32_e64 v235, -v234
	v_add_f32_e32 v230, v230, v234
	v_sub_f32_e32 v66, v66, v234
	v_sub_f32_e32 v67, v67, v234
	v_sub_f32_e32 v68, v68, v234
	v_sub_f32_e32 v69, v69, v234
	v_sub_f32_e32 v70, v70, v234
	v_sub_f32_e32 v71, v71, v234
	v_sub_f32_e32 v72, v72, v234
	v_sub_f32_e32 v73, v73, v234
	v_sub_f32_e32 v74, v74, v234
	v_sub_f32_e32 v75, v75, v234
	v_sub_f32_e32 v76, v76, v234
	v_sub_f32_e32 v77, v77, v234
	v_sub_f32_e32 v78, v78, v234
	v_sub_f32_e32 v79, v79, v234
	v_sub_f32_e32 v80, v80, v234
	v_sub_f32_e32 v81, v81, v234
	v_sub_f32_e32 v82, v82, v234
	v_sub_f32_e32 v83, v83, v234
	v_sub_f32_e32 v84, v84, v234
	v_sub_f32_e32 v85, v85, v234
	v_sub_f32_e32 v86, v86, v234
	v_sub_f32_e32 v87, v87, v234
	v_sub_f32_e32 v88, v88, v234
	v_sub_f32_e32 v89, v89, v234
	v_sub_f32_e32 v90, v90, v234
	v_sub_f32_e32 v91, v91, v234
	v_sub_f32_e32 v92, v92, v234
	v_sub_f32_e32 v93, v93, v234
	v_sub_f32_e32 v94, v94, v234
	v_sub_f32_e32 v95, v95, v234
	v_sub_f32_e32 v96, v96, v234
	v_sub_f32_e32 v97, v97, v234
	v_mul_f32_e32 v231, v231, v235
	v_mul_f32_e32 v232, v232, v235
	v_mul_f32_e32 v2, v2, v235
	v_mul_f32_e32 v3, v3, v235
	v_mul_f32_e32 v4, v4, v235
	v_mul_f32_e32 v5, v5, v235
	v_mul_f32_e32 v6, v6, v235
	v_mul_f32_e32 v7, v7, v235
	v_mul_f32_e32 v8, v8, v235
	v_mul_f32_e32 v9, v9, v235
	v_mul_f32_e32 v10, v10, v235
	v_mul_f32_e32 v11, v11, v235
	v_mul_f32_e32 v12, v12, v235
	v_mul_f32_e32 v13, v13, v235
	v_mul_f32_e32 v14, v14, v235
	v_mul_f32_e32 v15, v15, v235
	v_mul_f32_e32 v16, v16, v235
	v_mul_f32_e32 v17, v17, v235
	v_mul_f32_e32 v18, v18, v235
	v_mul_f32_e32 v19, v19, v235
	v_mul_f32_e32 v20, v20, v235
	v_mul_f32_e32 v21, v21, v235
	v_mul_f32_e32 v22, v22, v235
	v_mul_f32_e32 v23, v23, v235
	v_mul_f32_e32 v24, v24, v235
	v_mul_f32_e32 v25, v25, v235
	v_mul_f32_e32 v26, v26, v235
	v_mul_f32_e32 v27, v27, v235
	v_mul_f32_e32 v28, v28, v235
	v_mul_f32_e32 v29, v29, v235
	v_mul_f32_e32 v30, v30, v235
	v_mul_f32_e32 v31, v31, v235
	v_mul_f32_e32 v32, v32, v235
	v_mul_f32_e32 v33, v33, v235
	v_sub_f32_e32 v122, 0, v230
	v_mov_b32_e32 v123, v122
	v_mov_b32_e32 v124, v122
	v_mov_b32_e32 v125, v122
	v_mov_b32_e32 v126, v122
	v_mov_b32_e32 v127, v122
	v_mov_b32_e32 v128, v122
	v_mov_b32_e32 v129, v122
	v_mov_b32_e32 v130, v122
	v_mov_b32_e32 v131, v122
	v_mov_b32_e32 v132, v122
	v_mov_b32_e32 v133, v122
	v_mov_b32_e32 v134, v122
	v_mov_b32_e32 v135, v122
	v_mov_b32_e32 v136, v122
	v_mov_b32_e32 v137, v122
.Lmla_nr_p0:
	ds_read_b128 v[138:141], v220 offset:26624
	ds_read_b128 v[142:145], v220 offset:33280
	ds_read_b128 v[146:149], v220 offset:26656
	ds_read_b128 v[150:153], v220 offset:33312
	ds_read_b128 v[154:157], v220 offset:26688
	ds_read_b128 v[158:161], v220 offset:33344
	s_waitcnt lgkmcnt(6)
	s_barrier
	v_exp_f32_e32 v66, v66
	v_exp_f32_e32 v67, v67
	v_exp_f32_e32 v68, v68
	v_exp_f32_e32 v69, v69
	s_waitcnt lgkmcnt(5)
	v_mfma_f32_32x32x16_bf16 v[34:49], v[138:141], v[98:101], v[122:137]
	ds_read_b128 v[138:141], v220 offset:26720
	v_add_f32_e32 v231, v231, v66
	v_add_f32_e32 v232, v232, v67
	v_exp_f32_e32 v70, v70
	v_exp_f32_e32 v71, v71
	s_waitcnt lgkmcnt(5)
	v_mfma_f32_32x32x16_bf16 v[50:65], v[142:145], v[98:101], v[122:137]
	ds_read_b128 v[142:145], v220 offset:33376
	v_add_f32_e32 v231, v231, v68
	v_add_f32_e32 v232, v232, v69
	v_exp_f32_e32 v72, v72
	v_exp_f32_e32 v73, v73
	s_waitcnt lgkmcnt(5)
	v_mfma_f32_32x32x16_bf16 v[34:49], v[146:149], v[102:105], v[34:49]
	ds_read_b128 v[146:149], v220 offset:26752
	global_load_dwordx4 v[216:219], v229, s[10:11]
	s_add_u32 s10, s10, 0x80
	s_addc_u32 s11, s11, 0
	v_add_f32_e32 v231, v231, v70
	v_add_f32_e32 v232, v232, v71
	v_add_f32_e32 v231, v231, v72
	v_add_f32_e32 v232, v232, v73
	v_cvt_pk_bf16_f32 v66, v66, v67
	v_cvt_pk_bf16_f32 v67, v68, v69
	s_waitcnt lgkmcnt(5)
	v_mfma_f32_32x32x16_bf16 v[50:65], v[150:153], v[102:105], v[50:65]
	ds_read_b128 v[150:153], v220 offset:33408
	v_cvt_pk_bf16_f32 v68, v70, v71
	v_cvt_pk_bf16_f32 v69, v72, v73
	v_exp_f32_e32 v74, v74
	v_exp_f32_e32 v75, v75
	s_waitcnt lgkmcnt(5)
	v_mfma_f32_32x32x16_bf16 v[34:49], v[154:157], v[106:109], v[34:49]
	ds_read_b128 v[154:157], v220 offset:26784
	v_exp_f32_e32 v76, v76
	v_exp_f32_e32 v77, v77
	v_add_f32_e32 v231, v231, v74
	v_add_f32_e32 v232, v232, v75
	s_waitcnt lgkmcnt(5)
	v_mfma_f32_32x32x16_bf16 v[50:65], v[158:161], v[106:109], v[50:65]
	ds_read_b128 v[158:161], v220 offset:33440
	v_exp_f32_e32 v78, v78
	v_exp_f32_e32 v79, v79
	v_add_f32_e32 v231, v231, v76
	v_add_f32_e32 v232, v232, v77
	v_exp_f32_e32 v80, v80
	s_waitcnt lgkmcnt(5)
	v_mfma_f32_32x32x16_bf16 v[34:49], v[138:141], v[110:113], v[34:49]
	ds_read_b64 v[162:163], v221 offset:8704
	ds_read_b64 v[164:165], v221 offset:8720
	v_exp_f32_e32 v81, v81
	v_add_f32_e32 v231, v231, v78
	v_add_f32_e32 v232, v232, v79
	v_add_f32_e32 v231, v231, v80
	s_waitcnt lgkmcnt(6)
	v_mfma_f32_32x32x16_bf16 v[50:65], v[142:145], v[110:113], v[50:65]
	ds_read_b64 v[166:167], v221 offset:13056
	ds_read_b64 v[168:169], v221 offset:13072
	v_add_f32_e32 v232, v232, v81
	v_cvt_pk_bf16_f32 v74, v74, v75
	v_cvt_pk_bf16_f32 v75, v76, v77
	v_cvt_pk_bf16_f32 v76, v78, v79
	v_cvt_pk_bf16_f32 v77, v80, v81
	v_exp_f32_e32 v82, v82
	s_waitcnt lgkmcnt(7)
	v_mfma_f32_32x32x16_bf16 v[34:49], v[146:149], v[114:117], v[34:49]
	ds_read_b64 v[170:171], v221 offset:8736
	ds_read_b64 v[172:173], v221 offset:8752
	v_exp_f32_e32 v83, v83
	v_exp_f32_e32 v84, v84
	v_exp_f32_e32 v85, v85
	s_waitcnt lgkmcnt(8)
	v_mfma_f32_32x32x16_bf16 v[50:65], v[150:153], v[114:117], v[50:65]
	ds_read_b64 v[174:175], v221 offset:13088
	ds_read_b64 v[176:177], v221 offset:13104
	v_add_f32_e32 v231, v231, v82
	v_add_f32_e32 v232, v232, v83
	v_exp_f32_e32 v86, v86
	v_exp_f32_e32 v87, v87
	s_waitcnt lgkmcnt(9)
	v_mfma_f32_32x32x16_bf16 v[34:49], v[154:157], v[118:121], v[34:49]
	ds_read_b64 v[180:181], v221 offset:8768
	ds_read_b64 v[182:183], v221 offset:8784
	v_add_f32_e32 v231, v231, v84
	v_add_f32_e32 v232, v232, v85
	v_exp_f32_e32 v88, v88
	v_exp_f32_e32 v89, v89
	s_waitcnt lgkmcnt(10)
	v_mfma_f32_32x32x16_bf16 v[50:65], v[158:161], v[118:121], v[50:65]
	ds_read_b64 v[184:185], v221 offset:13120
	ds_read_b64 v[186:187], v221 offset:13136
	v_add_f32_e32 v231, v231, v86
	v_add_f32_e32 v232, v232, v87
	v_add_f32_e32 v231, v231, v88
	v_add_f32_e32 v232, v232, v89
	v_cvt_pk_bf16_f32 v82, v82, v83
	v_cvt_pk_bf16_f32 v83, v84, v85
	v_cvt_pk_bf16_f32 v84, v86, v87
	s_waitcnt lgkmcnt(10)
	v_mfma_f32_32x32x16_bf16 v[2:17], v[162:165], v[66:69], v[2:17]
	ds_read_b64 v[188:189], v221 offset:8800
	ds_read_b64 v[190:191], v221 offset:8816
	v_cvt_pk_bf16_f32 v85, v88, v89
	v_exp_f32_e32 v90, v90
	v_exp_f32_e32 v91, v91
	v_exp_f32_e32 v92, v92
	s_waitcnt lgkmcnt(10)
	v_mfma_f32_32x32x16_bf16 v[18:33], v[166:169], v[66:69], v[18:33]
	ds_read_b64 v[192:193], v221 offset:13152
	ds_read_b64 v[194:195], v221 offset:13168
	v_exp_f32_e32 v93, v93
	v_add_f32_e32 v231, v231, v90
	v_add_f32_e32 v232, v232, v91
	v_exp_f32_e32 v94, v94
	s_waitcnt lgkmcnt(10)
	v_mfma_f32_32x32x16_bf16 v[2:17], v[170:173], v[74:77], v[2:17]
	v_exp_f32_e32 v95, v95
	v_add_f32_e32 v231, v231, v92
	v_add_f32_e32 v232, v232, v93
	v_exp_f32_e32 v96, v96
	s_waitcnt lgkmcnt(8)
	v_mfma_f32_32x32x16_bf16 v[18:33], v[174:177], v[74:77], v[18:33]
	s_waitcnt vmcnt(1)
	ds_write_b128 v222, v[200:203] offset:0
	ds_write_b128 v223, v[204:207] offset:0
	ds_write_b128 v224, v[208:211] offset:0
	ds_write_b64 v225, v[212:213] offset:26112
	ds_write_b64 v225, v[214:215] offset:26120
	v_exp_f32_e32 v97, v97
	v_add_f32_e32 v231, v231, v94
	v_add_f32_e32 v232, v232, v95
	v_add_f32_e32 v231, v231, v96
	v_add_f32_e32 v232, v232, v97
	s_waitcnt lgkmcnt(11)
	v_mfma_f32_32x32x16_bf16 v[2:17], v[180:183], v[82:85], v[2:17]
	v_cvt_pk_bf16_f32 v90, v90, v91
	v_cvt_pk_bf16_f32 v91, v92, v93
	v_cvt_pk_bf16_f32 v92, v94, v95
	v_cvt_pk_bf16_f32 v93, v96, v97
	v_max3_f32 v234, v34, v35, v36
	v_max3_f32 v235, v50, v51, v52
	s_waitcnt lgkmcnt(9)
	v_mfma_f32_32x32x16_bf16 v[18:33], v[184:187], v[82:85], v[18:33]
	v_max3_f32 v234, v234, v37, v38
	v_max3_f32 v235, v235, v53, v54
	v_max3_f32 v234, v234, v39, v40
	v_max3_f32 v235, v235, v55, v56
	v_max3_f32 v234, v234, v41, v42
	v_max3_f32 v235, v235, v57, v58
	v_max3_f32 v234, v234, v43, v44
	s_waitcnt lgkmcnt(7)
	v_mfma_f32_32x32x16_bf16 v[2:17], v[188:191], v[90:93], v[2:17]
	v_max3_f32 v235, v235, v59, v60
	v_max3_f32 v234, v234, v45, v46
	v_max3_f32 v235, v235, v61, v62
	v_max3_f32 v234, v234, v47, v48
	v_max3_f32 v235, v235, v63, v64
	v_max3_f32 v234, v234, v49, v65
	s_waitcnt lgkmcnt(5)
	v_mfma_f32_32x32x16_bf16 v[18:33], v[192:195], v[90:93], v[18:33]
	v_max_f32_e32 v234, v234, v235
	v_mov_b32_e32 v235, v234
	s_nop 1
	v_permlane32_swap_b32_e32 v234, v235
	v_max_f32_e32 v233, v234, v235
	v_cmp_lt_f32_e32 vcc, 4.0, v233
	s_cbranch_vccz .Lmla_nr_p1
	s_nop 15
	v_max_f32_e32 v234, 0, v233
	v_exp_f32_e64 v235, -v234
	v_add_f32_e32 v230, v230, v234
	v_sub_f32_e32 v34, v34, v234
	v_sub_f32_e32 v35, v35, v234
	v_sub_f32_e32 v36, v36, v234
	v_sub_f32_e32 v37, v37, v234
	v_sub_f32_e32 v38, v38, v234
	v_sub_f32_e32 v39, v39, v234
	v_sub_f32_e32 v40, v40, v234
	v_sub_f32_e32 v41, v41, v234
	v_sub_f32_e32 v42, v42, v234
	v_sub_f32_e32 v43, v43, v234
	v_sub_f32_e32 v44, v44, v234
	v_sub_f32_e32 v45, v45, v234
	v_sub_f32_e32 v46, v46, v234
	v_sub_f32_e32 v47, v47, v234
	v_sub_f32_e32 v48, v48, v234
	v_sub_f32_e32 v49, v49, v234
	v_sub_f32_e32 v50, v50, v234
	v_sub_f32_e32 v51, v51, v234
	v_sub_f32_e32 v52, v52, v234
	v_sub_f32_e32 v53, v53, v234
	v_sub_f32_e32 v54, v54, v234
	v_sub_f32_e32 v55, v55, v234
	v_sub_f32_e32 v56, v56, v234
	v_sub_f32_e32 v57, v57, v234
	v_sub_f32_e32 v58, v58, v234
	v_sub_f32_e32 v59, v59, v234
	v_sub_f32_e32 v60, v60, v234
	v_sub_f32_e32 v61, v61, v234
	v_sub_f32_e32 v62, v62, v234
	v_sub_f32_e32 v63, v63, v234
	v_sub_f32_e32 v64, v64, v234
	v_sub_f32_e32 v65, v65, v234
	v_mul_f32_e32 v231, v231, v235
	v_mul_f32_e32 v232, v232, v235
	v_mul_f32_e32 v2, v2, v235
	v_mul_f32_e32 v3, v3, v235
	v_mul_f32_e32 v4, v4, v235
	v_mul_f32_e32 v5, v5, v235
	v_mul_f32_e32 v6, v6, v235
	v_mul_f32_e32 v7, v7, v235
	v_mul_f32_e32 v8, v8, v235
	v_mul_f32_e32 v9, v9, v235
	v_mul_f32_e32 v10, v10, v235
	v_mul_f32_e32 v11, v11, v235
	v_mul_f32_e32 v12, v12, v235
	v_mul_f32_e32 v13, v13, v235
	v_mul_f32_e32 v14, v14, v235
	v_mul_f32_e32 v15, v15, v235
	v_mul_f32_e32 v16, v16, v235
	v_mul_f32_e32 v17, v17, v235
	v_mul_f32_e32 v18, v18, v235
	v_mul_f32_e32 v19, v19, v235
	v_mul_f32_e32 v20, v20, v235
	v_mul_f32_e32 v21, v21, v235
	v_mul_f32_e32 v22, v22, v235
	v_mul_f32_e32 v23, v23, v235
	v_mul_f32_e32 v24, v24, v235
	v_mul_f32_e32 v25, v25, v235
	v_mul_f32_e32 v26, v26, v235
	v_mul_f32_e32 v27, v27, v235
	v_mul_f32_e32 v28, v28, v235
	v_mul_f32_e32 v29, v29, v235
	v_mul_f32_e32 v30, v30, v235
	v_mul_f32_e32 v31, v31, v235
	v_mul_f32_e32 v32, v32, v235
	v_mul_f32_e32 v33, v33, v235
	v_sub_f32_e32 v122, 0, v230
	v_mov_b32_e32 v123, v122
	v_mov_b32_e32 v124, v122
	v_mov_b32_e32 v125, v122
	v_mov_b32_e32 v126, v122
	v_mov_b32_e32 v127, v122
	v_mov_b32_e32 v128, v122
	v_mov_b32_e32 v129, v122
	v_mov_b32_e32 v130, v122
	v_mov_b32_e32 v131, v122
	v_mov_b32_e32 v132, v122
	v_mov_b32_e32 v133, v122
	v_mov_b32_e32 v134, v122
	v_mov_b32_e32 v135, v122
	v_mov_b32_e32 v136, v122
	v_mov_b32_e32 v137, v122
.Lmla_nr_p1:
	ds_read_b128 v[138:141], v220 offset:39936
	ds_read_b128 v[142:145], v220 offset:46592
	ds_read_b128 v[146:149], v220 offset:39968
	ds_read_b128 v[150:153], v220 offset:46624
	ds_read_b128 v[154:157], v220 offset:40000
	ds_read_b128 v[158:161], v220 offset:46656
	s_waitcnt lgkmcnt(6)
	s_barrier
	v_exp_f32_e32 v34, v34
	v_exp_f32_e32 v35, v35
	v_exp_f32_e32 v36, v36
	v_exp_f32_e32 v37, v37
	s_waitcnt lgkmcnt(5)
	v_mfma_f32_32x32x16_bf16 v[66:81], v[138:141], v[98:101], v[122:137]
	ds_read_b128 v[138:141], v220 offset:40032
	v_add_f32_e32 v231, v231, v34
	v_add_f32_e32 v232, v232, v35
	v_exp_f32_e32 v38, v38
	v_exp_f32_e32 v39, v39
	s_waitcnt lgkmcnt(5)
	v_mfma_f32_32x32x16_bf16 v[82:97], v[142:145], v[98:101], v[122:137]
	ds_read_b128 v[142:145], v220 offset:46688
	v_add_f32_e32 v231, v231, v36
	v_add_f32_e32 v232, v232, v37
	v_exp_f32_e32 v40, v40
	v_exp_f32_e32 v41, v41
	s_waitcnt lgkmcnt(5)
	v_mfma_f32_32x32x16_bf16 v[66:81], v[146:149], v[102:105], v[66:81]
	ds_read_b128 v[146:149], v220 offset:40064
	global_load_dwordx4 v[200:203], v226, s[4:5]
	global_load_dwordx4 v[204:207], v227, s[4:5]
	global_load_dwordx4 v[208:211], v228, s[4:5]
	s_add_u32 s4, s4, 0x6000
	s_addc_u32 s5, s5, 0
	global_load_dwordx4 v[212:215], v229, s[10:11]
	s_add_u32 s10, s10, 0x80
	s_addc_u32 s11, s11, 0
	v_add_f32_e32 v231, v231, v38
	v_add_f32_e32 v232, v232, v39
	v_add_f32_e32 v231, v231, v40
	v_add_f32_e32 v232, v232, v41
	v_cvt_pk_bf16_f32 v34, v34, v35
	v_cvt_pk_bf16_f32 v35, v36, v37
	s_waitcnt lgkmcnt(5)
	v_mfma_f32_32x32x16_bf16 v[82:97], v[150:153], v[102:105], v[82:97]
	ds_read_b128 v[150:153], v220 offset:46720
	v_cvt_pk_bf16_f32 v36, v38, v39
	v_cvt_pk_bf16_f32 v37, v40, v41
	v_exp_f32_e32 v42, v42
	v_exp_f32_e32 v43, v43
	s_waitcnt lgkmcnt(5)
	v_mfma_f32_32x32x16_bf16 v[66:81], v[154:157], v[106:109], v[66:81]
	ds_read_b128 v[154:157], v220 offset:40096
	v_exp_f32_e32 v44, v44
	v_exp_f32_e32 v45, v45
	v_add_f32_e32 v231, v231, v42
	v_add_f32_e32 v232, v232, v43
	s_waitcnt lgkmcnt(5)
	v_mfma_f32_32x32x16_bf16 v[82:97], v[158:161], v[106:109], v[82:97]
	ds_read_b128 v[158:161], v220 offset:46752
	v_exp_f32_e32 v46, v46
	v_exp_f32_e32 v47, v47
	v_add_f32_e32 v231, v231, v44
	v_add_f32_e32 v232, v232, v45
	v_exp_f32_e32 v48, v48
	s_waitcnt lgkmcnt(5)
	v_mfma_f32_32x32x16_bf16 v[66:81], v[138:141], v[110:113], v[66:81]
	ds_read_b64 v[162:163], v221 offset:17408
	ds_read_b64 v[164:165], v221 offset:17424
	v_exp_f32_e32 v49, v49
	v_add_f32_e32 v231, v231, v46
	v_add_f32_e32 v232, v232, v47
	v_add_f32_e32 v231, v231, v48
	s_waitcnt lgkmcnt(6)
	v_mfma_f32_32x32x16_bf16 v[82:97], v[142:145], v[110:113], v[82:97]
	ds_read_b64 v[166:167], v221 offset:21760
	ds_read_b64 v[168:169], v221 offset:21776
	v_add_f32_e32 v232, v232, v49
	v_cvt_pk_bf16_f32 v42, v42, v43
	v_cvt_pk_bf16_f32 v43, v44, v45
	v_cvt_pk_bf16_f32 v44, v46, v47
	v_cvt_pk_bf16_f32 v45, v48, v49
	v_exp_f32_e32 v50, v50
	s_waitcnt lgkmcnt(7)
	v_mfma_f32_32x32x16_bf16 v[66:81], v[146:149], v[114:117], v[66:81]
	ds_read_b64 v[170:171], v221 offset:17440
	ds_read_b64 v[172:173], v221 offset:17456
	v_exp_f32_e32 v51, v51
	v_exp_f32_e32 v52, v52
	v_exp_f32_e32 v53, v53
	s_waitcnt lgkmcnt(8)
	v_mfma_f32_32x32x16_bf16 v[82:97], v[150:153], v[114:117], v[82:97]
	ds_read_b64 v[174:175], v221 offset:21792
	ds_read_b64 v[176:177], v221 offset:21808
	v_add_f32_e32 v231, v231, v50
	v_add_f32_e32 v232, v232, v51
	v_exp_f32_e32 v54, v54
	v_exp_f32_e32 v55, v55
	s_waitcnt lgkmcnt(9)
	v_mfma_f32_32x32x16_bf16 v[66:81], v[154:157], v[118:121], v[66:81]
	ds_read_b64 v[180:181], v221 offset:17472
	ds_read_b64 v[182:183], v221 offset:17488
	v_add_f32_e32 v231, v231, v52
	v_add_f32_e32 v232, v232, v53
	v_exp_f32_e32 v56, v56
	v_exp_f32_e32 v57, v57
	s_waitcnt lgkmcnt(10)
	v_mfma_f32_32x32x16_bf16 v[82:97], v[158:161], v[118:121], v[82:97]
	ds_read_b64 v[184:185], v221 offset:21824
	ds_read_b64 v[186:187], v221 offset:21840
	v_add_f32_e32 v231, v231, v54
	v_add_f32_e32 v232, v232, v55
	v_add_f32_e32 v231, v231, v56
	v_add_f32_e32 v232, v232, v57
	v_cvt_pk_bf16_f32 v50, v50, v51
	v_cvt_pk_bf16_f32 v51, v52, v53
	v_cvt_pk_bf16_f32 v52, v54, v55
	s_waitcnt lgkmcnt(10)
	v_mfma_f32_32x32x16_bf16 v[2:17], v[162:165], v[34:37], v[2:17]
	ds_read_b64 v[188:189], v221 offset:17504
	ds_read_b64 v[190:191], v221 offset:17520
	v_cvt_pk_bf16_f32 v53, v56, v57
	v_exp_f32_e32 v58, v58
	v_exp_f32_e32 v59, v59
	v_exp_f32_e32 v60, v60
	s_waitcnt lgkmcnt(10)
	v_mfma_f32_32x32x16_bf16 v[18:33], v[166:169], v[34:37], v[18:33]
	ds_read_b64 v[192:193], v221 offset:21856
	ds_read_b64 v[194:195], v221 offset:21872
	v_exp_f32_e32 v61, v61
	v_add_f32_e32 v231, v231, v58
	v_add_f32_e32 v232, v232, v59
	v_exp_f32_e32 v62, v62
	s_waitcnt lgkmcnt(10)
	v_mfma_f32_32x32x16_bf16 v[2:17], v[170:173], v[42:45], v[2:17]
	v_exp_f32_e32 v63, v63
	v_add_f32_e32 v231, v231, v60
	v_add_f32_e32 v232, v232, v61
	v_exp_f32_e32 v64, v64
	s_waitcnt lgkmcnt(8)
	v_mfma_f32_32x32x16_bf16 v[18:33], v[174:177], v[42:45], v[18:33]
	s_waitcnt vmcnt(4)
	ds_write_b64 v225, v[216:217] offset:0
	ds_write_b64 v225, v[218:219] offset:8
	v_exp_f32_e32 v65, v65
	v_add_f32_e32 v231, v231, v62
	v_add_f32_e32 v232, v232, v63
	v_add_f32_e32 v231, v231, v64
	v_add_f32_e32 v232, v232, v65
	s_waitcnt lgkmcnt(8)
	v_mfma_f32_32x32x16_bf16 v[2:17], v[180:183], v[50:53], v[2:17]
	v_cvt_pk_bf16_f32 v58, v58, v59
	v_cvt_pk_bf16_f32 v59, v60, v61
	v_cvt_pk_bf16_f32 v60, v62, v63
	v_cvt_pk_bf16_f32 v61, v64, v65
	v_max3_f32 v234, v66, v67, v68
	v_max3_f32 v235, v82, v83, v84
	s_waitcnt lgkmcnt(6)
	v_mfma_f32_32x32x16_bf16 v[18:33], v[184:187], v[50:53], v[18:33]
	v_max3_f32 v234, v234, v69, v70
	v_max3_f32 v235, v235, v85, v86
	v_max3_f32 v234, v234, v71, v72
	v_max3_f32 v235, v235, v87, v88
	v_max3_f32 v234, v234, v73, v74
	v_max3_f32 v235, v235, v89, v90
	v_max3_f32 v234, v234, v75, v76
	s_waitcnt lgkmcnt(4)
	v_mfma_f32_32x32x16_bf16 v[2:17], v[188:191], v[58:61], v[2:17]
	v_max3_f32 v235, v235, v91, v92
	v_max3_f32 v234, v234, v77, v78
	v_max3_f32 v235, v235, v93, v94
	v_max3_f32 v234, v234, v79, v80
	v_max3_f32 v235, v235, v95, v96
	v_max3_f32 v234, v234, v81, v97
	s_waitcnt lgkmcnt(2)
	v_mfma_f32_32x32x16_bf16 v[18:33], v[192:195], v[58:61], v[18:33]
	v_max_f32_e32 v234, v234, v235
	v_mov_b32_e32 v235, v234
	s_nop 1
	v_permlane32_swap_b32_e32 v234, v235
	v_max_f32_e32 v233, v234, v235
	v_cmp_lt_f32_e32 vcc, 4.0, v233
	s_cbranch_vccz .Lmla_nr_p2
	s_nop 15
	v_max_f32_e32 v234, 0, v233
	v_exp_f32_e64 v235, -v234
	v_add_f32_e32 v230, v230, v234
	v_sub_f32_e32 v66, v66, v234
	v_sub_f32_e32 v67, v67, v234
	v_sub_f32_e32 v68, v68, v234
	v_sub_f32_e32 v69, v69, v234
	v_sub_f32_e32 v70, v70, v234
	v_sub_f32_e32 v71, v71, v234
	v_sub_f32_e32 v72, v72, v234
	v_sub_f32_e32 v73, v73, v234
	v_sub_f32_e32 v74, v74, v234
	v_sub_f32_e32 v75, v75, v234
	v_sub_f32_e32 v76, v76, v234
	v_sub_f32_e32 v77, v77, v234
	v_sub_f32_e32 v78, v78, v234
	v_sub_f32_e32 v79, v79, v234
	v_sub_f32_e32 v80, v80, v234
	v_sub_f32_e32 v81, v81, v234
	v_sub_f32_e32 v82, v82, v234
	v_sub_f32_e32 v83, v83, v234
	v_sub_f32_e32 v84, v84, v234
	v_sub_f32_e32 v85, v85, v234
	v_sub_f32_e32 v86, v86, v234
	v_sub_f32_e32 v87, v87, v234
	v_sub_f32_e32 v88, v88, v234
	v_sub_f32_e32 v89, v89, v234
	v_sub_f32_e32 v90, v90, v234
	v_sub_f32_e32 v91, v91, v234
	v_sub_f32_e32 v92, v92, v234
	v_sub_f32_e32 v93, v93, v234
	v_sub_f32_e32 v94, v94, v234
	v_sub_f32_e32 v95, v95, v234
	v_sub_f32_e32 v96, v96, v234
	v_sub_f32_e32 v97, v97, v234
	v_mul_f32_e32 v231, v231, v235
	v_mul_f32_e32 v232, v232, v235
	v_mul_f32_e32 v2, v2, v235
	v_mul_f32_e32 v3, v3, v235
	v_mul_f32_e32 v4, v4, v235
	v_mul_f32_e32 v5, v5, v235
	v_mul_f32_e32 v6, v6, v235
	v_mul_f32_e32 v7, v7, v235
	v_mul_f32_e32 v8, v8, v235
	v_mul_f32_e32 v9, v9, v235
	v_mul_f32_e32 v10, v10, v235
	v_mul_f32_e32 v11, v11, v235
	v_mul_f32_e32 v12, v12, v235
	v_mul_f32_e32 v13, v13, v235
	v_mul_f32_e32 v14, v14, v235
	v_mul_f32_e32 v15, v15, v235
	v_mul_f32_e32 v16, v16, v235
	v_mul_f32_e32 v17, v17, v235
	v_mul_f32_e32 v18, v18, v235
	v_mul_f32_e32 v19, v19, v235
	v_mul_f32_e32 v20, v20, v235
	v_mul_f32_e32 v21, v21, v235
	v_mul_f32_e32 v22, v22, v235
	v_mul_f32_e32 v23, v23, v235
	v_mul_f32_e32 v24, v24, v235
	v_mul_f32_e32 v25, v25, v235
	v_mul_f32_e32 v26, v26, v235
	v_mul_f32_e32 v27, v27, v235
	v_mul_f32_e32 v28, v28, v235
	v_mul_f32_e32 v29, v29, v235
	v_mul_f32_e32 v30, v30, v235
	v_mul_f32_e32 v31, v31, v235
	v_mul_f32_e32 v32, v32, v235
	v_mul_f32_e32 v33, v33, v235
	v_sub_f32_e32 v122, 0, v230
	v_mov_b32_e32 v123, v122
	v_mov_b32_e32 v124, v122
	v_mov_b32_e32 v125, v122
	v_mov_b32_e32 v126, v122
	v_mov_b32_e32 v127, v122
	v_mov_b32_e32 v128, v122
	v_mov_b32_e32 v129, v122
	v_mov_b32_e32 v130, v122
	v_mov_b32_e32 v131, v122
	v_mov_b32_e32 v132, v122
	v_mov_b32_e32 v133, v122
	v_mov_b32_e32 v134, v122
	v_mov_b32_e32 v135, v122
	v_mov_b32_e32 v136, v122
	v_mov_b32_e32 v137, v122
.Lmla_nr_p2:
	ds_read_b128 v[138:141], v220 offset:0
	ds_read_b128 v[142:145], v220 offset:6656
	ds_read_b128 v[146:149], v220 offset:32
	ds_read_b128 v[150:153], v220 offset:6688
	ds_read_b128 v[154:157], v220 offset:64
	ds_read_b128 v[158:161], v220 offset:6720
	s_waitcnt lgkmcnt(6)
	s_barrier
	v_exp_f32_e32 v66, v66
	v_exp_f32_e32 v67, v67
	v_exp_f32_e32 v68, v68
	v_exp_f32_e32 v69, v69
	s_waitcnt lgkmcnt(5)
	v_mfma_f32_32x32x16_bf16 v[34:49], v[138:141], v[98:101], v[122:137]
	ds_read_b128 v[138:141], v220 offset:96
	v_add_f32_e32 v231, v231, v66
	v_add_f32_e32 v232, v232, v67
	v_exp_f32_e32 v70, v70
	v_exp_f32_e32 v71, v71
	s_waitcnt lgkmcnt(5)
	v_mfma_f32_32x32x16_bf16 v[50:65], v[142:145], v[98:101], v[122:137]
	ds_read_b128 v[142:145], v220 offset:6752
	v_add_f32_e32 v231, v231, v68
	v_add_f32_e32 v232, v232, v69
	v_exp_f32_e32 v72, v72
	v_exp_f32_e32 v73, v73
	s_waitcnt lgkmcnt(5)
	v_mfma_f32_32x32x16_bf16 v[34:49], v[146:149], v[102:105], v[34:49]
	ds_read_b128 v[146:149], v220 offset:128
	global_load_dwordx4 v[216:219], v229, s[10:11]
	s_add_u32 s10, s10, 0x80
	s_addc_u32 s11, s11, 0
	v_add_f32_e32 v231, v231, v70
	v_add_f32_e32 v232, v232, v71
	v_add_f32_e32 v231, v231, v72
	v_add_f32_e32 v232, v232, v73
	v_cvt_pk_bf16_f32 v66, v66, v67
	v_cvt_pk_bf16_f32 v67, v68, v69
	s_waitcnt lgkmcnt(5)
	v_mfma_f32_32x32x16_bf16 v[50:65], v[150:153], v[102:105], v[50:65]
	ds_read_b128 v[150:153], v220 offset:6784
	v_cvt_pk_bf16_f32 v68, v70, v71
	v_cvt_pk_bf16_f32 v69, v72, v73
	v_exp_f32_e32 v74, v74
	v_exp_f32_e32 v75, v75
	s_waitcnt lgkmcnt(5)
	v_mfma_f32_32x32x16_bf16 v[34:49], v[154:157], v[106:109], v[34:49]
	ds_read_b128 v[154:157], v220 offset:160
	v_exp_f32_e32 v76, v76
	v_exp_f32_e32 v77, v77
	v_add_f32_e32 v231, v231, v74
	v_add_f32_e32 v232, v232, v75
	s_waitcnt lgkmcnt(5)
	v_mfma_f32_32x32x16_bf16 v[50:65], v[158:161], v[106:109], v[50:65]
	ds_read_b128 v[158:161], v220 offset:6816
	v_exp_f32_e32 v78, v78
	v_exp_f32_e32 v79, v79
	v_add_f32_e32 v231, v231, v76
	v_add_f32_e32 v232, v232, v77
	v_exp_f32_e32 v80, v80
	s_waitcnt lgkmcnt(5)
	v_mfma_f32_32x32x16_bf16 v[34:49], v[138:141], v[110:113], v[34:49]
	ds_read_b64 v[162:163], v221 offset:26112
	ds_read_b64 v[164:165], v221 offset:26128
	v_exp_f32_e32 v81, v81
	v_add_f32_e32 v231, v231, v78
	v_add_f32_e32 v232, v232, v79
	v_add_f32_e32 v231, v231, v80
	s_waitcnt lgkmcnt(6)
	v_mfma_f32_32x32x16_bf16 v[50:65], v[142:145], v[110:113], v[50:65]
	ds_read_b64 v[166:167], v221 offset:30464
	ds_read_b64 v[168:169], v221 offset:30480
	v_add_f32_e32 v232, v232, v81
	v_cvt_pk_bf16_f32 v74, v74, v75
	v_cvt_pk_bf16_f32 v75, v76, v77
	v_cvt_pk_bf16_f32 v76, v78, v79
	v_cvt_pk_bf16_f32 v77, v80, v81
	v_exp_f32_e32 v82, v82
	s_waitcnt lgkmcnt(7)
	v_mfma_f32_32x32x16_bf16 v[34:49], v[146:149], v[114:117], v[34:49]
	ds_read_b64 v[170:171], v221 offset:26144
	ds_read_b64 v[172:173], v221 offset:26160
	v_exp_f32_e32 v83, v83
	v_exp_f32_e32 v84, v84
	v_exp_f32_e32 v85, v85
	s_waitcnt lgkmcnt(8)
	v_mfma_f32_32x32x16_bf16 v[50:65], v[150:153], v[114:117], v[50:65]
	ds_read_b64 v[174:175], v221 offset:30496
	ds_read_b64 v[176:177], v221 offset:30512
	v_add_f32_e32 v231, v231, v82
	v_add_f32_e32 v232, v232, v83
	v_exp_f32_e32 v86, v86
	v_exp_f32_e32 v87, v87
	s_waitcnt lgkmcnt(9)
	v_mfma_f32_32x32x16_bf16 v[34:49], v[154:157], v[118:121], v[34:49]
	ds_read_b64 v[180:181], v221 offset:26176
	ds_read_b64 v[182:183], v221 offset:26192
	v_add_f32_e32 v231, v231, v84
	v_add_f32_e32 v232, v232, v85
	v_exp_f32_e32 v88, v88
	v_exp_f32_e32 v89, v89
	s_waitcnt lgkmcnt(10)
	v_mfma_f32_32x32x16_bf16 v[50:65], v[158:161], v[118:121], v[50:65]
	ds_read_b64 v[184:185], v221 offset:30528
	ds_read_b64 v[186:187], v221 offset:30544
	v_add_f32_e32 v231, v231, v86
	v_add_f32_e32 v232, v232, v87
	v_add_f32_e32 v231, v231, v88
	v_add_f32_e32 v232, v232, v89
	v_cvt_pk_bf16_f32 v82, v82, v83
	v_cvt_pk_bf16_f32 v83, v84, v85
	v_cvt_pk_bf16_f32 v84, v86, v87
	s_waitcnt lgkmcnt(10)
	v_mfma_f32_32x32x16_bf16 v[2:17], v[162:165], v[66:69], v[2:17]
	ds_read_b64 v[188:189], v221 offset:26208
	ds_read_b64 v[190:191], v221 offset:26224
	v_cvt_pk_bf16_f32 v85, v88, v89
	v_exp_f32_e32 v90, v90
	v_exp_f32_e32 v91, v91
	v_exp_f32_e32 v92, v92
	s_waitcnt lgkmcnt(10)
	v_mfma_f32_32x32x16_bf16 v[18:33], v[166:169], v[66:69], v[18:33]
	ds_read_b64 v[192:193], v221 offset:30560
	ds_read_b64 v[194:195], v221 offset:30576
	v_exp_f32_e32 v93, v93
	v_add_f32_e32 v231, v231, v90
	v_add_f32_e32 v232, v232, v91
	v_exp_f32_e32 v94, v94
	s_waitcnt lgkmcnt(10)
	v_mfma_f32_32x32x16_bf16 v[2:17], v[170:173], v[74:77], v[2:17]
	v_exp_f32_e32 v95, v95
	v_add_f32_e32 v231, v231, v92
	v_add_f32_e32 v232, v232, v93
	v_exp_f32_e32 v96, v96
	s_waitcnt lgkmcnt(8)
	v_mfma_f32_32x32x16_bf16 v[18:33], v[174:177], v[74:77], v[18:33]
	s_waitcnt vmcnt(1)
	ds_write_b128 v222, v[200:203] offset:26624
	ds_write_b128 v223, v[204:207] offset:26624
	ds_write_b128 v224, v[208:211] offset:26624
	ds_write_b64 v225, v[212:213] offset:8704
	ds_write_b64 v225, v[214:215] offset:8712
	v_exp_f32_e32 v97, v97
	v_add_f32_e32 v231, v231, v94
	v_add_f32_e32 v232, v232, v95
	v_add_f32_e32 v231, v231, v96
	v_add_f32_e32 v232, v232, v97
	s_waitcnt lgkmcnt(11)
	v_mfma_f32_32x32x16_bf16 v[2:17], v[180:183], v[82:85], v[2:17]
	v_cvt_pk_bf16_f32 v90, v90, v91
	v_cvt_pk_bf16_f32 v91, v92, v93
	v_cvt_pk_bf16_f32 v92, v94, v95
	v_cvt_pk_bf16_f32 v93, v96, v97
	v_max3_f32 v234, v34, v35, v36
	v_max3_f32 v235, v50, v51, v52
	s_waitcnt lgkmcnt(9)
	v_mfma_f32_32x32x16_bf16 v[18:33], v[184:187], v[82:85], v[18:33]
	v_max3_f32 v234, v234, v37, v38
	v_max3_f32 v235, v235, v53, v54
	v_max3_f32 v234, v234, v39, v40
	v_max3_f32 v235, v235, v55, v56
	v_max3_f32 v234, v234, v41, v42
	v_max3_f32 v235, v235, v57, v58
	v_max3_f32 v234, v234, v43, v44
	s_waitcnt lgkmcnt(7)
	v_mfma_f32_32x32x16_bf16 v[2:17], v[188:191], v[90:93], v[2:17]
	v_max3_f32 v235, v235, v59, v60
	v_max3_f32 v234, v234, v45, v46
	v_max3_f32 v235, v235, v61, v62
	v_max3_f32 v234, v234, v47, v48
	v_max3_f32 v235, v235, v63, v64
	v_max3_f32 v234, v234, v49, v65
	s_waitcnt lgkmcnt(5)
	v_mfma_f32_32x32x16_bf16 v[18:33], v[192:195], v[90:93], v[18:33]
	v_max_f32_e32 v234, v234, v235
	v_mov_b32_e32 v235, v234
	s_nop 1
	v_permlane32_swap_b32_e32 v234, v235
	v_max_f32_e32 v233, v234, v235
	v_cmp_lt_f32_e32 vcc, 4.0, v233
	s_cbranch_vccz .Lmla_nr_p3
	s_nop 15
	v_max_f32_e32 v234, 0, v233
	v_exp_f32_e64 v235, -v234
	v_add_f32_e32 v230, v230, v234
	v_sub_f32_e32 v34, v34, v234
	v_sub_f32_e32 v35, v35, v234
	v_sub_f32_e32 v36, v36, v234
	v_sub_f32_e32 v37, v37, v234
	v_sub_f32_e32 v38, v38, v234
	v_sub_f32_e32 v39, v39, v234
	v_sub_f32_e32 v40, v40, v234
	v_sub_f32_e32 v41, v41, v234
	v_sub_f32_e32 v42, v42, v234
	v_sub_f32_e32 v43, v43, v234
	v_sub_f32_e32 v44, v44, v234
	v_sub_f32_e32 v45, v45, v234
	v_sub_f32_e32 v46, v46, v234
	v_sub_f32_e32 v47, v47, v234
	v_sub_f32_e32 v48, v48, v234
	v_sub_f32_e32 v49, v49, v234
	v_sub_f32_e32 v50, v50, v234
	v_sub_f32_e32 v51, v51, v234
	v_sub_f32_e32 v52, v52, v234
	v_sub_f32_e32 v53, v53, v234
	v_sub_f32_e32 v54, v54, v234
	v_sub_f32_e32 v55, v55, v234
	v_sub_f32_e32 v56, v56, v234
	v_sub_f32_e32 v57, v57, v234
	v_sub_f32_e32 v58, v58, v234
	v_sub_f32_e32 v59, v59, v234
	v_sub_f32_e32 v60, v60, v234
	v_sub_f32_e32 v61, v61, v234
	v_sub_f32_e32 v62, v62, v234
	v_sub_f32_e32 v63, v63, v234
	v_sub_f32_e32 v64, v64, v234
	v_sub_f32_e32 v65, v65, v234
	v_mul_f32_e32 v231, v231, v235
	v_mul_f32_e32 v232, v232, v235
	v_mul_f32_e32 v2, v2, v235
	v_mul_f32_e32 v3, v3, v235
	v_mul_f32_e32 v4, v4, v235
	v_mul_f32_e32 v5, v5, v235
	v_mul_f32_e32 v6, v6, v235
	v_mul_f32_e32 v7, v7, v235
	v_mul_f32_e32 v8, v8, v235
	v_mul_f32_e32 v9, v9, v235
	v_mul_f32_e32 v10, v10, v235
	v_mul_f32_e32 v11, v11, v235
	v_mul_f32_e32 v12, v12, v235
	v_mul_f32_e32 v13, v13, v235
	v_mul_f32_e32 v14, v14, v235
	v_mul_f32_e32 v15, v15, v235
	v_mul_f32_e32 v16, v16, v235
	v_mul_f32_e32 v17, v17, v235
	v_mul_f32_e32 v18, v18, v235
	v_mul_f32_e32 v19, v19, v235
	v_mul_f32_e32 v20, v20, v235
	v_mul_f32_e32 v21, v21, v235
	v_mul_f32_e32 v22, v22, v235
	v_mul_f32_e32 v23, v23, v235
	v_mul_f32_e32 v24, v24, v235
	v_mul_f32_e32 v25, v25, v235
	v_mul_f32_e32 v26, v26, v235
	v_mul_f32_e32 v27, v27, v235
	v_mul_f32_e32 v28, v28, v235
	v_mul_f32_e32 v29, v29, v235
	v_mul_f32_e32 v30, v30, v235
	v_mul_f32_e32 v31, v31, v235
	v_mul_f32_e32 v32, v32, v235
	v_mul_f32_e32 v33, v33, v235
	v_sub_f32_e32 v122, 0, v230
	v_mov_b32_e32 v123, v122
	v_mov_b32_e32 v124, v122
	v_mov_b32_e32 v125, v122
	v_mov_b32_e32 v126, v122
	v_mov_b32_e32 v127, v122
	v_mov_b32_e32 v128, v122
	v_mov_b32_e32 v129, v122
	v_mov_b32_e32 v130, v122
	v_mov_b32_e32 v131, v122
	v_mov_b32_e32 v132, v122
	v_mov_b32_e32 v133, v122
	v_mov_b32_e32 v134, v122
	v_mov_b32_e32 v135, v122
	v_mov_b32_e32 v136, v122
	v_mov_b32_e32 v137, v122
.Lmla_nr_p3:
	ds_read_b128 v[138:141], v220 offset:13312
	ds_read_b128 v[142:145], v220 offset:19968
	ds_read_b128 v[146:149], v220 offset:13344
	ds_read_b128 v[150:153], v220 offset:20000
	ds_read_b128 v[154:157], v220 offset:13376
	ds_read_b128 v[158:161], v220 offset:20032
	s_waitcnt lgkmcnt(6)
	s_barrier
	s_add_i32 s16, s16, -1
	s_cmp_lg_u32 s16, 0
	s_cbranch_scc1 .Lmla_loop
	v_exp_f32_e32 v34, v34
	v_exp_f32_e32 v35, v35
	v_exp_f32_e32 v36, v36
	v_exp_f32_e32 v37, v37
	s_waitcnt lgkmcnt(5)
	v_mfma_f32_32x32x16_bf16 v[66:81], v[138:141], v[98:101], v[122:137]
	ds_read_b128 v[138:141], v220 offset:13408
	v_add_f32_e32 v231, v231, v34
	v_add_f32_e32 v232, v232, v35
	v_exp_f32_e32 v38, v38
	v_exp_f32_e32 v39, v39
	s_waitcnt lgkmcnt(5)
	v_mfma_f32_32x32x16_bf16 v[82:97], v[142:145], v[98:101], v[122:137]
	ds_read_b128 v[142:145], v220 offset:20064
	v_add_f32_e32 v231, v231, v36
	v_add_f32_e32 v232, v232, v37
	v_exp_f32_e32 v40, v40
	v_exp_f32_e32 v41, v41
	s_waitcnt lgkmcnt(5)
	v_mfma_f32_32x32x16_bf16 v[66:81], v[146:149], v[102:105], v[66:81]
	ds_read_b128 v[146:149], v220 offset:13440
	global_load_dwordx4 v[212:215], v229, s[10:11]
	s_add_u32 s10, s10, 0x80
	s_addc_u32 s11, s11, 0
	v_add_f32_e32 v231, v231, v38
	v_add_f32_e32 v232, v232, v39
	v_add_f32_e32 v231, v231, v40
	v_add_f32_e32 v232, v232, v41
	v_cvt_pk_bf16_f32 v34, v34, v35
	v_cvt_pk_bf16_f32 v35, v36, v37
	s_waitcnt lgkmcnt(5)
	v_mfma_f32_32x32x16_bf16 v[82:97], v[150:153], v[102:105], v[82:97]
	ds_read_b128 v[150:153], v220 offset:20096
	v_cvt_pk_bf16_f32 v36, v38, v39
	v_cvt_pk_bf16_f32 v37, v40, v41
	v_exp_f32_e32 v42, v42
	v_exp_f32_e32 v43, v43
	s_waitcnt lgkmcnt(5)
	v_mfma_f32_32x32x16_bf16 v[66:81], v[154:157], v[106:109], v[66:81]
	ds_read_b128 v[154:157], v220 offset:13472
	v_exp_f32_e32 v44, v44
	v_exp_f32_e32 v45, v45
	v_add_f32_e32 v231, v231, v42
	v_add_f32_e32 v232, v232, v43
	s_waitcnt lgkmcnt(5)
	v_mfma_f32_32x32x16_bf16 v[82:97], v[158:161], v[106:109], v[82:97]
	ds_read_b128 v[158:161], v220 offset:20128
	v_exp_f32_e32 v46, v46
	v_exp_f32_e32 v47, v47
	v_add_f32_e32 v231, v231, v44
	v_add_f32_e32 v232, v232, v45
	v_exp_f32_e32 v48, v48
	s_waitcnt lgkmcnt(5)
	v_mfma_f32_32x32x16_bf16 v[66:81], v[138:141], v[110:113], v[66:81]
	ds_read_b64 v[162:163], v221 offset:0
	ds_read_b64 v[164:165], v221 offset:16
	v_exp_f32_e32 v49, v49
	v_add_f32_e32 v231, v231, v46
	v_add_f32_e32 v232, v232, v47
	v_add_f32_e32 v231, v231, v48
	s_waitcnt lgkmcnt(6)
	v_mfma_f32_32x32x16_bf16 v[82:97], v[142:145], v[110:113], v[82:97]
	ds_read_b64 v[166:167], v221 offset:4352
	ds_read_b64 v[168:169], v221 offset:4368
	v_add_f32_e32 v232, v232, v49
	v_cvt_pk_bf16_f32 v42, v42, v43
	v_cvt_pk_bf16_f32 v43, v44, v45
	v_cvt_pk_bf16_f32 v44, v46, v47
	v_cvt_pk_bf16_f32 v45, v48, v49
	v_exp_f32_e32 v50, v50
	s_waitcnt lgkmcnt(7)
	v_mfma_f32_32x32x16_bf16 v[66:81], v[146:149], v[114:117], v[66:81]
	ds_read_b64 v[170:171], v221 offset:32
	ds_read_b64 v[172:173], v221 offset:48
	v_exp_f32_e32 v51, v51
	v_exp_f32_e32 v52, v52
	v_exp_f32_e32 v53, v53
	s_waitcnt lgkmcnt(8)
	v_mfma_f32_32x32x16_bf16 v[82:97], v[150:153], v[114:117], v[82:97]
	ds_read_b64 v[174:175], v221 offset:4384
	ds_read_b64 v[176:177], v221 offset:4400
	v_add_f32_e32 v231, v231, v50
	v_add_f32_e32 v232, v232, v51
	v_exp_f32_e32 v54, v54
	v_exp_f32_e32 v55, v55
	s_waitcnt lgkmcnt(9)
	v_mfma_f32_32x32x16_bf16 v[66:81], v[154:157], v[118:121], v[66:81]
	ds_read_b64 v[180:181], v221 offset:64
	ds_read_b64 v[182:183], v221 offset:80
	v_add_f32_e32 v231, v231, v52
	v_add_f32_e32 v232, v232, v53
	v_exp_f32_e32 v56, v56
	v_exp_f32_e32 v57, v57
	s_waitcnt lgkmcnt(10)
	v_mfma_f32_32x32x16_bf16 v[82:97], v[158:161], v[118:121], v[82:97]
	ds_read_b64 v[184:185], v221 offset:4416
	ds_read_b64 v[186:187], v221 offset:4432
	v_add_f32_e32 v231, v231, v54
	v_add_f32_e32 v232, v232, v55
	v_add_f32_e32 v231, v231, v56
	v_add_f32_e32 v232, v232, v57
	v_cvt_pk_bf16_f32 v50, v50, v51
	v_cvt_pk_bf16_f32 v51, v52, v53
	v_cvt_pk_bf16_f32 v52, v54, v55
	s_waitcnt lgkmcnt(10)
	v_mfma_f32_32x32x16_bf16 v[2:17], v[162:165], v[34:37], v[2:17]
	ds_read_b64 v[188:189], v221 offset:96
	ds_read_b64 v[190:191], v221 offset:112
	v_cvt_pk_bf16_f32 v53, v56, v57
	v_exp_f32_e32 v58, v58
	v_exp_f32_e32 v59, v59
	v_exp_f32_e32 v60, v60
	s_waitcnt lgkmcnt(10)
	v_mfma_f32_32x32x16_bf16 v[18:33], v[166:169], v[34:37], v[18:33]
	ds_read_b64 v[192:193], v221 offset:4448
	ds_read_b64 v[194:195], v221 offset:4464
	v_exp_f32_e32 v61, v61
	v_add_f32_e32 v231, v231, v58
	v_add_f32_e32 v232, v232, v59
	v_exp_f32_e32 v62, v62
	s_waitcnt lgkmcnt(10)
	v_mfma_f32_32x32x16_bf16 v[2:17], v[170:173], v[42:45], v[2:17]
	v_exp_f32_e32 v63, v63
	v_add_f32_e32 v231, v231, v60
	v_add_f32_e32 v232, v232, v61
	v_exp_f32_e32 v64, v64
	s_waitcnt lgkmcnt(8)
	v_mfma_f32_32x32x16_bf16 v[18:33], v[174:177], v[42:45], v[18:33]
	s_waitcnt vmcnt(1)
	ds_write_b64 v225, v[216:217] offset:17408
	ds_write_b64 v225, v[218:219] offset:17416
	v_exp_f32_e32 v65, v65
	v_add_f32_e32 v231, v231, v62
	v_add_f32_e32 v232, v232, v63
	v_add_f32_e32 v231, v231, v64
	v_add_f32_e32 v232, v232, v65
	s_waitcnt lgkmcnt(8)
	v_mfma_f32_32x32x16_bf16 v[2:17], v[180:183], v[50:53], v[2:17]
	v_cvt_pk_bf16_f32 v58, v58, v59
	v_cvt_pk_bf16_f32 v59, v60, v61
	v_cvt_pk_bf16_f32 v60, v62, v63
	v_cvt_pk_bf16_f32 v61, v64, v65
	v_max3_f32 v234, v66, v67, v68
	v_max3_f32 v235, v82, v83, v84
	s_waitcnt lgkmcnt(6)
	v_mfma_f32_32x32x16_bf16 v[18:33], v[184:187], v[50:53], v[18:33]
	v_max3_f32 v234, v234, v69, v70
	v_max3_f32 v235, v235, v85, v86
	v_max3_f32 v234, v234, v71, v72
	v_max3_f32 v235, v235, v87, v88
	v_max3_f32 v234, v234, v73, v74
	v_max3_f32 v235, v235, v89, v90
	v_max3_f32 v234, v234, v75, v76
	s_waitcnt lgkmcnt(4)
	v_mfma_f32_32x32x16_bf16 v[2:17], v[188:191], v[58:61], v[2:17]
	v_max3_f32 v235, v235, v91, v92
	v_max3_f32 v234, v234, v77, v78
	v_max3_f32 v235, v235, v93, v94
	v_max3_f32 v234, v234, v79, v80
	v_max3_f32 v235, v235, v95, v96
	v_max3_f32 v234, v234, v81, v97
	s_waitcnt lgkmcnt(2)
	v_mfma_f32_32x32x16_bf16 v[18:33], v[192:195], v[58:61], v[18:33]
	v_max_f32_e32 v234, v234, v235
	v_mov_b32_e32 v235, v234
	s_nop 1
	v_permlane32_swap_b32_e32 v234, v235
	v_max_f32_e32 v233, v234, v235
	v_cmp_lt_f32_e32 vcc, 4.0, v233
	s_cbranch_vccz .Lmla_nr_t0
	s_nop 15
	v_max_f32_e32 v234, 0, v233
	v_exp_f32_e64 v235, -v234
	v_add_f32_e32 v230, v230, v234
	v_sub_f32_e32 v66, v66, v234
	v_sub_f32_e32 v67, v67, v234
	v_sub_f32_e32 v68, v68, v234
	v_sub_f32_e32 v69, v69, v234
	v_sub_f32_e32 v70, v70, v234
	v_sub_f32_e32 v71, v71, v234
	v_sub_f32_e32 v72, v72, v234
	v_sub_f32_e32 v73, v73, v234
	v_sub_f32_e32 v74, v74, v234
	v_sub_f32_e32 v75, v75, v234
	v_sub_f32_e32 v76, v76, v234
	v_sub_f32_e32 v77, v77, v234
	v_sub_f32_e32 v78, v78, v234
	v_sub_f32_e32 v79, v79, v234
	v_sub_f32_e32 v80, v80, v234
	v_sub_f32_e32 v81, v81, v234
	v_sub_f32_e32 v82, v82, v234
	v_sub_f32_e32 v83, v83, v234
	v_sub_f32_e32 v84, v84, v234
	v_sub_f32_e32 v85, v85, v234
	v_sub_f32_e32 v86, v86, v234
	v_sub_f32_e32 v87, v87, v234
	v_sub_f32_e32 v88, v88, v234
	v_sub_f32_e32 v89, v89, v234
	v_sub_f32_e32 v90, v90, v234
	v_sub_f32_e32 v91, v91, v234
	v_sub_f32_e32 v92, v92, v234
	v_sub_f32_e32 v93, v93, v234
	v_sub_f32_e32 v94, v94, v234
	v_sub_f32_e32 v95, v95, v234
	v_sub_f32_e32 v96, v96, v234
	v_sub_f32_e32 v97, v97, v234
	v_mul_f32_e32 v231, v231, v235
	v_mul_f32_e32 v232, v232, v235
	v_mul_f32_e32 v2, v2, v235
	v_mul_f32_e32 v3, v3, v235
	v_mul_f32_e32 v4, v4, v235
	v_mul_f32_e32 v5, v5, v235
	v_mul_f32_e32 v6, v6, v235
	v_mul_f32_e32 v7, v7, v235
	v_mul_f32_e32 v8, v8, v235
	v_mul_f32_e32 v9, v9, v235
	v_mul_f32_e32 v10, v10, v235
	v_mul_f32_e32 v11, v11, v235
	v_mul_f32_e32 v12, v12, v235
	v_mul_f32_e32 v13, v13, v235
	v_mul_f32_e32 v14, v14, v235
	v_mul_f32_e32 v15, v15, v235
	v_mul_f32_e32 v16, v16, v235
	v_mul_f32_e32 v17, v17, v235
	v_mul_f32_e32 v18, v18, v235
	v_mul_f32_e32 v19, v19, v235
	v_mul_f32_e32 v20, v20, v235
	v_mul_f32_e32 v21, v21, v235
	v_mul_f32_e32 v22, v22, v235
	v_mul_f32_e32 v23, v23, v235
	v_mul_f32_e32 v24, v24, v235
	v_mul_f32_e32 v25, v25, v235
	v_mul_f32_e32 v26, v26, v235
	v_mul_f32_e32 v27, v27, v235
	v_mul_f32_e32 v28, v28, v235
	v_mul_f32_e32 v29, v29, v235
	v_mul_f32_e32 v30, v30, v235
	v_mul_f32_e32 v31, v31, v235
	v_mul_f32_e32 v32, v32, v235
	v_mul_f32_e32 v33, v33, v235
	v_sub_f32_e32 v122, 0, v230
	v_mov_b32_e32 v123, v122
	v_mov_b32_e32 v124, v122
	v_mov_b32_e32 v125, v122
	v_mov_b32_e32 v126, v122
	v_mov_b32_e32 v127, v122
	v_mov_b32_e32 v128, v122
	v_mov_b32_e32 v129, v122
	v_mov_b32_e32 v130, v122
	v_mov_b32_e32 v131, v122
	v_mov_b32_e32 v132, v122
	v_mov_b32_e32 v133, v122
	v_mov_b32_e32 v134, v122
	v_mov_b32_e32 v135, v122
	v_mov_b32_e32 v136, v122
	v_mov_b32_e32 v137, v122
.Lmla_nr_t0:
	ds_read_b128 v[138:141], v220 offset:26624
	ds_read_b128 v[142:145], v220 offset:33280
	ds_read_b128 v[146:149], v220 offset:26656
	ds_read_b128 v[150:153], v220 offset:33312
	ds_read_b128 v[154:157], v220 offset:26688
	ds_read_b128 v[158:161], v220 offset:33344
	s_waitcnt lgkmcnt(6)
	s_barrier
	v_exp_f32_e32 v66, v66
	v_exp_f32_e32 v67, v67
	v_exp_f32_e32 v68, v68
	v_exp_f32_e32 v69, v69
	s_waitcnt lgkmcnt(5)
	v_mfma_f32_32x32x16_bf16 v[34:49], v[138:141], v[98:101], v[122:137]
	ds_read_b128 v[138:141], v220 offset:26720
	v_add_f32_e32 v231, v231, v66
	v_add_f32_e32 v232, v232, v67
	v_exp_f32_e32 v70, v70
	v_exp_f32_e32 v71, v71
	s_waitcnt lgkmcnt(5)
	v_mfma_f32_32x32x16_bf16 v[50:65], v[142:145], v[98:101], v[122:137]
	ds_read_b128 v[142:145], v220 offset:33376
	v_add_f32_e32 v231, v231, v68
	v_add_f32_e32 v232, v232, v69
	v_exp_f32_e32 v72, v72
	v_exp_f32_e32 v73, v73
	s_waitcnt lgkmcnt(5)
	v_mfma_f32_32x32x16_bf16 v[34:49], v[146:149], v[102:105], v[34:49]
	ds_read_b128 v[146:149], v220 offset:26752
	v_add_f32_e32 v231, v231, v70
	v_add_f32_e32 v232, v232, v71
	v_add_f32_e32 v231, v231, v72
	v_add_f32_e32 v232, v232, v73
	v_cvt_pk_bf16_f32 v66, v66, v67
	v_cvt_pk_bf16_f32 v67, v68, v69
	s_waitcnt lgkmcnt(5)
	v_mfma_f32_32x32x16_bf16 v[50:65], v[150:153], v[102:105], v[50:65]
	ds_read_b128 v[150:153], v220 offset:33408
	v_cvt_pk_bf16_f32 v68, v70, v71
	v_cvt_pk_bf16_f32 v69, v72, v73
	v_exp_f32_e32 v74, v74
	v_exp_f32_e32 v75, v75
	s_waitcnt lgkmcnt(5)
	v_mfma_f32_32x32x16_bf16 v[34:49], v[154:157], v[106:109], v[34:49]
	ds_read_b128 v[154:157], v220 offset:26784
	v_exp_f32_e32 v76, v76
	v_exp_f32_e32 v77, v77
	v_add_f32_e32 v231, v231, v74
	v_add_f32_e32 v232, v232, v75
	s_waitcnt lgkmcnt(5)
	v_mfma_f32_32x32x16_bf16 v[50:65], v[158:161], v[106:109], v[50:65]
	ds_read_b128 v[158:161], v220 offset:33440
	v_exp_f32_e32 v78, v78
	v_exp_f32_e32 v79, v79
	v_add_f32_e32 v231, v231, v76
	v_add_f32_e32 v232, v232, v77
	v_exp_f32_e32 v80, v80
	s_waitcnt lgkmcnt(5)
	v_mfma_f32_32x32x16_bf16 v[34:49], v[138:141], v[110:113], v[34:49]
	ds_read_b64 v[162:163], v221 offset:8704
	ds_read_b64 v[164:165], v221 offset:8720
	v_exp_f32_e32 v81, v81
	v_add_f32_e32 v231, v231, v78
	v_add_f32_e32 v232, v232, v79
	v_add_f32_e32 v231, v231, v80
	s_waitcnt lgkmcnt(6)
	v_mfma_f32_32x32x16_bf16 v[50:65], v[142:145], v[110:113], v[50:65]
	ds_read_b64 v[166:167], v221 offset:13056
	ds_read_b64 v[168:169], v221 offset:13072
	v_add_f32_e32 v232, v232, v81
	v_cvt_pk_bf16_f32 v74, v74, v75
	v_cvt_pk_bf16_f32 v75, v76, v77
	v_cvt_pk_bf16_f32 v76, v78, v79
	v_cvt_pk_bf16_f32 v77, v80, v81
	v_exp_f32_e32 v82, v82
	s_waitcnt lgkmcnt(7)
	v_mfma_f32_32x32x16_bf16 v[34:49], v[146:149], v[114:117], v[34:49]
	ds_read_b64 v[170:171], v221 offset:8736
	ds_read_b64 v[172:173], v221 offset:8752
	v_exp_f32_e32 v83, v83
	v_exp_f32_e32 v84, v84
	v_exp_f32_e32 v85, v85
	s_waitcnt lgkmcnt(8)
	v_mfma_f32_32x32x16_bf16 v[50:65], v[150:153], v[114:117], v[50:65]
	ds_read_b64 v[174:175], v221 offset:13088
	ds_read_b64 v[176:177], v221 offset:13104
	v_add_f32_e32 v231, v231, v82
	v_add_f32_e32 v232, v232, v83
	v_exp_f32_e32 v86, v86
	v_exp_f32_e32 v87, v87
	s_waitcnt lgkmcnt(9)
	v_mfma_f32_32x32x16_bf16 v[34:49], v[154:157], v[118:121], v[34:49]
	ds_read_b64 v[180:181], v221 offset:8768
	ds_read_b64 v[182:183], v221 offset:8784
	v_add_f32_e32 v231, v231, v84
	v_add_f32_e32 v232, v232, v85
	v_exp_f32_e32 v88, v88
	v_exp_f32_e32 v89, v89
	s_waitcnt lgkmcnt(10)
	v_mfma_f32_32x32x16_bf16 v[50:65], v[158:161], v[118:121], v[50:65]
	ds_read_b64 v[184:185], v221 offset:13120
	ds_read_b64 v[186:187], v221 offset:13136
	v_add_f32_e32 v231, v231, v86
	v_add_f32_e32 v232, v232, v87
	v_add_f32_e32 v231, v231, v88
	v_add_f32_e32 v232, v232, v89
	v_cvt_pk_bf16_f32 v82, v82, v83
	v_cvt_pk_bf16_f32 v83, v84, v85
	v_cvt_pk_bf16_f32 v84, v86, v87
	s_waitcnt lgkmcnt(10)
	v_mfma_f32_32x32x16_bf16 v[2:17], v[162:165], v[66:69], v[2:17]
	ds_read_b64 v[188:189], v221 offset:8800
	ds_read_b64 v[190:191], v221 offset:8816
	v_cvt_pk_bf16_f32 v85, v88, v89
	v_exp_f32_e32 v90, v90
	v_exp_f32_e32 v91, v91
	v_exp_f32_e32 v92, v92
	s_waitcnt lgkmcnt(10)
	v_mfma_f32_32x32x16_bf16 v[18:33], v[166:169], v[66:69], v[18:33]
	ds_read_b64 v[192:193], v221 offset:13152
	ds_read_b64 v[194:195], v221 offset:13168
	v_exp_f32_e32 v93, v93
	v_add_f32_e32 v231, v231, v90
	v_add_f32_e32 v232, v232, v91
	v_exp_f32_e32 v94, v94
	s_waitcnt lgkmcnt(10)
	v_mfma_f32_32x32x16_bf16 v[2:17], v[170:173], v[74:77], v[2:17]
	v_exp_f32_e32 v95, v95
	v_add_f32_e32 v231, v231, v92
	v_add_f32_e32 v232, v232, v93
	v_exp_f32_e32 v96, v96
	s_waitcnt lgkmcnt(8)
	v_mfma_f32_32x32x16_bf16 v[18:33], v[174:177], v[74:77], v[18:33]
	s_waitcnt vmcnt(0)
	ds_write_b64 v225, v[212:213] offset:26112
	ds_write_b64 v225, v[214:215] offset:26120
	v_exp_f32_e32 v97, v97
	v_add_f32_e32 v231, v231, v94
	v_add_f32_e32 v232, v232, v95
	v_add_f32_e32 v231, v231, v96
	v_add_f32_e32 v232, v232, v97
	s_waitcnt lgkmcnt(8)
	v_mfma_f32_32x32x16_bf16 v[2:17], v[180:183], v[82:85], v[2:17]
	v_cvt_pk_bf16_f32 v90, v90, v91
	v_cvt_pk_bf16_f32 v91, v92, v93
	v_cvt_pk_bf16_f32 v92, v94, v95
	v_cvt_pk_bf16_f32 v93, v96, v97
	v_max3_f32 v234, v34, v35, v36
	v_max3_f32 v235, v50, v51, v52
	s_waitcnt lgkmcnt(6)
	v_mfma_f32_32x32x16_bf16 v[18:33], v[184:187], v[82:85], v[18:33]
	v_max3_f32 v234, v234, v37, v38
	v_max3_f32 v235, v235, v53, v54
	v_max3_f32 v234, v234, v39, v40
	v_max3_f32 v235, v235, v55, v56
	v_max3_f32 v234, v234, v41, v42
	v_max3_f32 v235, v235, v57, v58
	v_max3_f32 v234, v234, v43, v44
	s_waitcnt lgkmcnt(4)
	v_mfma_f32_32x32x16_bf16 v[2:17], v[188:191], v[90:93], v[2:17]
	v_max3_f32 v235, v235, v59, v60
	v_max3_f32 v234, v234, v45, v46
	v_max3_f32 v235, v235, v61, v62
	v_max3_f32 v234, v234, v47, v48
	v_max3_f32 v235, v235, v63, v64
	v_max3_f32 v234, v234, v49, v65
	s_waitcnt lgkmcnt(2)
	v_mfma_f32_32x32x16_bf16 v[18:33], v[192:195], v[90:93], v[18:33]
	v_max_f32_e32 v234, v234, v235
	v_mov_b32_e32 v235, v234
	s_nop 1
	v_permlane32_swap_b32_e32 v234, v235
	v_max_f32_e32 v233, v234, v235
	v_cmp_lt_f32_e32 vcc, 4.0, v233
	s_cbranch_vccz .Lmla_nr_t1
	s_nop 15
	v_max_f32_e32 v234, 0, v233
	v_exp_f32_e64 v235, -v234
	v_add_f32_e32 v230, v230, v234
	v_sub_f32_e32 v34, v34, v234
	v_sub_f32_e32 v35, v35, v234
	v_sub_f32_e32 v36, v36, v234
	v_sub_f32_e32 v37, v37, v234
	v_sub_f32_e32 v38, v38, v234
	v_sub_f32_e32 v39, v39, v234
	v_sub_f32_e32 v40, v40, v234
	v_sub_f32_e32 v41, v41, v234
	v_sub_f32_e32 v42, v42, v234
	v_sub_f32_e32 v43, v43, v234
	v_sub_f32_e32 v44, v44, v234
	v_sub_f32_e32 v45, v45, v234
	v_sub_f32_e32 v46, v46, v234
	v_sub_f32_e32 v47, v47, v234
	v_sub_f32_e32 v48, v48, v234
	v_sub_f32_e32 v49, v49, v234
	v_sub_f32_e32 v50, v50, v234
	v_sub_f32_e32 v51, v51, v234
	v_sub_f32_e32 v52, v52, v234
	v_sub_f32_e32 v53, v53, v234
	v_sub_f32_e32 v54, v54, v234
	v_sub_f32_e32 v55, v55, v234
	v_sub_f32_e32 v56, v56, v234
	v_sub_f32_e32 v57, v57, v234
	v_sub_f32_e32 v58, v58, v234
	v_sub_f32_e32 v59, v59, v234
	v_sub_f32_e32 v60, v60, v234
	v_sub_f32_e32 v61, v61, v234
	v_sub_f32_e32 v62, v62, v234
	v_sub_f32_e32 v63, v63, v234
	v_sub_f32_e32 v64, v64, v234
	v_sub_f32_e32 v65, v65, v234
	v_mul_f32_e32 v231, v231, v235
	v_mul_f32_e32 v232, v232, v235
	v_mul_f32_e32 v2, v2, v235
	v_mul_f32_e32 v3, v3, v235
	v_mul_f32_e32 v4, v4, v235
	v_mul_f32_e32 v5, v5, v235
	v_mul_f32_e32 v6, v6, v235
	v_mul_f32_e32 v7, v7, v235
	v_mul_f32_e32 v8, v8, v235
	v_mul_f32_e32 v9, v9, v235
	v_mul_f32_e32 v10, v10, v235
	v_mul_f32_e32 v11, v11, v235
	v_mul_f32_e32 v12, v12, v235
	v_mul_f32_e32 v13, v13, v235
	v_mul_f32_e32 v14, v14, v235
	v_mul_f32_e32 v15, v15, v235
	v_mul_f32_e32 v16, v16, v235
	v_mul_f32_e32 v17, v17, v235
	v_mul_f32_e32 v18, v18, v235
	v_mul_f32_e32 v19, v19, v235
	v_mul_f32_e32 v20, v20, v235
	v_mul_f32_e32 v21, v21, v235
	v_mul_f32_e32 v22, v22, v235
	v_mul_f32_e32 v23, v23, v235
	v_mul_f32_e32 v24, v24, v235
	v_mul_f32_e32 v25, v25, v235
	v_mul_f32_e32 v26, v26, v235
	v_mul_f32_e32 v27, v27, v235
	v_mul_f32_e32 v28, v28, v235
	v_mul_f32_e32 v29, v29, v235
	v_mul_f32_e32 v30, v30, v235
	v_mul_f32_e32 v31, v31, v235
	v_mul_f32_e32 v32, v32, v235
	v_mul_f32_e32 v33, v33, v235
	v_sub_f32_e32 v122, 0, v230
	v_mov_b32_e32 v123, v122
	v_mov_b32_e32 v124, v122
	v_mov_b32_e32 v125, v122
	v_mov_b32_e32 v126, v122
	v_mov_b32_e32 v127, v122
	v_mov_b32_e32 v128, v122
	v_mov_b32_e32 v129, v122
	v_mov_b32_e32 v130, v122
	v_mov_b32_e32 v131, v122
	v_mov_b32_e32 v132, v122
	v_mov_b32_e32 v133, v122
	v_mov_b32_e32 v134, v122
	v_mov_b32_e32 v135, v122
	v_mov_b32_e32 v136, v122
	v_mov_b32_e32 v137, v122
.Lmla_nr_t1:
	ds_read_b128 v[138:141], v220 offset:39936
	ds_read_b128 v[142:145], v220 offset:46592
	ds_read_b128 v[146:149], v220 offset:39968
	ds_read_b128 v[150:153], v220 offset:46624
	ds_read_b128 v[154:157], v220 offset:40000
	ds_read_b128 v[158:161], v220 offset:46656
	s_waitcnt lgkmcnt(6)
	s_barrier
	global_load_dwordx2 v[200:201], v236, s[14:15] offset:0
	global_load_dwordx2 v[202:203], v236, s[14:15] offset:16
	global_load_dwordx2 v[204:205], v236, s[14:15] offset:32
	global_load_dwordx2 v[206:207], v236, s[14:15] offset:48
	global_load_dwordx2 v[208:209], v236, s[14:15] offset:64
	global_load_dwordx2 v[210:211], v236, s[14:15] offset:80
	global_load_dwordx2 v[212:213], v236, s[14:15] offset:96
	global_load_dwordx2 v[214:215], v236, s[14:15] offset:112
	v_exp_f32_e32 v34, v34
	v_exp_f32_e32 v35, v35
	v_exp_f32_e32 v36, v36
	v_exp_f32_e32 v37, v37
	s_waitcnt lgkmcnt(5)
	v_mfma_f32_32x32x16_bf16 v[66:81], v[138:141], v[98:101], v[122:137]
	ds_read_b128 v[138:141], v220 offset:40032
	v_add_f32_e32 v231, v231, v34
	v_add_f32_e32 v232, v232, v35
	v_exp_f32_e32 v38, v38
	v_exp_f32_e32 v39, v39
	s_waitcnt lgkmcnt(5)
	v_mfma_f32_32x32x16_bf16 v[82:97], v[142:145], v[98:101], v[122:137]
	ds_read_b128 v[142:145], v220 offset:46688
	v_add_f32_e32 v231, v231, v36
	v_add_f32_e32 v232, v232, v37
	v_exp_f32_e32 v40, v40
	v_exp_f32_e32 v41, v41
	s_waitcnt lgkmcnt(5)
	v_mfma_f32_32x32x16_bf16 v[66:81], v[146:149], v[102:105], v[66:81]
	ds_read_b128 v[146:149], v220 offset:40064
	v_add_f32_e32 v231, v231, v38
	v_add_f32_e32 v232, v232, v39
	v_add_f32_e32 v231, v231, v40
	v_add_f32_e32 v232, v232, v41
	v_cvt_pk_bf16_f32 v34, v34, v35
	v_cvt_pk_bf16_f32 v35, v36, v37
	s_waitcnt lgkmcnt(5)
	v_mfma_f32_32x32x16_bf16 v[82:97], v[150:153], v[102:105], v[82:97]
	ds_read_b128 v[150:153], v220 offset:46720
	v_cvt_pk_bf16_f32 v36, v38, v39
	v_cvt_pk_bf16_f32 v37, v40, v41
	v_exp_f32_e32 v42, v42
	v_exp_f32_e32 v43, v43
	s_waitcnt lgkmcnt(5)
	v_mfma_f32_32x32x16_bf16 v[66:81], v[154:157], v[106:109], v[66:81]
	ds_read_b128 v[154:157], v220 offset:40096
	v_exp_f32_e32 v44, v44
	v_exp_f32_e32 v45, v45
	v_add_f32_e32 v231, v231, v42
	v_add_f32_e32 v232, v232, v43
	s_waitcnt lgkmcnt(5)
	v_mfma_f32_32x32x16_bf16 v[82:97], v[158:161], v[106:109], v[82:97]
	ds_read_b128 v[158:161], v220 offset:46752
	v_exp_f32_e32 v46, v46
	v_exp_f32_e32 v47, v47
	v_add_f32_e32 v231, v231, v44
	v_add_f32_e32 v232, v232, v45
	v_exp_f32_e32 v48, v48
	s_waitcnt lgkmcnt(5)
	v_mfma_f32_32x32x16_bf16 v[66:81], v[138:141], v[110:113], v[66:81]
	ds_read_b64 v[162:163], v221 offset:17408
	ds_read_b64 v[164:165], v221 offset:17424
	v_exp_f32_e32 v49, v49
	v_add_f32_e32 v231, v231, v46
	v_add_f32_e32 v232, v232, v47
	v_add_f32_e32 v231, v231, v48
	s_waitcnt lgkmcnt(6)
	v_mfma_f32_32x32x16_bf16 v[82:97], v[142:145], v[110:113], v[82:97]
	ds_read_b64 v[166:167], v221 offset:21760
	ds_read_b64 v[168:169], v221 offset:21776
	v_add_f32_e32 v232, v232, v49
	v_cvt_pk_bf16_f32 v42, v42, v43
	v_cvt_pk_bf16_f32 v43, v44, v45
	v_cvt_pk_bf16_f32 v44, v46, v47
	v_cvt_pk_bf16_f32 v45, v48, v49
	v_exp_f32_e32 v50, v50
	s_waitcnt lgkmcnt(7)
	v_mfma_f32_32x32x16_bf16 v[66:81], v[146:149], v[114:117], v[66:81]
	ds_read_b64 v[170:171], v221 offset:17440
	ds_read_b64 v[172:173], v221 offset:17456
	v_exp_f32_e32 v51, v51
	v_exp_f32_e32 v52, v52
	v_exp_f32_e32 v53, v53
	s_waitcnt lgkmcnt(8)
	v_mfma_f32_32x32x16_bf16 v[82:97], v[150:153], v[114:117], v[82:97]
	ds_read_b64 v[174:175], v221 offset:21792
	ds_read_b64 v[176:177], v221 offset:21808
	v_add_f32_e32 v231, v231, v50
	v_add_f32_e32 v232, v232, v51
	v_exp_f32_e32 v54, v54
	v_exp_f32_e32 v55, v55
	s_waitcnt lgkmcnt(9)
	v_mfma_f32_32x32x16_bf16 v[66:81], v[154:157], v[118:121], v[66:81]
	ds_read_b64 v[180:181], v221 offset:17472
	ds_read_b64 v[182:183], v221 offset:17488
	v_add_f32_e32 v231, v231, v52
	v_add_f32_e32 v232, v232, v53
	v_exp_f32_e32 v56, v56
	v_exp_f32_e32 v57, v57
	s_waitcnt lgkmcnt(10)
	v_mfma_f32_32x32x16_bf16 v[82:97], v[158:161], v[118:121], v[82:97]
	ds_read_b64 v[184:185], v221 offset:21824
	ds_read_b64 v[186:187], v221 offset:21840
	v_add_f32_e32 v231, v231, v54
	v_add_f32_e32 v232, v232, v55
	v_add_f32_e32 v231, v231, v56
	v_add_f32_e32 v232, v232, v57
	v_cvt_pk_bf16_f32 v50, v50, v51
	v_cvt_pk_bf16_f32 v51, v52, v53
	v_cvt_pk_bf16_f32 v52, v54, v55
	s_waitcnt lgkmcnt(10)
	v_mfma_f32_32x32x16_bf16 v[2:17], v[162:165], v[34:37], v[2:17]
	ds_read_b64 v[188:189], v221 offset:17504
	ds_read_b64 v[190:191], v221 offset:17520
	v_cvt_pk_bf16_f32 v53, v56, v57
	v_exp_f32_e32 v58, v58
	v_exp_f32_e32 v59, v59
	v_exp_f32_e32 v60, v60
	s_waitcnt lgkmcnt(10)
	v_mfma_f32_32x32x16_bf16 v[18:33], v[166:169], v[34:37], v[18:33]
	ds_read_b64 v[192:193], v221 offset:21856
	ds_read_b64 v[194:195], v221 offset:21872
	v_exp_f32_e32 v61, v61
	v_add_f32_e32 v231, v231, v58
	v_add_f32_e32 v232, v232, v59
	v_exp_f32_e32 v62, v62
	s_waitcnt lgkmcnt(10)
	v_mfma_f32_32x32x16_bf16 v[2:17], v[170:173], v[42:45], v[2:17]
	v_exp_f32_e32 v63, v63
	v_add_f32_e32 v231, v231, v60
	v_add_f32_e32 v232, v232, v61
	v_exp_f32_e32 v64, v64
	s_waitcnt lgkmcnt(8)
	v_mfma_f32_32x32x16_bf16 v[18:33], v[174:177], v[42:45], v[18:33]
	v_exp_f32_e32 v65, v65
	v_add_f32_e32 v231, v231, v62
	v_add_f32_e32 v232, v232, v63
	v_add_f32_e32 v231, v231, v64
	v_add_f32_e32 v232, v232, v65
	s_waitcnt lgkmcnt(6)
	v_mfma_f32_32x32x16_bf16 v[2:17], v[180:183], v[50:53], v[2:17]
	v_cvt_pk_bf16_f32 v58, v58, v59
	v_cvt_pk_bf16_f32 v59, v60, v61
	v_cvt_pk_bf16_f32 v60, v62, v63
	v_cvt_pk_bf16_f32 v61, v64, v65
	v_max3_f32 v234, v66, v67, v68
	v_max3_f32 v235, v82, v83, v84
	s_waitcnt lgkmcnt(4)
	v_mfma_f32_32x32x16_bf16 v[18:33], v[184:187], v[50:53], v[18:33]
	v_max3_f32 v234, v234, v69, v70
	v_max3_f32 v235, v235, v85, v86
	v_max3_f32 v234, v234, v71, v72
	v_max3_f32 v235, v235, v87, v88
	v_max3_f32 v234, v234, v73, v74
	v_max3_f32 v235, v235, v89, v90
	v_max3_f32 v234, v234, v75, v76
	s_waitcnt lgkmcnt(2)
	v_mfma_f32_32x32x16_bf16 v[2:17], v[188:191], v[58:61], v[2:17]
	v_max3_f32 v235, v235, v91, v92
	v_max3_f32 v234, v234, v77, v78
	v_max3_f32 v235, v235, v93, v94
	v_max3_f32 v234, v234, v79, v80
	v_max3_f32 v235, v235, v95, v96
	v_max3_f32 v234, v234, v81, v97
	s_waitcnt lgkmcnt(0)
	v_mfma_f32_32x32x16_bf16 v[18:33], v[192:195], v[58:61], v[18:33]
	v_max_f32_e32 v234, v234, v235
	v_mov_b32_e32 v235, v234
	s_nop 1
	v_permlane32_swap_b32_e32 v234, v235
	v_max_f32_e32 v233, v234, v235
	v_cmp_lt_f32_e32 vcc, 4.0, v233
	s_cbranch_vccz .Lmla_nr_t2
	s_nop 15
	v_max_f32_e32 v234, 0, v233
	v_exp_f32_e64 v235, -v234
	v_add_f32_e32 v230, v230, v234
	v_sub_f32_e32 v66, v66, v234
	v_sub_f32_e32 v67, v67, v234
	v_sub_f32_e32 v68, v68, v234
	v_sub_f32_e32 v69, v69, v234
	v_sub_f32_e32 v70, v70, v234
	v_sub_f32_e32 v71, v71, v234
	v_sub_f32_e32 v72, v72, v234
	v_sub_f32_e32 v73, v73, v234
	v_sub_f32_e32 v74, v74, v234
	v_sub_f32_e32 v75, v75, v234
	v_sub_f32_e32 v76, v76, v234
	v_sub_f32_e32 v77, v77, v234
	v_sub_f32_e32 v78, v78, v234
	v_sub_f32_e32 v79, v79, v234
	v_sub_f32_e32 v80, v80, v234
	v_sub_f32_e32 v81, v81, v234
	v_sub_f32_e32 v82, v82, v234
	v_sub_f32_e32 v83, v83, v234
	v_sub_f32_e32 v84, v84, v234
	v_sub_f32_e32 v85, v85, v234
	v_sub_f32_e32 v86, v86, v234
	v_sub_f32_e32 v87, v87, v234
	v_sub_f32_e32 v88, v88, v234
	v_sub_f32_e32 v89, v89, v234
	v_sub_f32_e32 v90, v90, v234
	v_sub_f32_e32 v91, v91, v234
	v_sub_f32_e32 v92, v92, v234
	v_sub_f32_e32 v93, v93, v234
	v_sub_f32_e32 v94, v94, v234
	v_sub_f32_e32 v95, v95, v234
	v_sub_f32_e32 v96, v96, v234
	v_sub_f32_e32 v97, v97, v234
	v_mul_f32_e32 v231, v231, v235
	v_mul_f32_e32 v232, v232, v235
	v_mul_f32_e32 v2, v2, v235
	v_mul_f32_e32 v3, v3, v235
	v_mul_f32_e32 v4, v4, v235
	v_mul_f32_e32 v5, v5, v235
	v_mul_f32_e32 v6, v6, v235
	v_mul_f32_e32 v7, v7, v235
	v_mul_f32_e32 v8, v8, v235
	v_mul_f32_e32 v9, v9, v235
	v_mul_f32_e32 v10, v10, v235
	v_mul_f32_e32 v11, v11, v235
	v_mul_f32_e32 v12, v12, v235
	v_mul_f32_e32 v13, v13, v235
	v_mul_f32_e32 v14, v14, v235
	v_mul_f32_e32 v15, v15, v235
	v_mul_f32_e32 v16, v16, v235
	v_mul_f32_e32 v17, v17, v235
	v_mul_f32_e32 v18, v18, v235
	v_mul_f32_e32 v19, v19, v235
	v_mul_f32_e32 v20, v20, v235
	v_mul_f32_e32 v21, v21, v235
	v_mul_f32_e32 v22, v22, v235
	v_mul_f32_e32 v23, v23, v235
	v_mul_f32_e32 v24, v24, v235
	v_mul_f32_e32 v25, v25, v235
	v_mul_f32_e32 v26, v26, v235
	v_mul_f32_e32 v27, v27, v235
	v_mul_f32_e32 v28, v28, v235
	v_mul_f32_e32 v29, v29, v235
	v_mul_f32_e32 v30, v30, v235
	v_mul_f32_e32 v31, v31, v235
	v_mul_f32_e32 v32, v32, v235
	v_mul_f32_e32 v33, v33, v235
	v_sub_f32_e32 v122, 0, v230
	v_mov_b32_e32 v123, v122
	v_mov_b32_e32 v124, v122
	v_mov_b32_e32 v125, v122
	v_mov_b32_e32 v126, v122
	v_mov_b32_e32 v127, v122
	v_mov_b32_e32 v128, v122
	v_mov_b32_e32 v129, v122
	v_mov_b32_e32 v130, v122
	v_mov_b32_e32 v131, v122
	v_mov_b32_e32 v132, v122
	v_mov_b32_e32 v133, v122
	v_mov_b32_e32 v134, v122
	v_mov_b32_e32 v135, v122
	v_mov_b32_e32 v136, v122
	v_mov_b32_e32 v137, v122
.Lmla_nr_t2:
	s_waitcnt lgkmcnt(0)
	s_barrier
	ds_read_b64 v[162:163], v221 offset:26112
	ds_read_b64 v[164:165], v221 offset:26128
	ds_read_b64 v[166:167], v221 offset:30464
	ds_read_b64 v[168:169], v221 offset:30480
	ds_read_b64 v[170:171], v221 offset:26144
	ds_read_b64 v[172:173], v221 offset:26160
	v_exp_f32_e32 v66, v66
	v_exp_f32_e32 v67, v67
	v_exp_f32_e32 v68, v68
	v_exp_f32_e32 v69, v69
	v_add_f32_e32 v231, v231, v66
	v_add_f32_e32 v232, v232, v67
	v_exp_f32_e32 v70, v70
	v_exp_f32_e32 v71, v71
	v_add_f32_e32 v231, v231, v68
	v_add_f32_e32 v232, v232, v69
	v_exp_f32_e32 v72, v72
	v_exp_f32_e32 v73, v73
	v_add_f32_e32 v231, v231, v70
	v_add_f32_e32 v232, v232, v71
	v_add_f32_e32 v231, v231, v72
	v_add_f32_e32 v232, v232, v73
	v_cvt_pk_bf16_f32 v66, v66, v67
	v_cvt_pk_bf16_f32 v67, v68, v69
	v_cvt_pk_bf16_f32 v68, v70, v71
	v_cvt_pk_bf16_f32 v69, v72, v73
	s_waitcnt lgkmcnt(4)
	s_nop 0
	v_mfma_f32_32x32x16_bf16 v[2:17], v[162:165], v[66:69], v[2:17]
	ds_read_b64 v[174:175], v221 offset:30496
	ds_read_b64 v[176:177], v221 offset:30512
	s_waitcnt lgkmcnt(4)
	v_mfma_f32_32x32x16_bf16 v[18:33], v[166:169], v[66:69], v[18:33]
	ds_read_b64 v[180:181], v221 offset:26176
	ds_read_b64 v[182:183], v221 offset:26192
	v_exp_f32_e32 v74, v74
	v_exp_f32_e32 v75, v75
	v_exp_f32_e32 v76, v76
	v_exp_f32_e32 v77, v77
	v_add_f32_e32 v231, v231, v74
	v_add_f32_e32 v232, v232, v75
	v_exp_f32_e32 v78, v78
	v_exp_f32_e32 v79, v79
	v_add_f32_e32 v231, v231, v76
	v_add_f32_e32 v232, v232, v77
	v_exp_f32_e32 v80, v80
	v_exp_f32_e32 v81, v81
	v_add_f32_e32 v231, v231, v78
	v_add_f32_e32 v232, v232, v79
	v_add_f32_e32 v231, v231, v80
	v_add_f32_e32 v232, v232, v81
	v_cvt_pk_bf16_f32 v74, v74, v75
	v_cvt_pk_bf16_f32 v75, v76, v77
	v_cvt_pk_bf16_f32 v76, v78, v79
	v_cvt_pk_bf16_f32 v77, v80, v81
	s_waitcnt lgkmcnt(4)
	s_nop 0
	v_mfma_f32_32x32x16_bf16 v[2:17], v[170:173], v[74:77], v[2:17]
	ds_read_b64 v[184:185], v221 offset:30528
	ds_read_b64 v[186:187], v221 offset:30544
	s_waitcnt lgkmcnt(4)
	v_mfma_f32_32x32x16_bf16 v[18:33], v[174:177], v[74:77], v[18:33]
	ds_read_b64 v[188:189], v221 offset:26208
	ds_read_b64 v[190:191], v221 offset:26224
	v_exp_f32_e32 v82, v82
	v_exp_f32_e32 v83, v83
	v_exp_f32_e32 v84, v84
	v_exp_f32_e32 v85, v85
	v_add_f32_e32 v231, v231, v82
	v_add_f32_e32 v232, v232, v83
	v_exp_f32_e32 v86, v86
	v_exp_f32_e32 v87, v87
	v_add_f32_e32 v231, v231, v84
	v_add_f32_e32 v232, v232, v85
	v_exp_f32_e32 v88, v88
	v_exp_f32_e32 v89, v89
	v_add_f32_e32 v231, v231, v86
	v_add_f32_e32 v232, v232, v87
	v_add_f32_e32 v231, v231, v88
	v_add_f32_e32 v232, v232, v89
	v_cvt_pk_bf16_f32 v82, v82, v83
	v_cvt_pk_bf16_f32 v83, v84, v85
	v_cvt_pk_bf16_f32 v84, v86, v87
	v_cvt_pk_bf16_f32 v85, v88, v89
	s_waitcnt lgkmcnt(4)
	s_nop 0
	v_mfma_f32_32x32x16_bf16 v[2:17], v[180:183], v[82:85], v[2:17]
	ds_read_b64 v[192:193], v221 offset:30560
	ds_read_b64 v[194:195], v221 offset:30576
	s_waitcnt lgkmcnt(4)
	v_mfma_f32_32x32x16_bf16 v[18:33], v[184:187], v[82:85], v[18:33]
	v_exp_f32_e32 v90, v90
	v_exp_f32_e32 v91, v91
	v_exp_f32_e32 v92, v92
	v_exp_f32_e32 v93, v93
	v_add_f32_e32 v231, v231, v90
	v_add_f32_e32 v232, v232, v91
	v_exp_f32_e32 v94, v94
	v_exp_f32_e32 v95, v95
	v_add_f32_e32 v231, v231, v92
	v_add_f32_e32 v232, v232, v93
	v_exp_f32_e32 v96, v96
	v_exp_f32_e32 v97, v97
	v_add_f32_e32 v231, v231, v94
	v_add_f32_e32 v232, v232, v95
	v_add_f32_e32 v231, v231, v96
	v_add_f32_e32 v232, v232, v97
	v_cvt_pk_bf16_f32 v90, v90, v91
	v_cvt_pk_bf16_f32 v91, v92, v93
	v_cvt_pk_bf16_f32 v92, v94, v95
	v_cvt_pk_bf16_f32 v93, v96, v97
	s_waitcnt lgkmcnt(2)
	s_nop 0
	v_mfma_f32_32x32x16_bf16 v[2:17], v[188:191], v[90:93], v[2:17]
	s_waitcnt lgkmcnt(0)
	v_mfma_f32_32x32x16_bf16 v[18:33], v[192:195], v[90:93], v[18:33]
	s_waitcnt lgkmcnt(0)
	s_barrier
	v_add_f32_e32 v231, v231, v232
	v_mov_b32_e32 v235, v231
	s_nop 1
	v_permlane32_swap_b32_e32 v231, v235
	v_add_f32_e32 v234, v231, v235
	v_div_scale_f32 v235, s[22:23], v234, v234, 1.0
	v_rcp_f32_e32 v179, v235
	v_div_scale_f32 v196, vcc, 1.0, v234, 1.0
	v_fma_f32 v197, -v235, v179, 1.0
	v_fmac_f32_e32 v179, v197, v179
	v_mul_f32_e32 v197, v196, v179
	v_fma_f32 v199, -v235, v197, v196
	v_fmac_f32_e32 v197, v199, v179
	v_fma_f32 v235, -v235, v197, v196
	v_div_fmas_f32 v235, v235, v179, v197
	v_div_fixup_f32 v234, v235, v234, 1.0
	s_nop 15
	v_mul_f32_e32 v2, v2, v234
	v_mul_f32_e32 v3, v3, v234
	v_mul_f32_e32 v4, v4, v234
	v_mul_f32_e32 v5, v5, v234
	v_mul_f32_e32 v6, v6, v234
	v_mul_f32_e32 v7, v7, v234
	v_mul_f32_e32 v8, v8, v234
	v_mul_f32_e32 v9, v9, v234
	v_mul_f32_e32 v10, v10, v234
	v_mul_f32_e32 v11, v11, v234
	v_mul_f32_e32 v12, v12, v234
	v_mul_f32_e32 v13, v13, v234
	v_mul_f32_e32 v14, v14, v234
	v_mul_f32_e32 v15, v15, v234
	v_mul_f32_e32 v16, v16, v234
	v_mul_f32_e32 v17, v17, v234
	v_mul_f32_e32 v18, v18, v234
	v_mul_f32_e32 v19, v19, v234
	v_mul_f32_e32 v20, v20, v234
	v_mul_f32_e32 v21, v21, v234
	v_mul_f32_e32 v22, v22, v234
	v_mul_f32_e32 v23, v23, v234
	v_mul_f32_e32 v24, v24, v234
	v_mul_f32_e32 v25, v25, v234
	v_mul_f32_e32 v26, v26, v234
	v_mul_f32_e32 v27, v27, v234
	v_mul_f32_e32 v28, v28, v234
	v_mul_f32_e32 v29, v29, v234
	v_mul_f32_e32 v30, v30, v234
	v_mul_f32_e32 v31, v31, v234
	v_mul_f32_e32 v32, v32, v234
	v_mul_f32_e32 v33, v33, v234
	s_waitcnt vmcnt(0)
	v_lshlrev_b32_e32 v179, 16, v200
	v_and_b32_e32 v196, 0xffff0000, v200
	v_lshlrev_b32_e32 v197, 16, v201
	v_and_b32_e32 v199, 0xffff0000, v201
	v_mul_f32_e32 v2, v2, v179
	v_mul_f32_e32 v3, v3, v196
	v_mul_f32_e32 v4, v4, v197
	v_mul_f32_e32 v5, v5, v199
	v_cvt_pk_bf16_f32 v200, v2, v3
	v_cvt_pk_bf16_f32 v201, v4, v5
	global_store_dwordx2 v236, v[200:201], s[14:15] offset:0
	v_lshlrev_b32_e32 v179, 16, v202
	v_and_b32_e32 v196, 0xffff0000, v202
	v_lshlrev_b32_e32 v197, 16, v203
	v_and_b32_e32 v199, 0xffff0000, v203
	v_mul_f32_e32 v6, v6, v179
	v_mul_f32_e32 v7, v7, v196
	v_mul_f32_e32 v8, v8, v197
	v_mul_f32_e32 v9, v9, v199
	v_cvt_pk_bf16_f32 v202, v6, v7
	v_cvt_pk_bf16_f32 v203, v8, v9
	global_store_dwordx2 v236, v[202:203], s[14:15] offset:16
	v_lshlrev_b32_e32 v179, 16, v204
	v_and_b32_e32 v196, 0xffff0000, v204
	v_lshlrev_b32_e32 v197, 16, v205
	v_and_b32_e32 v199, 0xffff0000, v205
	v_mul_f32_e32 v10, v10, v179
	v_mul_f32_e32 v11, v11, v196
	v_mul_f32_e32 v12, v12, v197
	v_mul_f32_e32 v13, v13, v199
	v_cvt_pk_bf16_f32 v204, v10, v11
	v_cvt_pk_bf16_f32 v205, v12, v13
	global_store_dwordx2 v236, v[204:205], s[14:15] offset:32
	v_lshlrev_b32_e32 v179, 16, v206
	v_and_b32_e32 v196, 0xffff0000, v206
	v_lshlrev_b32_e32 v197, 16, v207
	v_and_b32_e32 v199, 0xffff0000, v207
	v_mul_f32_e32 v14, v14, v179
	v_mul_f32_e32 v15, v15, v196
	v_mul_f32_e32 v16, v16, v197
	v_mul_f32_e32 v17, v17, v199
	v_cvt_pk_bf16_f32 v206, v14, v15
	v_cvt_pk_bf16_f32 v207, v16, v17
	global_store_dwordx2 v236, v[206:207], s[14:15] offset:48
	v_lshlrev_b32_e32 v179, 16, v208
	v_and_b32_e32 v196, 0xffff0000, v208
	v_lshlrev_b32_e32 v197, 16, v209
	v_and_b32_e32 v199, 0xffff0000, v209
	v_mul_f32_e32 v18, v18, v179
	v_mul_f32_e32 v19, v19, v196
	v_mul_f32_e32 v20, v20, v197
	v_mul_f32_e32 v21, v21, v199
	v_cvt_pk_bf16_f32 v208, v18, v19
	v_cvt_pk_bf16_f32 v209, v20, v21
	global_store_dwordx2 v236, v[208:209], s[14:15] offset:64
	v_lshlrev_b32_e32 v179, 16, v210
	v_and_b32_e32 v196, 0xffff0000, v210
	v_lshlrev_b32_e32 v197, 16, v211
	v_and_b32_e32 v199, 0xffff0000, v211
	v_mul_f32_e32 v22, v22, v179
	v_mul_f32_e32 v23, v23, v196
	v_mul_f32_e32 v24, v24, v197
	v_mul_f32_e32 v25, v25, v199
	v_cvt_pk_bf16_f32 v210, v22, v23
	v_cvt_pk_bf16_f32 v211, v24, v25
	global_store_dwordx2 v236, v[210:211], s[14:15] offset:80
	v_lshlrev_b32_e32 v179, 16, v212
	v_and_b32_e32 v196, 0xffff0000, v212
	v_lshlrev_b32_e32 v197, 16, v213
	v_and_b32_e32 v199, 0xffff0000, v213
	v_mul_f32_e32 v26, v26, v179
	v_mul_f32_e32 v27, v27, v196
	v_mul_f32_e32 v28, v28, v197
	v_mul_f32_e32 v29, v29, v199
	v_cvt_pk_bf16_f32 v212, v26, v27
	v_cvt_pk_bf16_f32 v213, v28, v29
	global_store_dwordx2 v236, v[212:213], s[14:15] offset:96
	v_lshlrev_b32_e32 v179, 16, v214
	v_and_b32_e32 v196, 0xffff0000, v214
	v_lshlrev_b32_e32 v197, 16, v215
	v_and_b32_e32 v199, 0xffff0000, v215
	v_mul_f32_e32 v30, v30, v179
	v_mul_f32_e32 v31, v31, v196
	v_mul_f32_e32 v32, v32, v197
	v_mul_f32_e32 v33, v33, v199
	v_cvt_pk_bf16_f32 v214, v30, v31
	v_cvt_pk_bf16_f32 v215, v32, v33
	global_store_dwordx2 v236, v[214:215], s[14:15] offset:112
	s_add_i32 s2, s2, s88
	s_cmpk_lt_i32 s2, 0x200
	s_cbranch_scc1 .Lmla_unit
